# k27 + the other five GEMM K loops treated the same way: per-segment s_setprio flips deleted, one static raise for waves 4-7 per loop
# speedup vs baseline: 1.0144x; 1.0043x over previous
; #define PG8_BAR __builtin_amdgcn_s_barrier()
; template <class Epi>
; __device__ __forceinline__ void gemm_phase(PG8_LAS unsigned char* lds, const Gemm g, const StaticOrder& S, const Epi& E, const int wave_s) {
;     ...
;         const bool has_next = S.next(ui + 1, nxt);
;         const char* nA = has_next ? (const char*)g.A + (size_t)nxt.pm * tstepA : cA; const char* nB = has_next ? (const char*)g.Bt + (size_t)nxt.pn * tstepB : cB;
;         float pre[8]; E.prefetch(cur, wr, fr, pre);
;         for (int t = 0; t < nt; t += 2) {
;             const bool last = (t == nt - 2);
;             const char* a1 = cA + (size_t)(t + 1) * kstep;
;             const char* a2 = last ? nA : cA + (size_t)(t + 2) * kstep; const char* b2 = last ? nB : cB + (size_t)(t + 2) * kstep;
;             const char* a3 = a2 + kstep; const char* b3 = b2 + kstep;
;             PG8_LDB(B0, 0, 0); PG8_LDB(B1, 0, 1); PG8_SCHED; PG8_LDA(At, 0, 0); PG8_STAGE(PG8_SA(1, 1), a1 + hstepA, voffA);
;             PG8_WAIT_V(8); PG8_WAIT_L(0); PG8_BAR; PG8_MMA(0, 0, At, B0); PG8_MMA(0, 1, At, B1); PG8_BAR; PG8_SCHED;
;             PG8_LDA(At, 0, 1); PG8_STAGE(PG8_SB(0, 0), b2, voffB); PG8_STAGE(PG8_SB(0, 1), b2 + hstepB, voffB); PG8_STAGE(PG8_SA(0, 0), a2, voffA);
;             PG8_WAIT_V(8); PG8_WAIT_L(0); PG8_BAR; PG8_MMA(1, 0, At, B0); PG8_MMA(1, 1, At, B1); PG8_BAR; PG8_SCHED;
;             PG8_LDB(B0, 1, 0); PG8_LDB(B1, 1, 1); PG8_SCHED; PG8_LDA(At, 1, 0); PG8_STAGE(PG8_SA(0, 1), a2 + hstepA, voffA);
;             PG8_WAIT_V(8); PG8_WAIT_L(0); PG8_BAR; PG8_MMA(0, 0, At, B0); PG8_MMA(0, 1, At, B1); PG8_BAR; PG8_SCHED;
;             PG8_LDA(At, 1, 1); PG8_STAGE(PG8_SB(1, 0), b3, voffB); PG8_STAGE(PG8_SB(1, 1), b3 + hstepB, voffB); PG8_STAGE(PG8_SA(1, 0), a3, voffA);
;             PG8_WAIT_V(8); PG8_WAIT_L(0); PG8_BAR; PG8_MMA(1, 0, At, B0); PG8_MMA(1, 1, At, B1); PG8_BAR; PG8_SCHED;
;         }
;         if (wr == 0) PG8_BAR;
;         { const int tl = fresh_tid(wave_s); const int w2 = wave_s, l2 = tl & 63;
;           E(acc, cur, w2 >> 2, w2 & 3, l2 & 15, l2 >> 4, pre); }
;         if (!has_next) break;
; #pragma unroll
;         for (int a = 0; a < 2; ++a)
; #pragma unroll
;             for (int b = 0; b < 2; ++b)
; #pragma unroll
;                 for (int m = 0; m < 4; ++m)
; #pragma unroll
;                     for (int n = 0; n < 2; ++n) acc[a][b][m][n] = (f32x4){0.f, 0.f, 0.f, 0.f};
.LBB0_129:
	s_waitcnt vmcnt(0)
	v_mov_b32_e32 v129, 0
	s_andn2_b64 vcc, exec, s[66:67]
	v_mov_b32_e32 v128, v129
	v_mov_b32_e32 v127, v129
	v_mov_b32_e32 v126, v129
	v_mov_b32_e32 v125, v129
	v_mov_b32_e32 v124, v129
	v_mov_b32_e32 v123, v129
	v_mov_b32_e32 v122, v129
	v_mov_b32_e32 v113, v129
	v_mov_b32_e32 v112, v129
	v_mov_b32_e32 v111, v129
	v_mov_b32_e32 v110, v129
	v_mov_b32_e32 v109, v129
	v_mov_b32_e32 v108, v129
	v_mov_b32_e32 v107, v129
	v_mov_b32_e32 v106, v129
	v_mov_b32_e32 v95, v129
	v_mov_b32_e32 v94, v129
	v_mov_b32_e32 v93, v129
	v_mov_b32_e32 v92, v129
	v_mov_b32_e32 v91, v129
	v_mov_b32_e32 v90, v129
	v_mov_b32_e32 v89, v129
	v_mov_b32_e32 v88, v129
	v_mov_b32_e32 v79, v129
	v_mov_b32_e32 v78, v129
	v_mov_b32_e32 v77, v129
	v_mov_b32_e32 v76, v129
	v_mov_b32_e32 v75, v129
	v_mov_b32_e32 v74, v129
	v_mov_b32_e32 v73, v129
	v_mov_b32_e32 v72, v129
	v_mov_b32_e32 v121, v129
	v_mov_b32_e32 v120, v129
	v_mov_b32_e32 v119, v129
	v_mov_b32_e32 v118, v129
	v_mov_b32_e32 v117, v129
	v_mov_b32_e32 v116, v129
	v_mov_b32_e32 v115, v129
	v_mov_b32_e32 v114, v129
	v_mov_b32_e32 v105, v129
	v_mov_b32_e32 v104, v129
	v_mov_b32_e32 v103, v129
	v_mov_b32_e32 v102, v129
	v_mov_b32_e32 v101, v129
	v_mov_b32_e32 v100, v129
	v_mov_b32_e32 v99, v129
	v_mov_b32_e32 v98, v129
	v_mov_b32_e32 v87, v129
	v_mov_b32_e32 v86, v129
	v_mov_b32_e32 v85, v129
	v_mov_b32_e32 v84, v129
	v_mov_b32_e32 v83, v129
	v_mov_b32_e32 v82, v129
	v_mov_b32_e32 v81, v129
	v_mov_b32_e32 v80, v129
	v_mov_b32_e32 v71, v129
	v_mov_b32_e32 v70, v129
	v_mov_b32_e32 v69, v129
	v_mov_b32_e32 v68, v129
	v_mov_b32_e32 v67, v129
	v_mov_b32_e32 v66, v129
	v_mov_b32_e32 v65, v129
	v_mov_b32_e32 v64, v129
	v_mov_b32_e32 v63, v129
	v_mov_b32_e32 v62, v129
	v_mov_b32_e32 v61, v129
	v_mov_b32_e32 v60, v129
	v_mov_b32_e32 v59, v129
	v_mov_b32_e32 v58, v129
	v_mov_b32_e32 v57, v129
	v_mov_b32_e32 v56, v129
	v_mov_b32_e32 v47, v129
	v_mov_b32_e32 v46, v129
	v_mov_b32_e32 v45, v129
	v_mov_b32_e32 v44, v129
	v_mov_b32_e32 v43, v129
	v_mov_b32_e32 v42, v129
	v_mov_b32_e32 v41, v129
	v_mov_b32_e32 v40, v129
	v_mov_b32_e32 v31, v129
	v_mov_b32_e32 v30, v129
	v_mov_b32_e32 v29, v129
	v_mov_b32_e32 v28, v129
	v_mov_b32_e32 v27, v129
	v_mov_b32_e32 v26, v129
	v_mov_b32_e32 v25, v129
	v_mov_b32_e32 v24, v129
	v_mov_b32_e32 v15, v129
	v_mov_b32_e32 v14, v129
	v_mov_b32_e32 v13, v129
	v_mov_b32_e32 v12, v129
	v_mov_b32_e32 v11, v129
	v_mov_b32_e32 v10, v129
	v_mov_b32_e32 v9, v129
	v_mov_b32_e32 v8, v129
	v_mov_b32_e32 v55, v129
	v_mov_b32_e32 v54, v129
	v_mov_b32_e32 v53, v129
	v_mov_b32_e32 v52, v129
	v_mov_b32_e32 v51, v129
	v_mov_b32_e32 v50, v129
	v_mov_b32_e32 v49, v129
	v_mov_b32_e32 v48, v129
	v_mov_b32_e32 v39, v129
	v_mov_b32_e32 v38, v129
	v_mov_b32_e32 v37, v129
	v_mov_b32_e32 v36, v129
	v_mov_b32_e32 v35, v129
	v_mov_b32_e32 v34, v129
	v_mov_b32_e32 v33, v129
	v_mov_b32_e32 v32, v129
	v_mov_b32_e32 v23, v129
	v_mov_b32_e32 v22, v129
	v_mov_b32_e32 v21, v129
	v_mov_b32_e32 v20, v129
	v_mov_b32_e32 v19, v129
	v_mov_b32_e32 v18, v129
	v_mov_b32_e32 v17, v129
	v_mov_b32_e32 v16, v129
	v_mov_b32_e32 v7, v129
	v_mov_b32_e32 v6, v129
	v_mov_b32_e32 v5, v129
	v_mov_b32_e32 v4, v129
	v_mov_b32_e32 v3, v129
	v_mov_b32_e32 v2, v129
	v_mov_b32_e32 v1, v129
	v_mov_b32_e32 v0, v129
	s_cbranch_vccnz .LBB0_132
	s_add_u32 s44, s6, 0x80
	s_addc_u32 s45, s7, 0
	s_add_u32 s12, s46, 0x100
	v_mov_b32_e32 v0, 0
	s_addc_u32 s13, s47, 0
	s_mov_b32 s6, 0
	v_mov_b32_e32 v1, v0
	v_mov_b32_e32 v2, v0
	v_mov_b32_e32 v3, v0
	v_mov_b32_e32 v4, v0
	v_mov_b32_e32 v5, v0
	v_mov_b32_e32 v6, v0
	v_mov_b32_e32 v7, v0
	v_mov_b32_e32 v16, v0
	v_mov_b32_e32 v17, v0
	v_mov_b32_e32 v18, v0
	v_mov_b32_e32 v19, v0
	v_mov_b32_e32 v20, v0
	v_mov_b32_e32 v21, v0
	v_mov_b32_e32 v22, v0
	v_mov_b32_e32 v23, v0
	v_mov_b32_e32 v32, v0
	v_mov_b32_e32 v33, v0
	v_mov_b32_e32 v34, v0
	v_mov_b32_e32 v35, v0
	v_mov_b32_e32 v36, v0
	v_mov_b32_e32 v37, v0
	v_mov_b32_e32 v38, v0
	v_mov_b32_e32 v39, v0
	v_mov_b32_e32 v48, v0
	v_mov_b32_e32 v49, v0
	v_mov_b32_e32 v50, v0
	v_mov_b32_e32 v51, v0
	v_mov_b32_e32 v52, v0
	v_mov_b32_e32 v53, v0
	v_mov_b32_e32 v54, v0
	v_mov_b32_e32 v55, v0
	v_mov_b32_e32 v8, v0
	v_mov_b32_e32 v9, v0
	v_mov_b32_e32 v10, v0
	v_mov_b32_e32 v11, v0
	v_mov_b32_e32 v12, v0
	v_mov_b32_e32 v13, v0
	v_mov_b32_e32 v14, v0
	v_mov_b32_e32 v15, v0
	v_mov_b32_e32 v24, v0
	v_mov_b32_e32 v25, v0
	v_mov_b32_e32 v26, v0
	v_mov_b32_e32 v27, v0
	v_mov_b32_e32 v28, v0
	v_mov_b32_e32 v29, v0
	v_mov_b32_e32 v30, v0
	v_mov_b32_e32 v31, v0
	v_mov_b32_e32 v40, v0
	v_mov_b32_e32 v41, v0
	v_mov_b32_e32 v42, v0
	v_mov_b32_e32 v43, v0
	v_mov_b32_e32 v44, v0
	v_mov_b32_e32 v45, v0
	v_mov_b32_e32 v46, v0
	v_mov_b32_e32 v47, v0
	v_mov_b32_e32 v56, v0
	v_mov_b32_e32 v57, v0
	v_mov_b32_e32 v58, v0
	v_mov_b32_e32 v59, v0
	v_mov_b32_e32 v60, v0
	v_mov_b32_e32 v61, v0
	v_mov_b32_e32 v62, v0
	v_mov_b32_e32 v63, v0
	v_mov_b32_e32 v64, v0
	v_mov_b32_e32 v65, v0
	v_mov_b32_e32 v66, v0
	v_mov_b32_e32 v67, v0
	v_mov_b32_e32 v68, v0
	v_mov_b32_e32 v69, v0
	v_mov_b32_e32 v70, v0
	v_mov_b32_e32 v71, v0
	v_mov_b32_e32 v80, v0
	v_mov_b32_e32 v81, v0
	v_mov_b32_e32 v82, v0
	v_mov_b32_e32 v83, v0
	v_mov_b32_e32 v84, v0
	v_mov_b32_e32 v85, v0
	v_mov_b32_e32 v86, v0
	v_mov_b32_e32 v87, v0
	v_mov_b32_e32 v98, v0
	v_mov_b32_e32 v99, v0
	v_mov_b32_e32 v100, v0
	v_mov_b32_e32 v101, v0
	v_mov_b32_e32 v102, v0
	v_mov_b32_e32 v103, v0
	v_mov_b32_e32 v104, v0
	v_mov_b32_e32 v105, v0
	v_mov_b32_e32 v114, v0
	v_mov_b32_e32 v115, v0
	v_mov_b32_e32 v116, v0
	v_mov_b32_e32 v117, v0
	v_mov_b32_e32 v118, v0
	v_mov_b32_e32 v119, v0
	v_mov_b32_e32 v120, v0
	v_mov_b32_e32 v121, v0
	v_mov_b32_e32 v72, v0
	v_mov_b32_e32 v73, v0
	v_mov_b32_e32 v74, v0
	v_mov_b32_e32 v75, v0
	v_mov_b32_e32 v76, v0
	v_mov_b32_e32 v77, v0
	v_mov_b32_e32 v78, v0
	v_mov_b32_e32 v79, v0
	v_mov_b32_e32 v88, v0
	v_mov_b32_e32 v89, v0
	v_mov_b32_e32 v90, v0
	v_mov_b32_e32 v91, v0
	v_mov_b32_e32 v92, v0
	v_mov_b32_e32 v93, v0
	v_mov_b32_e32 v94, v0
	v_mov_b32_e32 v95, v0
	v_mov_b32_e32 v106, v0
	v_mov_b32_e32 v107, v0
	v_mov_b32_e32 v108, v0
	v_mov_b32_e32 v109, v0
	v_mov_b32_e32 v110, v0
	v_mov_b32_e32 v111, v0
	v_mov_b32_e32 v112, v0
	v_mov_b32_e32 v113, v0
	v_mov_b32_e32 v122, v0
	v_mov_b32_e32 v123, v0
	v_mov_b32_e32 v124, v0
	v_mov_b32_e32 v125, v0
	v_mov_b32_e32 v126, v0
	v_mov_b32_e32 v127, v0
	v_mov_b32_e32 v128, v0
	v_mov_b32_e32 v129, v0
	v_readlane_b32 s7, v254, 61
	s_nop 3
	s_cmp_lt_u32 s7, 0x100
	s_cbranch_scc1 .Lg0_prio_done
	s_setprio 1
; #define PG8_STAGE(bufoff, gbase, voff) do { _Pragma("unroll") for (int _i = 0; _i < 2; ++_i) \
;         __builtin_amdgcn_global_load_lds((const unsigned*)((const char*)(gbase) + (voff)[_i]), (PG8_LAS unsigned*)(lds + (bufoff) + ldsw + _i * 8192), 16, 0, 0); } while (0)
; #define PG8_LDA(dst, b, h) do { _Pragma("unroll") for (int m = 0; m < 4; ++m) _Pragma("unroll") for (int k = 0; k < 2; ++k) dst[m][k] = *(const PG8_LAS bf16x8*)(lds + PG8_SA(b, h) + aoff + m * 2048 + k * 1024); } while (0)
; #define PG8_LDB(dst, b, h) do { _Pragma("unroll") for (int n = 0; n < 2; ++n) _Pragma("unroll") for (int k = 0; k < 2; ++k) dst[n][k] = *(const PG8_LAS bf16x8*)(lds + PG8_SB(b, h) + boff + n * 2048 + k * 1024); } while (0)
; #define PG8_MMA(ai, bj, At, Bt) do { __builtin_amdgcn_s_setprio(1); _Pragma("unroll") for (int m = 0; m < 4; ++m) _Pragma("unroll") for (int n = 0; n < 2; ++n) _Pragma("unroll") for (int k = 0; k < 2; ++k) \
;         acc[ai][bj][m][n] = __builtin_amdgcn_mfma_f32_16x16x32_bf16(Bt[n][k], At[m][k], acc[ai][bj][m][n], 0, 0, 0); __builtin_amdgcn_s_setprio(0); } while (0)
; #define PG8_WAIT_V(n) asm volatile("s_waitcnt vmcnt(" #n ")" ::: "memory")
; #define PG8_WAIT_L(n) asm volatile("s_waitcnt lgkmcnt(" #n ")" ::: "memory")
; #define PG8_BAR __builtin_amdgcn_s_barrier()
; #define PG8_SCHED __builtin_amdgcn_sched_barrier(0)
; template <class Epi>
; __device__ __forceinline__ void gemm_phase(PG8_LAS unsigned char* lds, const Gemm g, const StaticOrder& S, const Epi& E, const int wave_s) {
;     ...
;         for (int t = 0; t < nt; t += 2) {
;             const bool last = (t == nt - 2);
;             const char* a1 = cA + (size_t)(t + 1) * kstep;
;             const char* a2 = last ? nA : cA + (size_t)(t + 2) * kstep; const char* b2 = last ? nB : cB + (size_t)(t + 2) * kstep;
;             const char* a3 = a2 + kstep; const char* b3 = b2 + kstep;
;             PG8_LDB(B0, 0, 0); PG8_LDB(B1, 0, 1); PG8_SCHED; PG8_LDA(At, 0, 0); PG8_STAGE(PG8_SA(1, 1), a1 + hstepA, voffA);
;             PG8_WAIT_V(8); PG8_WAIT_L(0); PG8_BAR; PG8_MMA(0, 0, At, B0); PG8_MMA(0, 1, At, B1); PG8_BAR; PG8_SCHED;
;             PG8_LDA(At, 0, 1); PG8_STAGE(PG8_SB(0, 0), b2, voffB); PG8_STAGE(PG8_SB(0, 1), b2 + hstepB, voffB); PG8_STAGE(PG8_SA(0, 0), a2, voffA);
;             PG8_WAIT_V(8); PG8_WAIT_L(0); PG8_BAR; PG8_MMA(1, 0, At, B0); PG8_MMA(1, 1, At, B1); PG8_BAR; PG8_SCHED;
.Lg0_prio_done:
.LBB0_131:
	s_add_i32 s46, s6, 2
	s_add_u32 s47, s44, 0x80
	s_addc_u32 s7, s45, 0
	s_add_i32 s61, 0, 0x10000
	s_cmp_eq_u32 s40, s6
	s_cselect_b32 s7, s91, s7
	s_cselect_b32 s6, s90, s47
	s_cselect_b32 s73, s93, s13
	s_cselect_b32 s72, s92, s12
	s_add_i32 s47, 0, 0x14000
	v_add_u32_e32 v142, s61, v97
	v_add_u32_e32 v158, s47, v97
	ds_read_b128 v[130:133], v142
	ds_read_b128 v[134:137], v142 offset:1024
	ds_read_b128 v[138:141], v142 offset:2048
	ds_read_b128 v[142:145], v142 offset:3072
	ds_read_b128 v[146:149], v158
	ds_read_b128 v[150:153], v158 offset:1024
	ds_read_b128 v[154:157], v158 offset:2048
	ds_read_b128 v[158:161], v158 offset:3072
	v_lshl_add_u64 v[194:195], s[44:45], 0, v[224:225]
	s_add_i32 m0, s9, 0xc000
	ds_read_b128 v[162:165], v232
	ds_read_b128 v[166:169], v232 offset:1024
	ds_read_b128 v[170:173], v232 offset:2048
	ds_read_b128 v[174:177], v232 offset:3072
	ds_read_b128 v[178:181], v232 offset:4096
	ds_read_b128 v[182:185], v232 offset:5120
	ds_read_b128 v[186:189], v232 offset:6144
	ds_read_b128 v[190:193], v232 offset:7168
	global_load_lds_dwordx4 v[194:195], off
	v_lshl_add_u64 v[194:195], s[44:45], 0, v[226:227]
	s_add_i32 m0, s9, 0xe000
	s_nop 0
	global_load_lds_dwordx4 v[194:195], off
	s_waitcnt vmcnt(8)
	s_waitcnt lgkmcnt(0)
	s_barrier
	s_waitcnt lgkmcnt(0)
	v_mfma_f32_16x16x32_bf16 v[126:129], v[130:133], v[162:165], v[126:129]
	v_mfma_f32_16x16x32_bf16 v[122:125], v[138:141], v[162:165], v[122:125]
	v_mfma_f32_16x16x32_bf16 v[110:113], v[130:133], v[170:173], v[110:113]
	v_mfma_f32_16x16x32_bf16 v[106:109], v[138:141], v[170:173], v[106:109]
	v_mfma_f32_16x16x32_bf16 v[92:95], v[130:133], v[178:181], v[92:95]
	v_mfma_f32_16x16x32_bf16 v[88:91], v[138:141], v[178:181], v[88:91]
	v_mfma_f32_16x16x32_bf16 v[76:79], v[130:133], v[186:189], v[76:79]
	v_mfma_f32_16x16x32_bf16 v[72:75], v[138:141], v[186:189], v[72:75]
	v_mfma_f32_16x16x32_bf16 v[126:129], v[134:137], v[166:169], v[126:129]
	v_mfma_f32_16x16x32_bf16 v[122:125], v[142:145], v[166:169], v[122:125]
	v_mfma_f32_16x16x32_bf16 v[110:113], v[134:137], v[174:177], v[110:113]
	v_mfma_f32_16x16x32_bf16 v[106:109], v[142:145], v[174:177], v[106:109]
	v_mfma_f32_16x16x32_bf16 v[92:95], v[134:137], v[182:185], v[92:95]
	v_mfma_f32_16x16x32_bf16 v[88:91], v[142:145], v[182:185], v[88:91]
	v_mfma_f32_16x16x32_bf16 v[76:79], v[134:137], v[190:193], v[76:79]
	v_mfma_f32_16x16x32_bf16 v[72:75], v[142:145], v[190:193], v[72:75]
	v_mfma_f32_16x16x32_bf16 v[118:121], v[146:149], v[162:165], v[118:121]
	v_mfma_f32_16x16x32_bf16 v[114:117], v[154:157], v[162:165], v[114:117]
	v_mfma_f32_16x16x32_bf16 v[102:105], v[146:149], v[170:173], v[102:105]
	v_mfma_f32_16x16x32_bf16 v[98:101], v[154:157], v[170:173], v[98:101]
	v_mfma_f32_16x16x32_bf16 v[84:87], v[146:149], v[178:181], v[84:87]
	v_mfma_f32_16x16x32_bf16 v[80:83], v[154:157], v[178:181], v[80:83]
	v_mfma_f32_16x16x32_bf16 v[68:71], v[146:149], v[186:189], v[68:71]
	v_mfma_f32_16x16x32_bf16 v[64:67], v[154:157], v[186:189], v[64:67]
	v_mfma_f32_16x16x32_bf16 v[118:121], v[150:153], v[166:169], v[118:121]
	v_mfma_f32_16x16x32_bf16 v[114:117], v[158:161], v[166:169], v[114:117]
	v_mfma_f32_16x16x32_bf16 v[102:105], v[150:153], v[174:177], v[102:105]
	v_mfma_f32_16x16x32_bf16 v[98:101], v[158:161], v[174:177], v[98:101]
	v_mfma_f32_16x16x32_bf16 v[84:87], v[150:153], v[182:185], v[84:87]
	v_mfma_f32_16x16x32_bf16 v[80:83], v[158:161], v[182:185], v[80:83]
	v_mfma_f32_16x16x32_bf16 v[68:71], v[150:153], v[190:193], v[68:71]
	v_mfma_f32_16x16x32_bf16 v[64:67], v[158:161], v[190:193], v[64:67]
	s_barrier
	s_add_i32 s61, s61, s5
	v_lshl_add_u64 v[194:195], s[72:73], 0, v[210:211]
	s_mov_b32 m0, s61
	ds_read_b128 v[162:165], v232 offset:16384
	ds_read_b128 v[166:169], v232 offset:17408
	ds_read_b128 v[170:173], v232 offset:18432
	ds_read_b128 v[174:177], v232 offset:19456
	ds_read_b128 v[178:181], v232 offset:20480
	ds_read_b128 v[182:185], v232 offset:21504
	ds_read_b128 v[186:189], v232 offset:22528
	ds_read_b128 v[190:193], v232 offset:23552
	global_load_lds_dwordx4 v[194:195], off
	s_add_i32 m0, s61, 0x2000
	v_lshl_add_u64 v[196:197], s[72:73], 0, v[222:223]
	s_add_u32 s72, s72, s50
	s_addc_u32 s73, s73, s51
	s_add_i32 s47, s47, s5
	global_load_lds_dwordx4 v[196:197], off
	v_lshl_add_u64 v[198:199], s[72:73], 0, v[210:211]
	s_mov_b32 m0, s47
	v_lshl_add_u64 v[200:201], s[72:73], 0, v[222:223]
	global_load_lds_dwordx4 v[198:199], off
	s_add_i32 m0, s47, 0x2000
	v_lshl_add_u64 v[202:203], s[6:7], 0, v[218:219]
	global_load_lds_dwordx4 v[200:201], off
	s_mov_b32 m0, s9
	v_lshl_add_u64 v[204:205], s[6:7], 0, v[220:221]
	global_load_lds_dwordx4 v[202:203], off
	s_mov_b32 m0, s10
	s_nop 0
	global_load_lds_dwordx4 v[204:205], off
	s_waitcnt vmcnt(8)
	s_waitcnt lgkmcnt(0)
	s_barrier
; #define PG8_STAGE(bufoff, gbase, voff) do { _Pragma("unroll") for (int _i = 0; _i < 2; ++_i) \
;         __builtin_amdgcn_global_load_lds((const unsigned*)((const char*)(gbase) + (voff)[_i]), (PG8_LAS unsigned*)(lds + (bufoff) + ldsw + _i * 8192), 16, 0, 0); } while (0)
; #define PG8_LDA(dst, b, h) do { _Pragma("unroll") for (int m = 0; m < 4; ++m) _Pragma("unroll") for (int k = 0; k < 2; ++k) dst[m][k] = *(const PG8_LAS bf16x8*)(lds + PG8_SA(b, h) + aoff + m * 2048 + k * 1024); } while (0)
; #define PG8_LDB(dst, b, h) do { _Pragma("unroll") for (int n = 0; n < 2; ++n) _Pragma("unroll") for (int k = 0; k < 2; ++k) dst[n][k] = *(const PG8_LAS bf16x8*)(lds + PG8_SB(b, h) + boff + n * 2048 + k * 1024); } while (0)
; #define PG8_MMA(ai, bj, At, Bt) do { __builtin_amdgcn_s_setprio(1); _Pragma("unroll") for (int m = 0; m < 4; ++m) _Pragma("unroll") for (int n = 0; n < 2; ++n) _Pragma("unroll") for (int k = 0; k < 2; ++k) \
;         acc[ai][bj][m][n] = __builtin_amdgcn_mfma_f32_16x16x32_bf16(Bt[n][k], At[m][k], acc[ai][bj][m][n], 0, 0, 0); __builtin_amdgcn_s_setprio(0); } while (0)
; #define PG8_WAIT_V(n) asm volatile("s_waitcnt vmcnt(" #n ")" ::: "memory")
; #define PG8_WAIT_L(n) asm volatile("s_waitcnt lgkmcnt(" #n ")" ::: "memory")
; #define PG8_BAR __builtin_amdgcn_s_barrier()
; template <class Epi>
; __device__ __forceinline__ void gemm_phase(PG8_LAS unsigned char* lds, const Gemm g, const StaticOrder& S, const Epi& E, const int wave_s) {
;     ...
;             PG8_WAIT_V(8); PG8_WAIT_L(0); PG8_BAR; PG8_MMA(0, 0, At, B0); PG8_MMA(0, 1, At, B1); PG8_BAR; PG8_SCHED;
;             PG8_LDA(At, 0, 1); PG8_STAGE(PG8_SB(0, 0), b2, voffB); PG8_STAGE(PG8_SB(0, 1), b2 + hstepB, voffB); PG8_STAGE(PG8_SA(0, 0), a2, voffA);
;             PG8_WAIT_V(8); PG8_WAIT_L(0); PG8_BAR; PG8_MMA(1, 0, At, B0); PG8_MMA(1, 1, At, B1); PG8_BAR; PG8_SCHED;
;             PG8_LDB(B0, 1, 0); PG8_LDB(B1, 1, 1); PG8_SCHED; PG8_LDA(At, 1, 0); PG8_STAGE(PG8_SA(0, 1), a2 + hstepA, voffA);
;             PG8_WAIT_V(8); PG8_WAIT_L(0); PG8_BAR; PG8_MMA(0, 0, At, B0); PG8_MMA(0, 1, At, B1); PG8_BAR; PG8_SCHED;
;             PG8_LDA(At, 1, 1); PG8_STAGE(PG8_SB(1, 0), b3, voffB); PG8_STAGE(PG8_SB(1, 1), b3 + hstepB, voffB); PG8_STAGE(PG8_SA(1, 0), a3, voffA);
;             PG8_WAIT_V(8); PG8_WAIT_L(0); PG8_BAR; PG8_MMA(1, 0, At, B0); PG8_MMA(1, 1, At, B1); PG8_BAR; PG8_SCHED;
	s_waitcnt lgkmcnt(0)
	v_mfma_f32_16x16x32_bf16 v[60:63], v[130:133], v[162:165], v[60:63]
	v_mfma_f32_16x16x32_bf16 v[56:59], v[138:141], v[162:165], v[56:59]
	v_mfma_f32_16x16x32_bf16 v[44:47], v[130:133], v[170:173], v[44:47]
	v_mfma_f32_16x16x32_bf16 v[40:43], v[138:141], v[170:173], v[40:43]
	v_mfma_f32_16x16x32_bf16 v[28:31], v[130:133], v[178:181], v[28:31]
	v_mfma_f32_16x16x32_bf16 v[24:27], v[138:141], v[178:181], v[24:27]
	v_mfma_f32_16x16x32_bf16 v[12:15], v[130:133], v[186:189], v[12:15]
	v_mfma_f32_16x16x32_bf16 v[8:11], v[138:141], v[186:189], v[8:11]
	v_mfma_f32_16x16x32_bf16 v[60:63], v[134:137], v[166:169], v[60:63]
	v_mfma_f32_16x16x32_bf16 v[56:59], v[142:145], v[166:169], v[56:59]
	v_mfma_f32_16x16x32_bf16 v[44:47], v[134:137], v[174:177], v[44:47]
	v_mfma_f32_16x16x32_bf16 v[40:43], v[142:145], v[174:177], v[40:43]
	v_mfma_f32_16x16x32_bf16 v[28:31], v[134:137], v[182:185], v[28:31]
	v_mfma_f32_16x16x32_bf16 v[24:27], v[142:145], v[182:185], v[24:27]
	v_mfma_f32_16x16x32_bf16 v[12:15], v[134:137], v[190:193], v[12:15]
	v_mfma_f32_16x16x32_bf16 v[8:11], v[142:145], v[190:193], v[8:11]
	v_mfma_f32_16x16x32_bf16 v[52:55], v[146:149], v[162:165], v[52:55]
	v_mfma_f32_16x16x32_bf16 v[48:51], v[154:157], v[162:165], v[48:51]
	v_mfma_f32_16x16x32_bf16 v[36:39], v[146:149], v[170:173], v[36:39]
	v_mfma_f32_16x16x32_bf16 v[32:35], v[154:157], v[170:173], v[32:35]
	v_mfma_f32_16x16x32_bf16 v[20:23], v[146:149], v[178:181], v[20:23]
	v_mfma_f32_16x16x32_bf16 v[16:19], v[154:157], v[178:181], v[16:19]
	v_mfma_f32_16x16x32_bf16 v[4:7], v[146:149], v[186:189], v[4:7]
	v_mfma_f32_16x16x32_bf16 v[0:3], v[154:157], v[186:189], v[0:3]
	v_mfma_f32_16x16x32_bf16 v[52:55], v[150:153], v[166:169], v[52:55]
	v_mfma_f32_16x16x32_bf16 v[48:51], v[158:161], v[166:169], v[48:51]
	v_mfma_f32_16x16x32_bf16 v[36:39], v[150:153], v[174:177], v[36:39]
	v_mfma_f32_16x16x32_bf16 v[32:35], v[158:161], v[174:177], v[32:35]
	v_mfma_f32_16x16x32_bf16 v[20:23], v[150:153], v[182:185], v[20:23]
	v_mfma_f32_16x16x32_bf16 v[16:19], v[158:161], v[182:185], v[16:19]
	v_mfma_f32_16x16x32_bf16 v[4:7], v[150:153], v[190:193], v[4:7]
	v_mfma_f32_16x16x32_bf16 v[0:3], v[158:161], v[190:193], v[0:3]
	s_barrier
	s_add_i32 s47, 0, 0x18000
	s_add_i32 s61, 0, 0x1c000
	v_add_u32_e32 v142, s47, v97
	v_add_u32_e32 v158, s61, v97
	ds_read_b128 v[130:133], v142
	ds_read_b128 v[134:137], v142 offset:1024
	ds_read_b128 v[138:141], v142 offset:2048
	ds_read_b128 v[142:145], v142 offset:3072
	ds_read_b128 v[146:149], v158
	ds_read_b128 v[150:153], v158 offset:1024
	ds_read_b128 v[154:157], v158 offset:2048
	ds_read_b128 v[158:161], v158 offset:3072
	s_add_u32 s6, s6, s48
	s_addc_u32 s7, s7, s49
	s_mov_b32 m0, s11
	v_lshl_add_u64 v[206:207], s[6:7], 0, v[218:219]
	ds_read_b128 v[162:165], v232 offset:32768
	ds_read_b128 v[166:169], v232 offset:33792
	ds_read_b128 v[170:173], v232 offset:34816
	ds_read_b128 v[174:177], v232 offset:35840
	ds_read_b128 v[178:181], v232 offset:36864
	ds_read_b128 v[182:185], v232 offset:37888
	ds_read_b128 v[186:189], v232 offset:38912
	ds_read_b128 v[190:193], v232 offset:39936
	global_load_lds_dwordx4 v[206:207], off
	v_lshl_add_u64 v[206:207], s[6:7], 0, v[220:221]
	s_mov_b32 m0, s16
	s_nop 0
	global_load_lds_dwordx4 v[206:207], off
	s_waitcnt vmcnt(8)
	s_waitcnt lgkmcnt(0)
	s_barrier
	s_waitcnt lgkmcnt(0)
	v_mfma_f32_16x16x32_bf16 v[126:129], v[130:133], v[162:165], v[126:129]
	v_mfma_f32_16x16x32_bf16 v[122:125], v[138:141], v[162:165], v[122:125]
	v_mfma_f32_16x16x32_bf16 v[110:113], v[130:133], v[170:173], v[110:113]
	v_mfma_f32_16x16x32_bf16 v[106:109], v[138:141], v[170:173], v[106:109]
	v_mfma_f32_16x16x32_bf16 v[92:95], v[130:133], v[178:181], v[92:95]
	v_mfma_f32_16x16x32_bf16 v[88:91], v[138:141], v[178:181], v[88:91]
	v_mfma_f32_16x16x32_bf16 v[76:79], v[130:133], v[186:189], v[76:79]
	v_mfma_f32_16x16x32_bf16 v[72:75], v[138:141], v[186:189], v[72:75]
	v_mfma_f32_16x16x32_bf16 v[126:129], v[134:137], v[166:169], v[126:129]
	v_mfma_f32_16x16x32_bf16 v[122:125], v[142:145], v[166:169], v[122:125]
	v_mfma_f32_16x16x32_bf16 v[110:113], v[134:137], v[174:177], v[110:113]
	v_mfma_f32_16x16x32_bf16 v[106:109], v[142:145], v[174:177], v[106:109]
	v_mfma_f32_16x16x32_bf16 v[92:95], v[134:137], v[182:185], v[92:95]
	v_mfma_f32_16x16x32_bf16 v[88:91], v[142:145], v[182:185], v[88:91]
	v_mfma_f32_16x16x32_bf16 v[76:79], v[134:137], v[190:193], v[76:79]
	v_mfma_f32_16x16x32_bf16 v[72:75], v[142:145], v[190:193], v[72:75]
	v_mfma_f32_16x16x32_bf16 v[118:121], v[146:149], v[162:165], v[118:121]
	v_mfma_f32_16x16x32_bf16 v[114:117], v[154:157], v[162:165], v[114:117]
	v_mfma_f32_16x16x32_bf16 v[102:105], v[146:149], v[170:173], v[102:105]
	v_mfma_f32_16x16x32_bf16 v[98:101], v[154:157], v[170:173], v[98:101]
	v_mfma_f32_16x16x32_bf16 v[84:87], v[146:149], v[178:181], v[84:87]
	v_mfma_f32_16x16x32_bf16 v[80:83], v[154:157], v[178:181], v[80:83]
	v_mfma_f32_16x16x32_bf16 v[68:71], v[146:149], v[186:189], v[68:71]
	v_mfma_f32_16x16x32_bf16 v[64:67], v[154:157], v[186:189], v[64:67]
	v_mfma_f32_16x16x32_bf16 v[118:121], v[150:153], v[166:169], v[118:121]
	v_mfma_f32_16x16x32_bf16 v[114:117], v[158:161], v[166:169], v[114:117]
	v_mfma_f32_16x16x32_bf16 v[102:105], v[150:153], v[174:177], v[102:105]
	v_mfma_f32_16x16x32_bf16 v[98:101], v[158:161], v[174:177], v[98:101]
	v_mfma_f32_16x16x32_bf16 v[84:87], v[150:153], v[182:185], v[84:87]
	v_mfma_f32_16x16x32_bf16 v[80:83], v[158:161], v[182:185], v[80:83]
	v_mfma_f32_16x16x32_bf16 v[68:71], v[150:153], v[190:193], v[68:71]
	v_mfma_f32_16x16x32_bf16 v[64:67], v[158:161], v[190:193], v[64:67]
	s_barrier
; #define PG8_STAGE(bufoff, gbase, voff) do { _Pragma("unroll") for (int _i = 0; _i < 2; ++_i) \
;         __builtin_amdgcn_global_load_lds((const unsigned*)((const char*)(gbase) + (voff)[_i]), (PG8_LAS unsigned*)(lds + (bufoff) + ldsw + _i * 8192), 16, 0, 0); } while (0)
; #define PG8_LDA(dst, b, h) do { _Pragma("unroll") for (int m = 0; m < 4; ++m) _Pragma("unroll") for (int k = 0; k < 2; ++k) dst[m][k] = *(const PG8_LAS bf16x8*)(lds + PG8_SA(b, h) + aoff + m * 2048 + k * 1024); } while (0)
; #define PG8_MMA(ai, bj, At, Bt) do { __builtin_amdgcn_s_setprio(1); _Pragma("unroll") for (int m = 0; m < 4; ++m) _Pragma("unroll") for (int n = 0; n < 2; ++n) _Pragma("unroll") for (int k = 0; k < 2; ++k) \
;         acc[ai][bj][m][n] = __builtin_amdgcn_mfma_f32_16x16x32_bf16(Bt[n][k], At[m][k], acc[ai][bj][m][n], 0, 0, 0); __builtin_amdgcn_s_setprio(0); } while (0)
; #define PG8_WAIT_V(n) asm volatile("s_waitcnt vmcnt(" #n ")" ::: "memory")
; #define PG8_WAIT_L(n) asm volatile("s_waitcnt lgkmcnt(" #n ")" ::: "memory")
; #define PG8_BAR __builtin_amdgcn_s_barrier()
; #define PG8_SCHED __builtin_amdgcn_sched_barrier(0)
; template <class Epi>
; __device__ __forceinline__ void gemm_phase(PG8_LAS unsigned char* lds, const Gemm g, const StaticOrder& S, const Epi& E, const int wave_s) {
;     ...
;             PG8_WAIT_V(8); PG8_WAIT_L(0); PG8_BAR; PG8_MMA(0, 0, At, B0); PG8_MMA(0, 1, At, B1); PG8_BAR; PG8_SCHED;
;             PG8_LDA(At, 1, 1); PG8_STAGE(PG8_SB(1, 0), b3, voffB); PG8_STAGE(PG8_SB(1, 1), b3 + hstepB, voffB); PG8_STAGE(PG8_SA(1, 0), a3, voffA);
;             PG8_WAIT_V(8); PG8_WAIT_L(0); PG8_BAR; PG8_MMA(1, 0, At, B0); PG8_MMA(1, 1, At, B1); PG8_BAR; PG8_SCHED;
;         }
	s_add_i32 s6, s47, s5
	v_lshl_add_u64 v[194:195], v[194:195], 0, s[52:53]
	s_mov_b32 m0, s6
	ds_read_b128 v[162:165], v232 offset:49152
	ds_read_b128 v[166:169], v232 offset:50176
	ds_read_b128 v[170:173], v232 offset:51200
	ds_read_b128 v[174:177], v232 offset:52224
	ds_read_b128 v[178:181], v232 offset:53248
	ds_read_b128 v[182:185], v232 offset:54272
	ds_read_b128 v[186:189], v232 offset:55296
	ds_read_b128 v[190:193], v232 offset:56320
	global_load_lds_dwordx4 v[194:195], off
	v_lshl_add_u64 v[194:195], v[196:197], 0, s[52:53]
	s_add_i32 m0, s6, 0x2000
	s_add_i32 s6, s61, s5
	global_load_lds_dwordx4 v[194:195], off
	v_lshl_add_u64 v[194:195], v[198:199], 0, s[52:53]
	s_mov_b32 m0, s6
	s_nop 0
	global_load_lds_dwordx4 v[194:195], off
	v_lshl_add_u64 v[194:195], v[200:201], 0, s[52:53]
	s_add_i32 m0, s6, 0x2000
	s_nop 0
	global_load_lds_dwordx4 v[194:195], off
	v_lshl_add_u64 v[194:195], v[202:203], 0, s[52:53]
	s_mov_b32 m0, s38
	s_nop 0
	global_load_lds_dwordx4 v[194:195], off
	v_lshl_add_u64 v[194:195], v[204:205], 0, s[52:53]
	s_mov_b32 m0, s39
	s_nop 0
	global_load_lds_dwordx4 v[194:195], off
	s_waitcnt vmcnt(8)
	s_waitcnt lgkmcnt(0)
	s_barrier
	s_waitcnt lgkmcnt(0)
	v_mfma_f32_16x16x32_bf16 v[60:63], v[130:133], v[162:165], v[60:63]
	v_mfma_f32_16x16x32_bf16 v[56:59], v[138:141], v[162:165], v[56:59]
	v_mfma_f32_16x16x32_bf16 v[44:47], v[130:133], v[170:173], v[44:47]
	v_mfma_f32_16x16x32_bf16 v[40:43], v[138:141], v[170:173], v[40:43]
	v_mfma_f32_16x16x32_bf16 v[28:31], v[130:133], v[178:181], v[28:31]
	v_mfma_f32_16x16x32_bf16 v[24:27], v[138:141], v[178:181], v[24:27]
	v_mfma_f32_16x16x32_bf16 v[12:15], v[130:133], v[186:189], v[12:15]
	v_mfma_f32_16x16x32_bf16 v[8:11], v[138:141], v[186:189], v[8:11]
	v_mfma_f32_16x16x32_bf16 v[60:63], v[134:137], v[166:169], v[60:63]
	v_mfma_f32_16x16x32_bf16 v[56:59], v[142:145], v[166:169], v[56:59]
	v_mfma_f32_16x16x32_bf16 v[44:47], v[134:137], v[174:177], v[44:47]
	v_mfma_f32_16x16x32_bf16 v[40:43], v[142:145], v[174:177], v[40:43]
	v_mfma_f32_16x16x32_bf16 v[28:31], v[134:137], v[182:185], v[28:31]
	v_mfma_f32_16x16x32_bf16 v[24:27], v[142:145], v[182:185], v[24:27]
	v_mfma_f32_16x16x32_bf16 v[12:15], v[134:137], v[190:193], v[12:15]
	v_mfma_f32_16x16x32_bf16 v[8:11], v[142:145], v[190:193], v[8:11]
	v_mfma_f32_16x16x32_bf16 v[52:55], v[146:149], v[162:165], v[52:55]
	v_mfma_f32_16x16x32_bf16 v[48:51], v[154:157], v[162:165], v[48:51]
	v_mfma_f32_16x16x32_bf16 v[36:39], v[146:149], v[170:173], v[36:39]
	v_mfma_f32_16x16x32_bf16 v[32:35], v[154:157], v[170:173], v[32:35]
	v_mfma_f32_16x16x32_bf16 v[20:23], v[146:149], v[178:181], v[20:23]
	v_mfma_f32_16x16x32_bf16 v[16:19], v[154:157], v[178:181], v[16:19]
	v_mfma_f32_16x16x32_bf16 v[4:7], v[146:149], v[186:189], v[4:7]
	v_mfma_f32_16x16x32_bf16 v[0:3], v[154:157], v[186:189], v[0:3]
	v_mfma_f32_16x16x32_bf16 v[52:55], v[150:153], v[166:169], v[52:55]
	v_mfma_f32_16x16x32_bf16 v[48:51], v[158:161], v[166:169], v[48:51]
	v_mfma_f32_16x16x32_bf16 v[36:39], v[150:153], v[174:177], v[36:39]
	v_mfma_f32_16x16x32_bf16 v[32:35], v[158:161], v[174:177], v[32:35]
	v_mfma_f32_16x16x32_bf16 v[20:23], v[150:153], v[182:185], v[20:23]
	v_mfma_f32_16x16x32_bf16 v[16:19], v[158:161], v[182:185], v[16:19]
	v_mfma_f32_16x16x32_bf16 v[4:7], v[150:153], v[190:193], v[4:7]
	v_mfma_f32_16x16x32_bf16 v[0:3], v[158:161], v[190:193], v[0:3]
	s_barrier
	s_add_u32 s44, s44, 0x100
	s_addc_u32 s45, s45, 0
	s_add_u32 s12, s12, 0x100
	s_addc_u32 s13, s13, 0
	s_cmp_ge_i32 s46, s37
	s_mov_b32 s6, s46
	s_cbranch_scc0 .LBB0_131
	s_setprio 0

; #define PG8_BAR __builtin_amdgcn_s_barrier()
; template <class Epi>
; __device__ __forceinline__ void gemm_phase(PG8_LAS unsigned char* lds, const Gemm g, const StaticOrder& S, const Epi& E, const int wave_s) {
;     ...
;         const bool has_next = S.next(ui + 1, nxt);
;         const char* nA = has_next ? (const char*)g.A + (size_t)nxt.pm * tstepA : cA; const char* nB = has_next ? (const char*)g.Bt + (size_t)nxt.pn * tstepB : cB;
;         float pre[8]; E.prefetch(cur, wr, fr, pre);
;         for (int t = 0; t < nt; t += 2) {
;             const bool last = (t == nt - 2);
;             const char* a1 = cA + (size_t)(t + 1) * kstep;
;             const char* a2 = last ? nA : cA + (size_t)(t + 2) * kstep; const char* b2 = last ? nB : cB + (size_t)(t + 2) * kstep;
;             const char* a3 = a2 + kstep; const char* b3 = b2 + kstep;
;             PG8_LDB(B0, 0, 0); PG8_LDB(B1, 0, 1); PG8_SCHED; PG8_LDA(At, 0, 0); PG8_STAGE(PG8_SA(1, 1), a1 + hstepA, voffA);
;             PG8_WAIT_V(8); PG8_WAIT_L(0); PG8_BAR; PG8_MMA(0, 0, At, B0); PG8_MMA(0, 1, At, B1); PG8_BAR; PG8_SCHED;
;             PG8_LDA(At, 0, 1); PG8_STAGE(PG8_SB(0, 0), b2, voffB); PG8_STAGE(PG8_SB(0, 1), b2 + hstepB, voffB); PG8_STAGE(PG8_SA(0, 0), a2, voffA);
;             PG8_WAIT_V(8); PG8_WAIT_L(0); PG8_BAR; PG8_MMA(1, 0, At, B0); PG8_MMA(1, 1, At, B1); PG8_BAR; PG8_SCHED;
;             PG8_LDB(B0, 1, 0); PG8_LDB(B1, 1, 1); PG8_SCHED; PG8_LDA(At, 1, 0); PG8_STAGE(PG8_SA(0, 1), a2 + hstepA, voffA);
;             PG8_WAIT_V(8); PG8_WAIT_L(0); PG8_BAR; PG8_MMA(0, 0, At, B0); PG8_MMA(0, 1, At, B1); PG8_BAR; PG8_SCHED;
;             PG8_LDA(At, 1, 1); PG8_STAGE(PG8_SB(1, 0), b3, voffB); PG8_STAGE(PG8_SB(1, 1), b3 + hstepB, voffB); PG8_STAGE(PG8_SA(1, 0), a3, voffA);
;             PG8_WAIT_V(8); PG8_WAIT_L(0); PG8_BAR; PG8_MMA(1, 0, At, B0); PG8_MMA(1, 1, At, B1); PG8_BAR; PG8_SCHED;
;         }
;         if (wr == 0) PG8_BAR;
;         { const int tl = fresh_tid(wave_s); const int w2 = wave_s, l2 = tl & 63;
;           E(acc, cur, w2 >> 2, w2 & 3, l2 & 15, l2 >> 4, pre); }
;         if (!has_next) break;
; #pragma unroll
;         for (int a = 0; a < 2; ++a)
; #pragma unroll
;             for (int b = 0; b < 2; ++b)
; #pragma unroll
;                 for (int m = 0; m < 4; ++m)
; #pragma unroll
;                     for (int n = 0; n < 2; ++n) acc[a][b][m][n] = (f32x4){0.f, 0.f, 0.f, 0.f};
.LBB0_334:
	v_mov_b32_e32 v125, 0
	s_andn2_b64 vcc, exec, s[70:71]
	v_mov_b32_e32 v124, v125
	v_mov_b32_e32 v123, v125
	v_mov_b32_e32 v122, v125
	v_mov_b32_e32 v129, v125
	v_mov_b32_e32 v128, v125
	v_mov_b32_e32 v127, v125
	v_mov_b32_e32 v126, v125
	v_mov_b32_e32 v113, v125
	v_mov_b32_e32 v112, v125
	v_mov_b32_e32 v111, v125
	v_mov_b32_e32 v110, v125
	v_mov_b32_e32 v109, v125
	v_mov_b32_e32 v108, v125
	v_mov_b32_e32 v107, v125
	v_mov_b32_e32 v106, v125
	v_mov_b32_e32 v95, v125
	v_mov_b32_e32 v94, v125
	v_mov_b32_e32 v93, v125
	v_mov_b32_e32 v92, v125
	v_mov_b32_e32 v91, v125
	v_mov_b32_e32 v90, v125
	v_mov_b32_e32 v89, v125
	v_mov_b32_e32 v88, v125
	v_mov_b32_e32 v79, v125
	v_mov_b32_e32 v78, v125
	v_mov_b32_e32 v77, v125
	v_mov_b32_e32 v76, v125
	v_mov_b32_e32 v75, v125
	v_mov_b32_e32 v74, v125
	v_mov_b32_e32 v73, v125
	v_mov_b32_e32 v72, v125
	v_mov_b32_e32 v121, v125
	v_mov_b32_e32 v120, v125
	v_mov_b32_e32 v119, v125
	v_mov_b32_e32 v118, v125
	v_mov_b32_e32 v117, v125
	v_mov_b32_e32 v116, v125
	v_mov_b32_e32 v115, v125
	v_mov_b32_e32 v114, v125
	v_mov_b32_e32 v105, v125
	v_mov_b32_e32 v104, v125
	v_mov_b32_e32 v103, v125
	v_mov_b32_e32 v102, v125
	v_mov_b32_e32 v101, v125
	v_mov_b32_e32 v100, v125
	v_mov_b32_e32 v99, v125
	v_mov_b32_e32 v98, v125
	v_mov_b32_e32 v87, v125
	v_mov_b32_e32 v86, v125
	v_mov_b32_e32 v85, v125
	v_mov_b32_e32 v84, v125
	v_mov_b32_e32 v83, v125
	v_mov_b32_e32 v82, v125
	v_mov_b32_e32 v81, v125
	v_mov_b32_e32 v80, v125
	v_mov_b32_e32 v71, v125
	v_mov_b32_e32 v70, v125
	v_mov_b32_e32 v69, v125
	v_mov_b32_e32 v68, v125
	v_mov_b32_e32 v67, v125
	v_mov_b32_e32 v66, v125
	v_mov_b32_e32 v65, v125
	v_mov_b32_e32 v64, v125
	v_mov_b32_e32 v63, v125
	v_mov_b32_e32 v62, v125
	v_mov_b32_e32 v61, v125
	v_mov_b32_e32 v60, v125
	v_mov_b32_e32 v59, v125
	v_mov_b32_e32 v58, v125
	v_mov_b32_e32 v57, v125
	v_mov_b32_e32 v56, v125
	v_mov_b32_e32 v47, v125
	v_mov_b32_e32 v46, v125
	v_mov_b32_e32 v45, v125
	v_mov_b32_e32 v44, v125
	v_mov_b32_e32 v43, v125
	v_mov_b32_e32 v42, v125
	v_mov_b32_e32 v41, v125
	v_mov_b32_e32 v40, v125
	v_mov_b32_e32 v31, v125
	v_mov_b32_e32 v30, v125
	v_mov_b32_e32 v29, v125
	v_mov_b32_e32 v28, v125
	v_mov_b32_e32 v27, v125
	v_mov_b32_e32 v26, v125
	v_mov_b32_e32 v25, v125
	v_mov_b32_e32 v24, v125
	v_mov_b32_e32 v15, v125
	v_mov_b32_e32 v14, v125
	v_mov_b32_e32 v13, v125
	v_mov_b32_e32 v12, v125
	v_mov_b32_e32 v11, v125
	v_mov_b32_e32 v10, v125
	v_mov_b32_e32 v9, v125
	v_mov_b32_e32 v8, v125
	v_mov_b32_e32 v55, v125
	v_mov_b32_e32 v54, v125
	v_mov_b32_e32 v53, v125
	v_mov_b32_e32 v52, v125
	v_mov_b32_e32 v51, v125
	v_mov_b32_e32 v50, v125
	v_mov_b32_e32 v49, v125
	v_mov_b32_e32 v48, v125
	v_mov_b32_e32 v39, v125
	v_mov_b32_e32 v38, v125
	v_mov_b32_e32 v37, v125
	v_mov_b32_e32 v36, v125
	v_mov_b32_e32 v35, v125
	v_mov_b32_e32 v34, v125
	v_mov_b32_e32 v33, v125
	v_mov_b32_e32 v32, v125
	v_mov_b32_e32 v23, v125
	v_mov_b32_e32 v22, v125
	v_mov_b32_e32 v21, v125
	v_mov_b32_e32 v20, v125
	v_mov_b32_e32 v19, v125
	v_mov_b32_e32 v18, v125
	v_mov_b32_e32 v17, v125
	v_mov_b32_e32 v16, v125
	v_mov_b32_e32 v7, v125
	v_mov_b32_e32 v6, v125
	v_mov_b32_e32 v5, v125
	v_mov_b32_e32 v4, v125
	v_mov_b32_e32 v3, v125
	v_mov_b32_e32 v2, v125
	v_mov_b32_e32 v1, v125
	v_mov_b32_e32 v0, v125
	s_cbranch_vccnz .LBB0_337
	s_add_u32 s44, s46, 0x80
	s_addc_u32 s45, s47, 0
	s_add_u32 s9, s6, 0x100
	v_mov_b32_e32 v0, 0
	s_addc_u32 s25, s7, 0
	s_mov_b32 s6, 0
	v_mov_b32_e32 v1, v0
	v_mov_b32_e32 v2, v0
	v_mov_b32_e32 v3, v0
	v_mov_b32_e32 v4, v0
	v_mov_b32_e32 v5, v0
	v_mov_b32_e32 v6, v0
	v_mov_b32_e32 v7, v0
	v_mov_b32_e32 v16, v0
	v_mov_b32_e32 v17, v0
	v_mov_b32_e32 v18, v0
	v_mov_b32_e32 v19, v0
	v_mov_b32_e32 v20, v0
	v_mov_b32_e32 v21, v0
	v_mov_b32_e32 v22, v0
	v_mov_b32_e32 v23, v0
	v_mov_b32_e32 v32, v0
	v_mov_b32_e32 v33, v0
	v_mov_b32_e32 v34, v0
	v_mov_b32_e32 v35, v0
	v_mov_b32_e32 v36, v0
	v_mov_b32_e32 v37, v0
	v_mov_b32_e32 v38, v0
	v_mov_b32_e32 v39, v0
	v_mov_b32_e32 v48, v0
	v_mov_b32_e32 v49, v0
	v_mov_b32_e32 v50, v0
	v_mov_b32_e32 v51, v0
	v_mov_b32_e32 v52, v0
	v_mov_b32_e32 v53, v0
	v_mov_b32_e32 v54, v0
	v_mov_b32_e32 v55, v0
	v_mov_b32_e32 v8, v0
	v_mov_b32_e32 v9, v0
	v_mov_b32_e32 v10, v0
	v_mov_b32_e32 v11, v0
	v_mov_b32_e32 v12, v0
	v_mov_b32_e32 v13, v0
	v_mov_b32_e32 v14, v0
	v_mov_b32_e32 v15, v0
	v_mov_b32_e32 v24, v0
	v_mov_b32_e32 v25, v0
	v_mov_b32_e32 v26, v0
	v_mov_b32_e32 v27, v0
	v_mov_b32_e32 v28, v0
	v_mov_b32_e32 v29, v0
	v_mov_b32_e32 v30, v0
	v_mov_b32_e32 v31, v0
	v_mov_b32_e32 v40, v0
	v_mov_b32_e32 v41, v0
	v_mov_b32_e32 v42, v0
	v_mov_b32_e32 v43, v0
	v_mov_b32_e32 v44, v0
	v_mov_b32_e32 v45, v0
	v_mov_b32_e32 v46, v0
	v_mov_b32_e32 v47, v0
	v_mov_b32_e32 v56, v0
	v_mov_b32_e32 v57, v0
	v_mov_b32_e32 v58, v0
	v_mov_b32_e32 v59, v0
	v_mov_b32_e32 v60, v0
	v_mov_b32_e32 v61, v0
	v_mov_b32_e32 v62, v0
	v_mov_b32_e32 v63, v0
	v_mov_b32_e32 v64, v0
	v_mov_b32_e32 v65, v0
	v_mov_b32_e32 v66, v0
	v_mov_b32_e32 v67, v0
	v_mov_b32_e32 v68, v0
	v_mov_b32_e32 v69, v0
	v_mov_b32_e32 v70, v0
	v_mov_b32_e32 v71, v0
	v_mov_b32_e32 v80, v0
	v_mov_b32_e32 v81, v0
	v_mov_b32_e32 v82, v0
	v_mov_b32_e32 v83, v0
	v_mov_b32_e32 v84, v0
	v_mov_b32_e32 v85, v0
	v_mov_b32_e32 v86, v0
	v_mov_b32_e32 v87, v0
	v_mov_b32_e32 v98, v0
	v_mov_b32_e32 v99, v0
	v_mov_b32_e32 v100, v0
	v_mov_b32_e32 v101, v0
	v_mov_b32_e32 v102, v0
	v_mov_b32_e32 v103, v0
	v_mov_b32_e32 v104, v0
	v_mov_b32_e32 v105, v0
	v_mov_b32_e32 v114, v0
	v_mov_b32_e32 v115, v0
	v_mov_b32_e32 v116, v0
	v_mov_b32_e32 v117, v0
	v_mov_b32_e32 v118, v0
	v_mov_b32_e32 v119, v0
	v_mov_b32_e32 v120, v0
	v_mov_b32_e32 v121, v0
	v_mov_b32_e32 v72, v0
	v_mov_b32_e32 v73, v0
	v_mov_b32_e32 v74, v0
	v_mov_b32_e32 v75, v0
	v_mov_b32_e32 v76, v0
	v_mov_b32_e32 v77, v0
	v_mov_b32_e32 v78, v0
	v_mov_b32_e32 v79, v0
	v_mov_b32_e32 v88, v0
	v_mov_b32_e32 v89, v0
	v_mov_b32_e32 v90, v0
	v_mov_b32_e32 v91, v0
	v_mov_b32_e32 v92, v0
	v_mov_b32_e32 v93, v0
	v_mov_b32_e32 v94, v0
	v_mov_b32_e32 v95, v0
	v_mov_b32_e32 v106, v0
	v_mov_b32_e32 v107, v0
	v_mov_b32_e32 v108, v0
	v_mov_b32_e32 v109, v0
	v_mov_b32_e32 v110, v0
	v_mov_b32_e32 v111, v0
	v_mov_b32_e32 v112, v0
	v_mov_b32_e32 v113, v0
	v_mov_b32_e32 v126, v0
	v_mov_b32_e32 v127, v0
	v_mov_b32_e32 v128, v0
	v_mov_b32_e32 v129, v0
	v_mov_b32_e32 v122, v0
	v_mov_b32_e32 v123, v0
	v_mov_b32_e32 v124, v0
	v_mov_b32_e32 v125, v0
	v_readlane_b32 s7, v254, 61
	s_nop 3
	s_cmp_lt_u32 s7, 0x100
	s_cbranch_scc1 .Lg1_prio_done
	s_setprio 1
; #define PG8_STAGE(bufoff, gbase, voff) do { _Pragma("unroll") for (int _i = 0; _i < 2; ++_i) \
;         __builtin_amdgcn_global_load_lds((const unsigned*)((const char*)(gbase) + (voff)[_i]), (PG8_LAS unsigned*)(lds + (bufoff) + ldsw + _i * 8192), 16, 0, 0); } while (0)
; #define PG8_LDA(dst, b, h) do { _Pragma("unroll") for (int m = 0; m < 4; ++m) _Pragma("unroll") for (int k = 0; k < 2; ++k) dst[m][k] = *(const PG8_LAS bf16x8*)(lds + PG8_SA(b, h) + aoff + m * 2048 + k * 1024); } while (0)
; #define PG8_LDB(dst, b, h) do { _Pragma("unroll") for (int n = 0; n < 2; ++n) _Pragma("unroll") for (int k = 0; k < 2; ++k) dst[n][k] = *(const PG8_LAS bf16x8*)(lds + PG8_SB(b, h) + boff + n * 2048 + k * 1024); } while (0)
; #define PG8_MMA(ai, bj, At, Bt) do { __builtin_amdgcn_s_setprio(1); _Pragma("unroll") for (int m = 0; m < 4; ++m) _Pragma("unroll") for (int n = 0; n < 2; ++n) _Pragma("unroll") for (int k = 0; k < 2; ++k) \
;         acc[ai][bj][m][n] = __builtin_amdgcn_mfma_f32_16x16x32_bf16(Bt[n][k], At[m][k], acc[ai][bj][m][n], 0, 0, 0); __builtin_amdgcn_s_setprio(0); } while (0)
; #define PG8_WAIT_V(n) asm volatile("s_waitcnt vmcnt(" #n ")" ::: "memory")
; #define PG8_WAIT_L(n) asm volatile("s_waitcnt lgkmcnt(" #n ")" ::: "memory")
; #define PG8_BAR __builtin_amdgcn_s_barrier()
; #define PG8_SCHED __builtin_amdgcn_sched_barrier(0)
; template <class Epi>
; __device__ __forceinline__ void gemm_phase(PG8_LAS unsigned char* lds, const Gemm g, const StaticOrder& S, const Epi& E, const int wave_s) {
;     ...
;         for (int t = 0; t < nt; t += 2) {
;             const bool last = (t == nt - 2);
;             const char* a1 = cA + (size_t)(t + 1) * kstep;
;             const char* a2 = last ? nA : cA + (size_t)(t + 2) * kstep; const char* b2 = last ? nB : cB + (size_t)(t + 2) * kstep;
;             const char* a3 = a2 + kstep; const char* b3 = b2 + kstep;
;             PG8_LDB(B0, 0, 0); PG8_LDB(B1, 0, 1); PG8_SCHED; PG8_LDA(At, 0, 0); PG8_STAGE(PG8_SA(1, 1), a1 + hstepA, voffA);
;             PG8_WAIT_V(8); PG8_WAIT_L(0); PG8_BAR; PG8_MMA(0, 0, At, B0); PG8_MMA(0, 1, At, B1); PG8_BAR; PG8_SCHED;
;             PG8_LDA(At, 0, 1); PG8_STAGE(PG8_SB(0, 0), b2, voffB); PG8_STAGE(PG8_SB(0, 1), b2 + hstepB, voffB); PG8_STAGE(PG8_SA(0, 0), a2, voffA);
;             PG8_WAIT_V(8); PG8_WAIT_L(0); PG8_BAR; PG8_MMA(1, 0, At, B0); PG8_MMA(1, 1, At, B1); PG8_BAR; PG8_SCHED;
.Lg1_prio_done:
.LBB0_336:
	s_add_i32 s36, s6, 2
	s_add_u32 s38, s44, 0x80
	s_addc_u32 s7, s45, 0
	s_add_i32 s46, 0, 0x10000
	s_cmp_eq_u32 s5, s6
	s_cselect_b32 s7, s91, s7
	s_cselect_b32 s6, s90, s38
	s_cselect_b32 s39, s93, s25
	s_cselect_b32 s38, s92, s9
	s_add_i32 s47, 0, 0x14000
	v_add_u32_e32 v154, s46, v97
	v_add_u32_e32 v171, s47, v97
	ds_read_b128 v[130:133], v154
	ds_read_b128 v[134:137], v154 offset:1024
	ds_read_b128 v[150:153], v154 offset:2048
	ds_read_b128 v[154:157], v154 offset:3072
	ds_read_b128 v[158:161], v171
	ds_read_b128 v[162:165], v171 offset:1024
	ds_read_b128 v[166:169], v171 offset:2048
	ds_read_b128 v[172:175], v171 offset:3072
	v_lshl_add_u64 v[208:209], s[44:45], 0, v[146:147]
	s_add_i32 m0, s13, 0xc000
	ds_read_b128 v[176:179], v170
	ds_read_b128 v[180:183], v170 offset:1024
	ds_read_b128 v[184:187], v170 offset:2048
	ds_read_b128 v[188:191], v170 offset:3072
	ds_read_b128 v[192:195], v170 offset:4096
	ds_read_b128 v[196:199], v170 offset:5120
	ds_read_b128 v[200:203], v170 offset:6144
	ds_read_b128 v[204:207], v170 offset:7168
	global_load_lds_dwordx4 v[208:209], off
	v_lshl_add_u64 v[208:209], s[44:45], 0, v[148:149]
	s_add_i32 m0, s13, 0xe000
	s_nop 0
	global_load_lds_dwordx4 v[208:209], off
	s_waitcnt vmcnt(8)
	s_waitcnt lgkmcnt(0)
	s_barrier
	s_waitcnt lgkmcnt(0)
	v_mfma_f32_16x16x32_bf16 v[122:125], v[130:133], v[176:179], v[122:125]
	v_mfma_f32_16x16x32_bf16 v[126:129], v[150:153], v[176:179], v[126:129]
	v_mfma_f32_16x16x32_bf16 v[110:113], v[130:133], v[184:187], v[110:113]
	v_mfma_f32_16x16x32_bf16 v[106:109], v[150:153], v[184:187], v[106:109]
	v_mfma_f32_16x16x32_bf16 v[92:95], v[130:133], v[192:195], v[92:95]
	v_mfma_f32_16x16x32_bf16 v[88:91], v[150:153], v[192:195], v[88:91]
	v_mfma_f32_16x16x32_bf16 v[76:79], v[130:133], v[200:203], v[76:79]
	v_mfma_f32_16x16x32_bf16 v[72:75], v[150:153], v[200:203], v[72:75]
	v_mfma_f32_16x16x32_bf16 v[122:125], v[134:137], v[180:183], v[122:125]
	v_mfma_f32_16x16x32_bf16 v[126:129], v[154:157], v[180:183], v[126:129]
	v_mfma_f32_16x16x32_bf16 v[110:113], v[134:137], v[188:191], v[110:113]
	v_mfma_f32_16x16x32_bf16 v[106:109], v[154:157], v[188:191], v[106:109]
	v_mfma_f32_16x16x32_bf16 v[92:95], v[134:137], v[196:199], v[92:95]
	v_mfma_f32_16x16x32_bf16 v[88:91], v[154:157], v[196:199], v[88:91]
	v_mfma_f32_16x16x32_bf16 v[76:79], v[134:137], v[204:207], v[76:79]
	v_mfma_f32_16x16x32_bf16 v[72:75], v[154:157], v[204:207], v[72:75]
	v_mfma_f32_16x16x32_bf16 v[118:121], v[158:161], v[176:179], v[118:121]
	v_mfma_f32_16x16x32_bf16 v[114:117], v[166:169], v[176:179], v[114:117]
	v_mfma_f32_16x16x32_bf16 v[102:105], v[158:161], v[184:187], v[102:105]
	v_mfma_f32_16x16x32_bf16 v[98:101], v[166:169], v[184:187], v[98:101]
	v_mfma_f32_16x16x32_bf16 v[84:87], v[158:161], v[192:195], v[84:87]
	v_mfma_f32_16x16x32_bf16 v[80:83], v[166:169], v[192:195], v[80:83]
	v_mfma_f32_16x16x32_bf16 v[68:71], v[158:161], v[200:203], v[68:71]
	v_mfma_f32_16x16x32_bf16 v[64:67], v[166:169], v[200:203], v[64:67]
	v_mfma_f32_16x16x32_bf16 v[118:121], v[162:165], v[180:183], v[118:121]
	v_mfma_f32_16x16x32_bf16 v[114:117], v[172:175], v[180:183], v[114:117]
	v_mfma_f32_16x16x32_bf16 v[102:105], v[162:165], v[188:191], v[102:105]
	v_mfma_f32_16x16x32_bf16 v[98:101], v[172:175], v[188:191], v[98:101]
	v_mfma_f32_16x16x32_bf16 v[84:87], v[162:165], v[196:199], v[84:87]
	v_mfma_f32_16x16x32_bf16 v[80:83], v[172:175], v[196:199], v[80:83]
	v_mfma_f32_16x16x32_bf16 v[68:71], v[162:165], v[204:207], v[68:71]
	v_mfma_f32_16x16x32_bf16 v[64:67], v[172:175], v[204:207], v[64:67]
	s_barrier
	s_add_i32 s46, s46, s12
	v_lshl_add_u64 v[208:209], s[38:39], 0, v[140:141]
	s_mov_b32 m0, s46
	ds_read_b128 v[176:179], v170 offset:16384
	ds_read_b128 v[180:183], v170 offset:17408
	ds_read_b128 v[184:187], v170 offset:18432
	ds_read_b128 v[188:191], v170 offset:19456
	ds_read_b128 v[192:195], v170 offset:20480
	ds_read_b128 v[196:199], v170 offset:21504
	ds_read_b128 v[200:203], v170 offset:22528
	ds_read_b128 v[204:207], v170 offset:23552
	global_load_lds_dwordx4 v[208:209], off
	s_add_i32 m0, s46, 0x2000
	v_lshl_add_u64 v[218:219], s[38:39], 0, v[144:145]
	s_add_u32 s38, s38, s62
	s_addc_u32 s39, s39, s63
	s_add_i32 s46, s47, s12
	global_load_lds_dwordx4 v[218:219], off
	v_lshl_add_u64 v[220:221], s[38:39], 0, v[140:141]
	s_mov_b32 m0, s46
	v_lshl_add_u64 v[222:223], s[38:39], 0, v[144:145]
	global_load_lds_dwordx4 v[220:221], off
	s_add_i32 m0, s46, 0x2000
	v_lshl_add_u64 v[224:225], s[6:7], 0, v[138:139]
	global_load_lds_dwordx4 v[222:223], off
	s_mov_b32 m0, s13
	v_lshl_add_u64 v[226:227], s[6:7], 0, v[142:143]
	global_load_lds_dwordx4 v[224:225], off
	s_mov_b32 m0, s40
	s_nop 0
	global_load_lds_dwordx4 v[226:227], off
	s_waitcnt vmcnt(8)
	s_waitcnt lgkmcnt(0)
	s_barrier
; #define PG8_STAGE(bufoff, gbase, voff) do { _Pragma("unroll") for (int _i = 0; _i < 2; ++_i) \
;         __builtin_amdgcn_global_load_lds((const unsigned*)((const char*)(gbase) + (voff)[_i]), (PG8_LAS unsigned*)(lds + (bufoff) + ldsw + _i * 8192), 16, 0, 0); } while (0)
; #define PG8_LDA(dst, b, h) do { _Pragma("unroll") for (int m = 0; m < 4; ++m) _Pragma("unroll") for (int k = 0; k < 2; ++k) dst[m][k] = *(const PG8_LAS bf16x8*)(lds + PG8_SA(b, h) + aoff + m * 2048 + k * 1024); } while (0)
; #define PG8_LDB(dst, b, h) do { _Pragma("unroll") for (int n = 0; n < 2; ++n) _Pragma("unroll") for (int k = 0; k < 2; ++k) dst[n][k] = *(const PG8_LAS bf16x8*)(lds + PG8_SB(b, h) + boff + n * 2048 + k * 1024); } while (0)
; #define PG8_MMA(ai, bj, At, Bt) do { __builtin_amdgcn_s_setprio(1); _Pragma("unroll") for (int m = 0; m < 4; ++m) _Pragma("unroll") for (int n = 0; n < 2; ++n) _Pragma("unroll") for (int k = 0; k < 2; ++k) \
;         acc[ai][bj][m][n] = __builtin_amdgcn_mfma_f32_16x16x32_bf16(Bt[n][k], At[m][k], acc[ai][bj][m][n], 0, 0, 0); __builtin_amdgcn_s_setprio(0); } while (0)
; #define PG8_WAIT_V(n) asm volatile("s_waitcnt vmcnt(" #n ")" ::: "memory")
; #define PG8_WAIT_L(n) asm volatile("s_waitcnt lgkmcnt(" #n ")" ::: "memory")
; #define PG8_BAR __builtin_amdgcn_s_barrier()
; template <class Epi>
; __device__ __forceinline__ void gemm_phase(PG8_LAS unsigned char* lds, const Gemm g, const StaticOrder& S, const Epi& E, const int wave_s) {
;     ...
;             PG8_WAIT_V(8); PG8_WAIT_L(0); PG8_BAR; PG8_MMA(0, 0, At, B0); PG8_MMA(0, 1, At, B1); PG8_BAR; PG8_SCHED;
;             PG8_LDA(At, 0, 1); PG8_STAGE(PG8_SB(0, 0), b2, voffB); PG8_STAGE(PG8_SB(0, 1), b2 + hstepB, voffB); PG8_STAGE(PG8_SA(0, 0), a2, voffA);
;             PG8_WAIT_V(8); PG8_WAIT_L(0); PG8_BAR; PG8_MMA(1, 0, At, B0); PG8_MMA(1, 1, At, B1); PG8_BAR; PG8_SCHED;
;             PG8_LDB(B0, 1, 0); PG8_LDB(B1, 1, 1); PG8_SCHED; PG8_LDA(At, 1, 0); PG8_STAGE(PG8_SA(0, 1), a2 + hstepA, voffA);
;             PG8_WAIT_V(8); PG8_WAIT_L(0); PG8_BAR; PG8_MMA(0, 0, At, B0); PG8_MMA(0, 1, At, B1); PG8_BAR; PG8_SCHED;
;             PG8_LDA(At, 1, 1); PG8_STAGE(PG8_SB(1, 0), b3, voffB); PG8_STAGE(PG8_SB(1, 1), b3 + hstepB, voffB); PG8_STAGE(PG8_SA(1, 0), a3, voffA);
;             PG8_WAIT_V(8); PG8_WAIT_L(0); PG8_BAR; PG8_MMA(1, 0, At, B0); PG8_MMA(1, 1, At, B1); PG8_BAR; PG8_SCHED;
	s_waitcnt lgkmcnt(0)
	v_mfma_f32_16x16x32_bf16 v[60:63], v[130:133], v[176:179], v[60:63]
	v_mfma_f32_16x16x32_bf16 v[56:59], v[150:153], v[176:179], v[56:59]
	v_mfma_f32_16x16x32_bf16 v[44:47], v[130:133], v[184:187], v[44:47]
	v_mfma_f32_16x16x32_bf16 v[40:43], v[150:153], v[184:187], v[40:43]
	v_mfma_f32_16x16x32_bf16 v[28:31], v[130:133], v[192:195], v[28:31]
	v_mfma_f32_16x16x32_bf16 v[24:27], v[150:153], v[192:195], v[24:27]
	v_mfma_f32_16x16x32_bf16 v[12:15], v[130:133], v[200:203], v[12:15]
	v_mfma_f32_16x16x32_bf16 v[8:11], v[150:153], v[200:203], v[8:11]
	v_mfma_f32_16x16x32_bf16 v[60:63], v[134:137], v[180:183], v[60:63]
	v_mfma_f32_16x16x32_bf16 v[56:59], v[154:157], v[180:183], v[56:59]
	v_mfma_f32_16x16x32_bf16 v[44:47], v[134:137], v[188:191], v[44:47]
	v_mfma_f32_16x16x32_bf16 v[40:43], v[154:157], v[188:191], v[40:43]
	v_mfma_f32_16x16x32_bf16 v[28:31], v[134:137], v[196:199], v[28:31]
	v_mfma_f32_16x16x32_bf16 v[24:27], v[154:157], v[196:199], v[24:27]
	v_mfma_f32_16x16x32_bf16 v[12:15], v[134:137], v[204:207], v[12:15]
	v_mfma_f32_16x16x32_bf16 v[8:11], v[154:157], v[204:207], v[8:11]
	v_mfma_f32_16x16x32_bf16 v[52:55], v[158:161], v[176:179], v[52:55]
	v_mfma_f32_16x16x32_bf16 v[48:51], v[166:169], v[176:179], v[48:51]
	v_mfma_f32_16x16x32_bf16 v[36:39], v[158:161], v[184:187], v[36:39]
	v_mfma_f32_16x16x32_bf16 v[32:35], v[166:169], v[184:187], v[32:35]
	v_mfma_f32_16x16x32_bf16 v[20:23], v[158:161], v[192:195], v[20:23]
	v_mfma_f32_16x16x32_bf16 v[16:19], v[166:169], v[192:195], v[16:19]
	v_mfma_f32_16x16x32_bf16 v[4:7], v[158:161], v[200:203], v[4:7]
	v_mfma_f32_16x16x32_bf16 v[0:3], v[166:169], v[200:203], v[0:3]
	v_mfma_f32_16x16x32_bf16 v[52:55], v[162:165], v[180:183], v[52:55]
	v_mfma_f32_16x16x32_bf16 v[48:51], v[172:175], v[180:183], v[48:51]
	v_mfma_f32_16x16x32_bf16 v[36:39], v[162:165], v[188:191], v[36:39]
	v_mfma_f32_16x16x32_bf16 v[32:35], v[172:175], v[188:191], v[32:35]
	v_mfma_f32_16x16x32_bf16 v[20:23], v[162:165], v[196:199], v[20:23]
	v_mfma_f32_16x16x32_bf16 v[16:19], v[172:175], v[196:199], v[16:19]
	v_mfma_f32_16x16x32_bf16 v[4:7], v[162:165], v[204:207], v[4:7]
	v_mfma_f32_16x16x32_bf16 v[0:3], v[172:175], v[204:207], v[0:3]
	s_barrier
	s_add_i32 s38, 0, 0x18000
	s_add_i32 s39, 0, 0x1c000
	v_add_u32_e32 v154, s38, v97
	v_add_u32_e32 v171, s39, v97
	ds_read_b128 v[130:133], v154
	ds_read_b128 v[134:137], v154 offset:1024
	ds_read_b128 v[150:153], v154 offset:2048
	ds_read_b128 v[154:157], v154 offset:3072
	ds_read_b128 v[158:161], v171
	ds_read_b128 v[162:165], v171 offset:1024
	ds_read_b128 v[166:169], v171 offset:2048
	ds_read_b128 v[172:175], v171 offset:3072
	s_add_u32 s6, s6, s60
	s_addc_u32 s7, s7, s61
	s_mov_b32 m0, s41
	v_lshl_add_u64 v[228:229], s[6:7], 0, v[138:139]
	ds_read_b128 v[176:179], v170 offset:32768
	ds_read_b128 v[180:183], v170 offset:33792
	ds_read_b128 v[184:187], v170 offset:34816
	ds_read_b128 v[188:191], v170 offset:35840
	ds_read_b128 v[192:195], v170 offset:36864
	ds_read_b128 v[196:199], v170 offset:37888
	ds_read_b128 v[200:203], v170 offset:38912
	ds_read_b128 v[204:207], v170 offset:39936
	global_load_lds_dwordx4 v[228:229], off
	v_lshl_add_u64 v[228:229], s[6:7], 0, v[142:143]
	s_mov_b32 m0, s4
	s_nop 0
	global_load_lds_dwordx4 v[228:229], off
	s_waitcnt vmcnt(8)
	s_waitcnt lgkmcnt(0)
	s_barrier
	s_waitcnt lgkmcnt(0)
	v_mfma_f32_16x16x32_bf16 v[122:125], v[130:133], v[176:179], v[122:125]
	v_mfma_f32_16x16x32_bf16 v[126:129], v[150:153], v[176:179], v[126:129]
	v_mfma_f32_16x16x32_bf16 v[110:113], v[130:133], v[184:187], v[110:113]
	v_mfma_f32_16x16x32_bf16 v[106:109], v[150:153], v[184:187], v[106:109]
	v_mfma_f32_16x16x32_bf16 v[92:95], v[130:133], v[192:195], v[92:95]
	v_mfma_f32_16x16x32_bf16 v[88:91], v[150:153], v[192:195], v[88:91]
	v_mfma_f32_16x16x32_bf16 v[76:79], v[130:133], v[200:203], v[76:79]
	v_mfma_f32_16x16x32_bf16 v[72:75], v[150:153], v[200:203], v[72:75]
	v_mfma_f32_16x16x32_bf16 v[122:125], v[134:137], v[180:183], v[122:125]
	v_mfma_f32_16x16x32_bf16 v[126:129], v[154:157], v[180:183], v[126:129]
	v_mfma_f32_16x16x32_bf16 v[110:113], v[134:137], v[188:191], v[110:113]
	v_mfma_f32_16x16x32_bf16 v[106:109], v[154:157], v[188:191], v[106:109]
	v_mfma_f32_16x16x32_bf16 v[92:95], v[134:137], v[196:199], v[92:95]
	v_mfma_f32_16x16x32_bf16 v[88:91], v[154:157], v[196:199], v[88:91]
	v_mfma_f32_16x16x32_bf16 v[76:79], v[134:137], v[204:207], v[76:79]
	v_mfma_f32_16x16x32_bf16 v[72:75], v[154:157], v[204:207], v[72:75]
	v_mfma_f32_16x16x32_bf16 v[118:121], v[158:161], v[176:179], v[118:121]
	v_mfma_f32_16x16x32_bf16 v[114:117], v[166:169], v[176:179], v[114:117]
	v_mfma_f32_16x16x32_bf16 v[102:105], v[158:161], v[184:187], v[102:105]
	v_mfma_f32_16x16x32_bf16 v[98:101], v[166:169], v[184:187], v[98:101]
	v_mfma_f32_16x16x32_bf16 v[84:87], v[158:161], v[192:195], v[84:87]
	v_mfma_f32_16x16x32_bf16 v[80:83], v[166:169], v[192:195], v[80:83]
	v_mfma_f32_16x16x32_bf16 v[68:71], v[158:161], v[200:203], v[68:71]
	v_mfma_f32_16x16x32_bf16 v[64:67], v[166:169], v[200:203], v[64:67]
	v_mfma_f32_16x16x32_bf16 v[118:121], v[162:165], v[180:183], v[118:121]
	v_mfma_f32_16x16x32_bf16 v[114:117], v[172:175], v[180:183], v[114:117]
	v_mfma_f32_16x16x32_bf16 v[102:105], v[162:165], v[188:191], v[102:105]
	v_mfma_f32_16x16x32_bf16 v[98:101], v[172:175], v[188:191], v[98:101]
	v_mfma_f32_16x16x32_bf16 v[84:87], v[162:165], v[196:199], v[84:87]
	v_mfma_f32_16x16x32_bf16 v[80:83], v[172:175], v[196:199], v[80:83]
	v_mfma_f32_16x16x32_bf16 v[68:71], v[162:165], v[204:207], v[68:71]
	v_mfma_f32_16x16x32_bf16 v[64:67], v[172:175], v[204:207], v[64:67]
	s_barrier
; #define PG8_STAGE(bufoff, gbase, voff) do { _Pragma("unroll") for (int _i = 0; _i < 2; ++_i) \
;         __builtin_amdgcn_global_load_lds((const unsigned*)((const char*)(gbase) + (voff)[_i]), (PG8_LAS unsigned*)(lds + (bufoff) + ldsw + _i * 8192), 16, 0, 0); } while (0)
; #define PG8_LDA(dst, b, h) do { _Pragma("unroll") for (int m = 0; m < 4; ++m) _Pragma("unroll") for (int k = 0; k < 2; ++k) dst[m][k] = *(const PG8_LAS bf16x8*)(lds + PG8_SA(b, h) + aoff + m * 2048 + k * 1024); } while (0)
; #define PG8_MMA(ai, bj, At, Bt) do { __builtin_amdgcn_s_setprio(1); _Pragma("unroll") for (int m = 0; m < 4; ++m) _Pragma("unroll") for (int n = 0; n < 2; ++n) _Pragma("unroll") for (int k = 0; k < 2; ++k) \
;         acc[ai][bj][m][n] = __builtin_amdgcn_mfma_f32_16x16x32_bf16(Bt[n][k], At[m][k], acc[ai][bj][m][n], 0, 0, 0); __builtin_amdgcn_s_setprio(0); } while (0)
; #define PG8_WAIT_V(n) asm volatile("s_waitcnt vmcnt(" #n ")" ::: "memory")
; #define PG8_WAIT_L(n) asm volatile("s_waitcnt lgkmcnt(" #n ")" ::: "memory")
; #define PG8_BAR __builtin_amdgcn_s_barrier()
; #define PG8_SCHED __builtin_amdgcn_sched_barrier(0)
; template <class Epi>
; __device__ __forceinline__ void gemm_phase(PG8_LAS unsigned char* lds, const Gemm g, const StaticOrder& S, const Epi& E, const int wave_s) {
;     ...
;             PG8_WAIT_V(8); PG8_WAIT_L(0); PG8_BAR; PG8_MMA(0, 0, At, B0); PG8_MMA(0, 1, At, B1); PG8_BAR; PG8_SCHED;
;             PG8_LDA(At, 1, 1); PG8_STAGE(PG8_SB(1, 0), b3, voffB); PG8_STAGE(PG8_SB(1, 1), b3 + hstepB, voffB); PG8_STAGE(PG8_SA(1, 0), a3, voffA);
;             PG8_WAIT_V(8); PG8_WAIT_L(0); PG8_BAR; PG8_MMA(1, 0, At, B0); PG8_MMA(1, 1, At, B1); PG8_BAR; PG8_SCHED;
;         }
	s_add_i32 s6, s38, s12
	v_lshl_add_u64 v[208:209], v[208:209], 0, s[52:53]
	s_mov_b32 m0, s6
	ds_read_b128 v[176:179], v170 offset:49152
	ds_read_b128 v[180:183], v170 offset:50176
	ds_read_b128 v[184:187], v170 offset:51200
	ds_read_b128 v[188:191], v170 offset:52224
	ds_read_b128 v[192:195], v170 offset:53248
	ds_read_b128 v[196:199], v170 offset:54272
	ds_read_b128 v[200:203], v170 offset:55296
	ds_read_b128 v[204:207], v170 offset:56320
	global_load_lds_dwordx4 v[208:209], off
	v_lshl_add_u64 v[208:209], v[218:219], 0, s[52:53]
	s_add_i32 m0, s6, 0x2000
	s_add_i32 s6, s39, s12
	global_load_lds_dwordx4 v[208:209], off
	v_lshl_add_u64 v[208:209], v[220:221], 0, s[52:53]
	s_mov_b32 m0, s6
	s_nop 0
	global_load_lds_dwordx4 v[208:209], off
	v_lshl_add_u64 v[208:209], v[222:223], 0, s[52:53]
	s_add_i32 m0, s6, 0x2000
	s_nop 0
	global_load_lds_dwordx4 v[208:209], off
	v_lshl_add_u64 v[208:209], v[224:225], 0, s[52:53]
	s_mov_b32 m0, s10
	s_nop 0
	global_load_lds_dwordx4 v[208:209], off
	v_lshl_add_u64 v[208:209], v[226:227], 0, s[52:53]
	s_mov_b32 m0, s11
	s_nop 0
	global_load_lds_dwordx4 v[208:209], off
	s_waitcnt vmcnt(8)
	s_waitcnt lgkmcnt(0)
	s_barrier
	s_waitcnt lgkmcnt(0)
	v_mfma_f32_16x16x32_bf16 v[60:63], v[130:133], v[176:179], v[60:63]
	v_mfma_f32_16x16x32_bf16 v[56:59], v[150:153], v[176:179], v[56:59]
	v_mfma_f32_16x16x32_bf16 v[44:47], v[130:133], v[184:187], v[44:47]
	v_mfma_f32_16x16x32_bf16 v[40:43], v[150:153], v[184:187], v[40:43]
	v_mfma_f32_16x16x32_bf16 v[28:31], v[130:133], v[192:195], v[28:31]
	v_mfma_f32_16x16x32_bf16 v[24:27], v[150:153], v[192:195], v[24:27]
	v_mfma_f32_16x16x32_bf16 v[12:15], v[130:133], v[200:203], v[12:15]
	v_mfma_f32_16x16x32_bf16 v[8:11], v[150:153], v[200:203], v[8:11]
	v_mfma_f32_16x16x32_bf16 v[60:63], v[134:137], v[180:183], v[60:63]
	v_mfma_f32_16x16x32_bf16 v[56:59], v[154:157], v[180:183], v[56:59]
	v_mfma_f32_16x16x32_bf16 v[44:47], v[134:137], v[188:191], v[44:47]
	v_mfma_f32_16x16x32_bf16 v[40:43], v[154:157], v[188:191], v[40:43]
	v_mfma_f32_16x16x32_bf16 v[28:31], v[134:137], v[196:199], v[28:31]
	v_mfma_f32_16x16x32_bf16 v[24:27], v[154:157], v[196:199], v[24:27]
	v_mfma_f32_16x16x32_bf16 v[12:15], v[134:137], v[204:207], v[12:15]
	v_mfma_f32_16x16x32_bf16 v[8:11], v[154:157], v[204:207], v[8:11]
	v_mfma_f32_16x16x32_bf16 v[52:55], v[158:161], v[176:179], v[52:55]
	v_mfma_f32_16x16x32_bf16 v[48:51], v[166:169], v[176:179], v[48:51]
	v_mfma_f32_16x16x32_bf16 v[36:39], v[158:161], v[184:187], v[36:39]
	v_mfma_f32_16x16x32_bf16 v[32:35], v[166:169], v[184:187], v[32:35]
	v_mfma_f32_16x16x32_bf16 v[20:23], v[158:161], v[192:195], v[20:23]
	v_mfma_f32_16x16x32_bf16 v[16:19], v[166:169], v[192:195], v[16:19]
	v_mfma_f32_16x16x32_bf16 v[4:7], v[158:161], v[200:203], v[4:7]
	v_mfma_f32_16x16x32_bf16 v[0:3], v[166:169], v[200:203], v[0:3]
	v_mfma_f32_16x16x32_bf16 v[52:55], v[162:165], v[180:183], v[52:55]
	v_mfma_f32_16x16x32_bf16 v[48:51], v[172:175], v[180:183], v[48:51]
	v_mfma_f32_16x16x32_bf16 v[36:39], v[162:165], v[188:191], v[36:39]
	v_mfma_f32_16x16x32_bf16 v[32:35], v[172:175], v[188:191], v[32:35]
	v_mfma_f32_16x16x32_bf16 v[20:23], v[162:165], v[196:199], v[20:23]
	v_mfma_f32_16x16x32_bf16 v[16:19], v[172:175], v[196:199], v[16:19]
	v_mfma_f32_16x16x32_bf16 v[4:7], v[162:165], v[204:207], v[4:7]
	v_mfma_f32_16x16x32_bf16 v[0:3], v[172:175], v[204:207], v[0:3]
	s_barrier
	s_add_u32 s44, s44, 0x100
	s_addc_u32 s45, s45, 0
	s_add_u32 s9, s9, 0x100
	s_addc_u32 s25, s25, 0
	s_cmp_ge_i32 s36, s68
	s_mov_b32 s6, s36
	s_cbranch_scc0 .LBB0_336
	s_setprio 0

; template <class Epi>
; __device__ __forceinline__ void gemm_phase(PG8_LAS unsigned char* lds, const Gemm g, const StaticOrder& S, const Epi& E, const int wave_s) {
;     ...
;         for (int t = 0; t < nt; t += 2) {
;             const bool last = (t == nt - 2);
;             const char* a1 = cA + (size_t)(t + 1) * kstep;
;             const char* a2 = last ? nA : cA + (size_t)(t + 2) * kstep; const char* b2 = last ? nB : cB + (size_t)(t + 2) * kstep;
;     ...
;         for (int a = 0; a < 2; ++a)
; #pragma unroll
;             for (int b = 0; b < 2; ++b)
; #pragma unroll
;                 for (int m = 0; m < 4; ++m)
; #pragma unroll
;                     for (int n = 0; n < 2; ++n) acc[a][b][m][n] = (f32x4){0.f, 0.f, 0.f, 0.f};
.LBB0_457:
	v_mov_b32_e32 v129, 0
	s_andn2_b64 vcc, exec, s[66:67]
	v_mov_b32_e32 v128, v129
	v_mov_b32_e32 v127, v129
	v_mov_b32_e32 v126, v129
	v_mov_b32_e32 v125, v129
	v_mov_b32_e32 v124, v129
	v_mov_b32_e32 v123, v129
	v_mov_b32_e32 v122, v129
	v_mov_b32_e32 v113, v129
	v_mov_b32_e32 v112, v129
	v_mov_b32_e32 v111, v129
	v_mov_b32_e32 v110, v129
	v_mov_b32_e32 v109, v129
	v_mov_b32_e32 v108, v129
	v_mov_b32_e32 v107, v129
	v_mov_b32_e32 v106, v129
	v_mov_b32_e32 v95, v129
	v_mov_b32_e32 v94, v129
	v_mov_b32_e32 v93, v129
	v_mov_b32_e32 v92, v129
	v_mov_b32_e32 v91, v129
	v_mov_b32_e32 v90, v129
	v_mov_b32_e32 v89, v129
	v_mov_b32_e32 v88, v129
	v_mov_b32_e32 v79, v129
	v_mov_b32_e32 v78, v129
	v_mov_b32_e32 v77, v129
	v_mov_b32_e32 v76, v129
	v_mov_b32_e32 v75, v129
	v_mov_b32_e32 v74, v129
	v_mov_b32_e32 v73, v129
	v_mov_b32_e32 v72, v129
	v_mov_b32_e32 v121, v129
	v_mov_b32_e32 v120, v129
	v_mov_b32_e32 v119, v129
	v_mov_b32_e32 v118, v129
	v_mov_b32_e32 v117, v129
	v_mov_b32_e32 v116, v129
	v_mov_b32_e32 v115, v129
	v_mov_b32_e32 v114, v129
	v_mov_b32_e32 v105, v129
	v_mov_b32_e32 v104, v129
	v_mov_b32_e32 v103, v129
	v_mov_b32_e32 v102, v129
	v_mov_b32_e32 v101, v129
	v_mov_b32_e32 v100, v129
	v_mov_b32_e32 v99, v129
	v_mov_b32_e32 v98, v129
	v_mov_b32_e32 v87, v129
	v_mov_b32_e32 v86, v129
	v_mov_b32_e32 v85, v129
	v_mov_b32_e32 v84, v129
	v_mov_b32_e32 v83, v129
	v_mov_b32_e32 v82, v129
	v_mov_b32_e32 v81, v129
	v_mov_b32_e32 v80, v129
	v_mov_b32_e32 v71, v129
	v_mov_b32_e32 v70, v129
	v_mov_b32_e32 v69, v129
	v_mov_b32_e32 v68, v129
	v_mov_b32_e32 v67, v129
	v_mov_b32_e32 v66, v129
	v_mov_b32_e32 v65, v129
	v_mov_b32_e32 v64, v129
	v_mov_b32_e32 v63, v129
	v_mov_b32_e32 v62, v129
	v_mov_b32_e32 v61, v129
	v_mov_b32_e32 v60, v129
	v_mov_b32_e32 v59, v129
	v_mov_b32_e32 v58, v129
	v_mov_b32_e32 v57, v129
	v_mov_b32_e32 v56, v129
	v_mov_b32_e32 v47, v129
	v_mov_b32_e32 v46, v129
	v_mov_b32_e32 v45, v129
	v_mov_b32_e32 v44, v129
	v_mov_b32_e32 v43, v129
	v_mov_b32_e32 v42, v129
	v_mov_b32_e32 v41, v129
	v_mov_b32_e32 v40, v129
	v_mov_b32_e32 v31, v129
	v_mov_b32_e32 v30, v129
	v_mov_b32_e32 v29, v129
	v_mov_b32_e32 v28, v129
	v_mov_b32_e32 v27, v129
	v_mov_b32_e32 v26, v129
	v_mov_b32_e32 v25, v129
	v_mov_b32_e32 v24, v129
	v_mov_b32_e32 v15, v129
	v_mov_b32_e32 v14, v129
	v_mov_b32_e32 v13, v129
	v_mov_b32_e32 v12, v129
	v_mov_b32_e32 v11, v129
	v_mov_b32_e32 v10, v129
	v_mov_b32_e32 v9, v129
	v_mov_b32_e32 v8, v129
	v_mov_b32_e32 v55, v129
	v_mov_b32_e32 v54, v129
	v_mov_b32_e32 v53, v129
	v_mov_b32_e32 v52, v129
	v_mov_b32_e32 v51, v129
	v_mov_b32_e32 v50, v129
	v_mov_b32_e32 v49, v129
	v_mov_b32_e32 v48, v129
	v_mov_b32_e32 v39, v129
	v_mov_b32_e32 v38, v129
	v_mov_b32_e32 v37, v129
	v_mov_b32_e32 v36, v129
	v_mov_b32_e32 v35, v129
	v_mov_b32_e32 v34, v129
	v_mov_b32_e32 v33, v129
	v_mov_b32_e32 v32, v129
	v_mov_b32_e32 v23, v129
	v_mov_b32_e32 v22, v129
	v_mov_b32_e32 v21, v129
	v_mov_b32_e32 v20, v129
	v_mov_b32_e32 v19, v129
	v_mov_b32_e32 v18, v129
	v_mov_b32_e32 v17, v129
	v_mov_b32_e32 v16, v129
	v_mov_b32_e32 v7, v129
	v_mov_b32_e32 v6, v129
	v_mov_b32_e32 v5, v129
	v_mov_b32_e32 v4, v129
	v_mov_b32_e32 v3, v129
	v_mov_b32_e32 v2, v129
	v_mov_b32_e32 v1, v129
	v_mov_b32_e32 v0, v129
	s_cbranch_vccnz .LBB0_461
	s_add_u32 s44, s46, 0x80
	s_addc_u32 s45, s47, 0
	s_add_u32 s8, s6, 0x100
	v_mov_b32_e32 v0, 0
	s_addc_u32 s9, s7, 0
	s_mov_b32 s6, 0
	v_mov_b32_e32 v1, v0
	v_mov_b32_e32 v2, v0
	v_mov_b32_e32 v3, v0
	v_mov_b32_e32 v4, v0
	v_mov_b32_e32 v5, v0
	v_mov_b32_e32 v6, v0
	v_mov_b32_e32 v7, v0
	v_mov_b32_e32 v16, v0
	v_mov_b32_e32 v17, v0
	v_mov_b32_e32 v18, v0
	v_mov_b32_e32 v19, v0
	v_mov_b32_e32 v20, v0
	v_mov_b32_e32 v21, v0
	v_mov_b32_e32 v22, v0
	v_mov_b32_e32 v23, v0
	v_mov_b32_e32 v32, v0
	v_mov_b32_e32 v33, v0
	v_mov_b32_e32 v34, v0
	v_mov_b32_e32 v35, v0
	v_mov_b32_e32 v36, v0
	v_mov_b32_e32 v37, v0
	v_mov_b32_e32 v38, v0
	v_mov_b32_e32 v39, v0
	v_mov_b32_e32 v48, v0
	v_mov_b32_e32 v49, v0
	v_mov_b32_e32 v50, v0
	v_mov_b32_e32 v51, v0
	v_mov_b32_e32 v52, v0
	v_mov_b32_e32 v53, v0
	v_mov_b32_e32 v54, v0
	v_mov_b32_e32 v55, v0
	v_mov_b32_e32 v8, v0
	v_mov_b32_e32 v9, v0
	v_mov_b32_e32 v10, v0
	v_mov_b32_e32 v11, v0
	v_mov_b32_e32 v12, v0
	v_mov_b32_e32 v13, v0
	v_mov_b32_e32 v14, v0
	v_mov_b32_e32 v15, v0
	v_mov_b32_e32 v24, v0
	v_mov_b32_e32 v25, v0
	v_mov_b32_e32 v26, v0
	v_mov_b32_e32 v27, v0
	v_mov_b32_e32 v28, v0
	v_mov_b32_e32 v29, v0
	v_mov_b32_e32 v30, v0
	v_mov_b32_e32 v31, v0
	v_mov_b32_e32 v40, v0
	v_mov_b32_e32 v41, v0
	v_mov_b32_e32 v42, v0
	v_mov_b32_e32 v43, v0
	v_mov_b32_e32 v44, v0
	v_mov_b32_e32 v45, v0
	v_mov_b32_e32 v46, v0
	v_mov_b32_e32 v47, v0
	v_mov_b32_e32 v56, v0
	v_mov_b32_e32 v57, v0
	v_mov_b32_e32 v58, v0
	v_mov_b32_e32 v59, v0
	v_mov_b32_e32 v60, v0
	v_mov_b32_e32 v61, v0
	v_mov_b32_e32 v62, v0
	v_mov_b32_e32 v63, v0
	v_mov_b32_e32 v64, v0
	v_mov_b32_e32 v65, v0
	v_mov_b32_e32 v66, v0
	v_mov_b32_e32 v67, v0
	v_mov_b32_e32 v68, v0
	v_mov_b32_e32 v69, v0
	v_mov_b32_e32 v70, v0
	v_mov_b32_e32 v71, v0
	v_mov_b32_e32 v80, v0
	v_mov_b32_e32 v81, v0
	v_mov_b32_e32 v82, v0
	v_mov_b32_e32 v83, v0
	v_mov_b32_e32 v84, v0
	v_mov_b32_e32 v85, v0
	v_mov_b32_e32 v86, v0
	v_mov_b32_e32 v87, v0
	v_mov_b32_e32 v98, v0
	v_mov_b32_e32 v99, v0
	v_mov_b32_e32 v100, v0
	v_mov_b32_e32 v101, v0
	v_mov_b32_e32 v102, v0
	v_mov_b32_e32 v103, v0
	v_mov_b32_e32 v104, v0
	v_mov_b32_e32 v105, v0
	v_mov_b32_e32 v114, v0
	v_mov_b32_e32 v115, v0
	v_mov_b32_e32 v116, v0
	v_mov_b32_e32 v117, v0
	v_mov_b32_e32 v118, v0
	v_mov_b32_e32 v119, v0
	v_mov_b32_e32 v120, v0
	v_mov_b32_e32 v121, v0
	v_mov_b32_e32 v72, v0
	v_mov_b32_e32 v73, v0
	v_mov_b32_e32 v74, v0
	v_mov_b32_e32 v75, v0
	v_mov_b32_e32 v76, v0
	v_mov_b32_e32 v77, v0
	v_mov_b32_e32 v78, v0
	v_mov_b32_e32 v79, v0
	v_mov_b32_e32 v88, v0
	v_mov_b32_e32 v89, v0
	v_mov_b32_e32 v90, v0
	v_mov_b32_e32 v91, v0
	v_mov_b32_e32 v92, v0
	v_mov_b32_e32 v93, v0
	v_mov_b32_e32 v94, v0
	v_mov_b32_e32 v95, v0
	v_mov_b32_e32 v106, v0
	v_mov_b32_e32 v107, v0
	v_mov_b32_e32 v108, v0
	v_mov_b32_e32 v109, v0
	v_mov_b32_e32 v110, v0
	v_mov_b32_e32 v111, v0
	v_mov_b32_e32 v112, v0
	v_mov_b32_e32 v113, v0
	v_mov_b32_e32 v122, v0
	v_mov_b32_e32 v123, v0
	v_mov_b32_e32 v124, v0
	v_mov_b32_e32 v125, v0
	v_mov_b32_e32 v126, v0
	v_mov_b32_e32 v127, v0
	v_mov_b32_e32 v128, v0
	v_mov_b32_e32 v129, v0
	v_readlane_b32 s7, v254, 61
	s_nop 3
	s_cmp_lt_u32 s7, 0x100
	s_cbranch_scc1 .Lg2_prio_done
	s_setprio 1
; #define PG8_STAGE(bufoff, gbase, voff) do { _Pragma("unroll") for (int _i = 0; _i < 2; ++_i) \
;         __builtin_amdgcn_global_load_lds((const unsigned*)((const char*)(gbase) + (voff)[_i]), (PG8_LAS unsigned*)(lds + (bufoff) + ldsw + _i * 8192), 16, 0, 0); } while (0)
; #define PG8_LDA(dst, b, h) do { _Pragma("unroll") for (int m = 0; m < 4; ++m) _Pragma("unroll") for (int k = 0; k < 2; ++k) dst[m][k] = *(const PG8_LAS bf16x8*)(lds + PG8_SA(b, h) + aoff + m * 2048 + k * 1024); } while (0)
; #define PG8_LDB(dst, b, h) do { _Pragma("unroll") for (int n = 0; n < 2; ++n) _Pragma("unroll") for (int k = 0; k < 2; ++k) dst[n][k] = *(const PG8_LAS bf16x8*)(lds + PG8_SB(b, h) + boff + n * 2048 + k * 1024); } while (0)
; #define PG8_MMA(ai, bj, At, Bt) do { __builtin_amdgcn_s_setprio(1); _Pragma("unroll") for (int m = 0; m < 4; ++m) _Pragma("unroll") for (int n = 0; n < 2; ++n) _Pragma("unroll") for (int k = 0; k < 2; ++k) \
;         acc[ai][bj][m][n] = __builtin_amdgcn_mfma_f32_16x16x32_bf16(Bt[n][k], At[m][k], acc[ai][bj][m][n], 0, 0, 0); __builtin_amdgcn_s_setprio(0); } while (0)
; #define PG8_WAIT_V(n) asm volatile("s_waitcnt vmcnt(" #n ")" ::: "memory")
; #define PG8_WAIT_L(n) asm volatile("s_waitcnt lgkmcnt(" #n ")" ::: "memory")
; #define PG8_BAR __builtin_amdgcn_s_barrier()
; #define PG8_SCHED __builtin_amdgcn_sched_barrier(0)
; template <class Epi>
; __device__ __forceinline__ void gemm_phase(PG8_LAS unsigned char* lds, const Gemm g, const StaticOrder& S, const Epi& E, const int wave_s) {
;     ...
;         for (int t = 0; t < nt; t += 2) {
;             const bool last = (t == nt - 2);
;             const char* a1 = cA + (size_t)(t + 1) * kstep;
;             const char* a2 = last ? nA : cA + (size_t)(t + 2) * kstep; const char* b2 = last ? nB : cB + (size_t)(t + 2) * kstep;
;             const char* a3 = a2 + kstep; const char* b3 = b2 + kstep;
;             PG8_LDB(B0, 0, 0); PG8_LDB(B1, 0, 1); PG8_SCHED; PG8_LDA(At, 0, 0); PG8_STAGE(PG8_SA(1, 1), a1 + hstepA, voffA);
;             PG8_WAIT_V(8); PG8_WAIT_L(0); PG8_BAR; PG8_MMA(0, 0, At, B0); PG8_MMA(0, 1, At, B1); PG8_BAR; PG8_SCHED;
;             PG8_LDA(At, 0, 1); PG8_STAGE(PG8_SB(0, 0), b2, voffB); PG8_STAGE(PG8_SB(0, 1), b2 + hstepB, voffB); PG8_STAGE(PG8_SA(0, 0), a2, voffA);
;             PG8_WAIT_V(8); PG8_WAIT_L(0); PG8_BAR; PG8_MMA(1, 0, At, B0); PG8_MMA(1, 1, At, B1); PG8_BAR; PG8_SCHED;
.Lg2_prio_done:
.LBB0_459:
	s_add_i32 s12, s6, 2
	s_add_u32 s13, s44, 0x80
	s_addc_u32 s7, s45, 0
	s_add_i32 s16, 0, 0x10000
	s_cmp_eq_u32 s36, s6
	s_cselect_b32 s7, s71, s7
	s_cselect_b32 s6, s70, s13
	v_add_u32_e32 v154, s16, v97
	s_cselect_b32 s39, s87, s9
	s_cselect_b32 s38, s86, s8
	s_add_i32 s13, 0, 0x14000
	ds_read_b128 v[130:133], v154
	ds_read_b128 v[146:149], v154 offset:1024
	ds_read_b128 v[150:153], v154 offset:2048
	ds_read_b128 v[158:161], v154 offset:3072
	v_add_u32_e32 v154, s13, v97
	ds_read_b128 v[162:165], v154
	ds_read_b128 v[166:169], v154 offset:1024
	ds_read_b128 v[170:173], v154 offset:2048
	ds_read_b128 v[174:177], v154 offset:3072
	v_lshl_add_u64 v[154:155], s[44:45], 0, v[142:143]
	s_add_i32 m0, s40, 0xc000
	ds_read_b128 v[178:181], v156
	ds_read_b128 v[182:185], v156 offset:1024
	ds_read_b128 v[186:189], v156 offset:2048
	ds_read_b128 v[190:193], v156 offset:3072
	ds_read_b128 v[194:197], v156 offset:4096
	ds_read_b128 v[198:201], v156 offset:5120
	ds_read_b128 v[202:205], v156 offset:6144
	ds_read_b128 v[206:209], v156 offset:7168
	global_load_lds_dwordx4 v[154:155], off
	v_lshl_add_u64 v[154:155], s[44:45], 0, v[144:145]
	s_add_i32 m0, s40, 0xe000
	s_nop 0
	global_load_lds_dwordx4 v[154:155], off
	s_waitcnt vmcnt(8)
	s_waitcnt lgkmcnt(0)
	s_barrier
	s_waitcnt lgkmcnt(0)
	v_mfma_f32_16x16x32_bf16 v[126:129], v[130:133], v[178:181], v[126:129]
	v_mfma_f32_16x16x32_bf16 v[122:125], v[150:153], v[178:181], v[122:125]
	v_mfma_f32_16x16x32_bf16 v[110:113], v[130:133], v[186:189], v[110:113]
	v_mfma_f32_16x16x32_bf16 v[106:109], v[150:153], v[186:189], v[106:109]
	v_mfma_f32_16x16x32_bf16 v[92:95], v[130:133], v[194:197], v[92:95]
	v_mfma_f32_16x16x32_bf16 v[88:91], v[150:153], v[194:197], v[88:91]
	v_mfma_f32_16x16x32_bf16 v[76:79], v[130:133], v[202:205], v[76:79]
	v_mfma_f32_16x16x32_bf16 v[72:75], v[150:153], v[202:205], v[72:75]
	v_mfma_f32_16x16x32_bf16 v[126:129], v[146:149], v[182:185], v[126:129]
	v_mfma_f32_16x16x32_bf16 v[122:125], v[158:161], v[182:185], v[122:125]
	v_mfma_f32_16x16x32_bf16 v[110:113], v[146:149], v[190:193], v[110:113]
	v_mfma_f32_16x16x32_bf16 v[106:109], v[158:161], v[190:193], v[106:109]
	v_mfma_f32_16x16x32_bf16 v[92:95], v[146:149], v[198:201], v[92:95]
	v_mfma_f32_16x16x32_bf16 v[88:91], v[158:161], v[198:201], v[88:91]
	v_mfma_f32_16x16x32_bf16 v[76:79], v[146:149], v[206:209], v[76:79]
	v_mfma_f32_16x16x32_bf16 v[72:75], v[158:161], v[206:209], v[72:75]
	v_mfma_f32_16x16x32_bf16 v[118:121], v[162:165], v[178:181], v[118:121]
	v_mfma_f32_16x16x32_bf16 v[114:117], v[170:173], v[178:181], v[114:117]
	v_mfma_f32_16x16x32_bf16 v[102:105], v[162:165], v[186:189], v[102:105]
	v_mfma_f32_16x16x32_bf16 v[98:101], v[170:173], v[186:189], v[98:101]
	v_mfma_f32_16x16x32_bf16 v[84:87], v[162:165], v[194:197], v[84:87]
	v_mfma_f32_16x16x32_bf16 v[80:83], v[170:173], v[194:197], v[80:83]
	v_mfma_f32_16x16x32_bf16 v[68:71], v[162:165], v[202:205], v[68:71]
	v_mfma_f32_16x16x32_bf16 v[64:67], v[170:173], v[202:205], v[64:67]
	v_mfma_f32_16x16x32_bf16 v[118:121], v[166:169], v[182:185], v[118:121]
	v_mfma_f32_16x16x32_bf16 v[114:117], v[174:177], v[182:185], v[114:117]
	v_mfma_f32_16x16x32_bf16 v[102:105], v[166:169], v[190:193], v[102:105]
	v_mfma_f32_16x16x32_bf16 v[98:101], v[174:177], v[190:193], v[98:101]
	v_mfma_f32_16x16x32_bf16 v[84:87], v[166:169], v[198:201], v[84:87]
	v_mfma_f32_16x16x32_bf16 v[80:83], v[174:177], v[198:201], v[80:83]
	v_mfma_f32_16x16x32_bf16 v[68:71], v[166:169], v[206:209], v[68:71]
	v_mfma_f32_16x16x32_bf16 v[64:67], v[174:177], v[206:209], v[64:67]
	s_barrier
	s_add_i32 s16, s16, s37
	v_lshl_add_u64 v[154:155], s[38:39], 0, v[136:137]
	s_mov_b32 m0, s16
	ds_read_b128 v[178:181], v156 offset:16384
	ds_read_b128 v[182:185], v156 offset:17408
	ds_read_b128 v[186:189], v156 offset:18432
	ds_read_b128 v[190:193], v156 offset:19456
	ds_read_b128 v[194:197], v156 offset:20480
	ds_read_b128 v[198:201], v156 offset:21504
	ds_read_b128 v[202:205], v156 offset:22528
	ds_read_b128 v[206:209], v156 offset:23552
	global_load_lds_dwordx4 v[154:155], off
	s_add_i32 m0, s16, 0x2000
	v_lshl_add_u64 v[218:219], s[38:39], 0, v[140:141]
	s_add_u32 s38, s38, s50
	s_addc_u32 s39, s39, s51
	s_add_i32 s13, s13, s37
	global_load_lds_dwordx4 v[218:219], off
	v_lshl_add_u64 v[220:221], s[38:39], 0, v[136:137]
	s_mov_b32 m0, s13
	v_lshl_add_u64 v[222:223], s[38:39], 0, v[140:141]
	global_load_lds_dwordx4 v[220:221], off
	s_add_i32 m0, s13, 0x2000
	v_lshl_add_u64 v[224:225], s[6:7], 0, v[134:135]
	global_load_lds_dwordx4 v[222:223], off
	s_mov_b32 m0, s40
	v_lshl_add_u64 v[226:227], s[6:7], 0, v[138:139]
	global_load_lds_dwordx4 v[224:225], off
	s_mov_b32 m0, s41
	s_nop 0
	global_load_lds_dwordx4 v[226:227], off
	s_waitcnt vmcnt(8)
	s_waitcnt lgkmcnt(0)
	s_barrier
; #define PG8_STAGE(bufoff, gbase, voff) do { _Pragma("unroll") for (int _i = 0; _i < 2; ++_i) \
;         __builtin_amdgcn_global_load_lds((const unsigned*)((const char*)(gbase) + (voff)[_i]), (PG8_LAS unsigned*)(lds + (bufoff) + ldsw + _i * 8192), 16, 0, 0); } while (0)
; #define PG8_LDA(dst, b, h) do { _Pragma("unroll") for (int m = 0; m < 4; ++m) _Pragma("unroll") for (int k = 0; k < 2; ++k) dst[m][k] = *(const PG8_LAS bf16x8*)(lds + PG8_SA(b, h) + aoff + m * 2048 + k * 1024); } while (0)
; #define PG8_LDB(dst, b, h) do { _Pragma("unroll") for (int n = 0; n < 2; ++n) _Pragma("unroll") for (int k = 0; k < 2; ++k) dst[n][k] = *(const PG8_LAS bf16x8*)(lds + PG8_SB(b, h) + boff + n * 2048 + k * 1024); } while (0)
; #define PG8_MMA(ai, bj, At, Bt) do { __builtin_amdgcn_s_setprio(1); _Pragma("unroll") for (int m = 0; m < 4; ++m) _Pragma("unroll") for (int n = 0; n < 2; ++n) _Pragma("unroll") for (int k = 0; k < 2; ++k) \
;         acc[ai][bj][m][n] = __builtin_amdgcn_mfma_f32_16x16x32_bf16(Bt[n][k], At[m][k], acc[ai][bj][m][n], 0, 0, 0); __builtin_amdgcn_s_setprio(0); } while (0)
; #define PG8_WAIT_V(n) asm volatile("s_waitcnt vmcnt(" #n ")" ::: "memory")
; #define PG8_WAIT_L(n) asm volatile("s_waitcnt lgkmcnt(" #n ")" ::: "memory")
; #define PG8_BAR __builtin_amdgcn_s_barrier()
; #define PG8_SCHED __builtin_amdgcn_sched_barrier(0)
; template <class Epi>
; __device__ __forceinline__ void gemm_phase(PG8_LAS unsigned char* lds, const Gemm g, const StaticOrder& S, const Epi& E, const int wave_s) {
;     ...
;             PG8_WAIT_V(8); PG8_WAIT_L(0); PG8_BAR; PG8_MMA(1, 0, At, B0); PG8_MMA(1, 1, At, B1); PG8_BAR; PG8_SCHED;
;             PG8_LDB(B0, 1, 0); PG8_LDB(B1, 1, 1); PG8_SCHED; PG8_LDA(At, 1, 0); PG8_STAGE(PG8_SA(0, 1), a2 + hstepA, voffA);
;             PG8_WAIT_V(8); PG8_WAIT_L(0); PG8_BAR; PG8_MMA(0, 0, At, B0); PG8_MMA(0, 1, At, B1); PG8_BAR; PG8_SCHED;
;             PG8_LDA(At, 1, 1); PG8_STAGE(PG8_SB(1, 0), b3, voffB); PG8_STAGE(PG8_SB(1, 1), b3 + hstepB, voffB); PG8_STAGE(PG8_SA(1, 0), a3, voffA);
;             PG8_WAIT_V(8); PG8_WAIT_L(0); PG8_BAR; PG8_MMA(1, 0, At, B0); PG8_MMA(1, 1, At, B1); PG8_BAR; PG8_SCHED;
	s_waitcnt lgkmcnt(0)
	v_mfma_f32_16x16x32_bf16 v[60:63], v[130:133], v[178:181], v[60:63]
	v_mfma_f32_16x16x32_bf16 v[56:59], v[150:153], v[178:181], v[56:59]
	v_mfma_f32_16x16x32_bf16 v[44:47], v[130:133], v[186:189], v[44:47]
	v_mfma_f32_16x16x32_bf16 v[40:43], v[150:153], v[186:189], v[40:43]
	v_mfma_f32_16x16x32_bf16 v[28:31], v[130:133], v[194:197], v[28:31]
	v_mfma_f32_16x16x32_bf16 v[24:27], v[150:153], v[194:197], v[24:27]
	v_mfma_f32_16x16x32_bf16 v[12:15], v[130:133], v[202:205], v[12:15]
	v_mfma_f32_16x16x32_bf16 v[8:11], v[150:153], v[202:205], v[8:11]
	v_mfma_f32_16x16x32_bf16 v[60:63], v[146:149], v[182:185], v[60:63]
	v_mfma_f32_16x16x32_bf16 v[56:59], v[158:161], v[182:185], v[56:59]
	v_mfma_f32_16x16x32_bf16 v[44:47], v[146:149], v[190:193], v[44:47]
	v_mfma_f32_16x16x32_bf16 v[40:43], v[158:161], v[190:193], v[40:43]
	v_mfma_f32_16x16x32_bf16 v[28:31], v[146:149], v[198:201], v[28:31]
	v_mfma_f32_16x16x32_bf16 v[24:27], v[158:161], v[198:201], v[24:27]
	v_mfma_f32_16x16x32_bf16 v[12:15], v[146:149], v[206:209], v[12:15]
	v_mfma_f32_16x16x32_bf16 v[8:11], v[158:161], v[206:209], v[8:11]
	v_mfma_f32_16x16x32_bf16 v[52:55], v[162:165], v[178:181], v[52:55]
	v_mfma_f32_16x16x32_bf16 v[48:51], v[170:173], v[178:181], v[48:51]
	v_mfma_f32_16x16x32_bf16 v[36:39], v[162:165], v[186:189], v[36:39]
	v_mfma_f32_16x16x32_bf16 v[32:35], v[170:173], v[186:189], v[32:35]
	v_mfma_f32_16x16x32_bf16 v[20:23], v[162:165], v[194:197], v[20:23]
	v_mfma_f32_16x16x32_bf16 v[16:19], v[170:173], v[194:197], v[16:19]
	v_mfma_f32_16x16x32_bf16 v[4:7], v[162:165], v[202:205], v[4:7]
	v_mfma_f32_16x16x32_bf16 v[0:3], v[170:173], v[202:205], v[0:3]
	v_mfma_f32_16x16x32_bf16 v[52:55], v[166:169], v[182:185], v[52:55]
	v_mfma_f32_16x16x32_bf16 v[48:51], v[174:177], v[182:185], v[48:51]
	v_mfma_f32_16x16x32_bf16 v[36:39], v[166:169], v[190:193], v[36:39]
	v_mfma_f32_16x16x32_bf16 v[32:35], v[174:177], v[190:193], v[32:35]
	v_mfma_f32_16x16x32_bf16 v[20:23], v[166:169], v[198:201], v[20:23]
	v_mfma_f32_16x16x32_bf16 v[16:19], v[174:177], v[198:201], v[16:19]
	v_mfma_f32_16x16x32_bf16 v[4:7], v[166:169], v[206:209], v[4:7]
	v_mfma_f32_16x16x32_bf16 v[0:3], v[174:177], v[206:209], v[0:3]
	s_barrier
	s_add_i32 s13, 0, 0x18000
	v_add_u32_e32 v157, s13, v97
	s_add_i32 s16, 0, 0x1c000
	ds_read_b128 v[130:133], v157
	ds_read_b128 v[146:149], v157 offset:1024
	ds_read_b128 v[150:153], v157 offset:2048
	ds_read_b128 v[158:161], v157 offset:3072
	v_add_u32_e32 v157, s16, v97
	ds_read_b128 v[162:165], v157
	ds_read_b128 v[166:169], v157 offset:1024
	ds_read_b128 v[170:173], v157 offset:2048
	ds_read_b128 v[174:177], v157 offset:3072
	s_add_u32 s6, s6, s48
	s_addc_u32 s7, s7, s49
	s_mov_b32 m0, s92
	v_lshl_add_u64 v[228:229], s[6:7], 0, v[134:135]
	ds_read_b128 v[178:181], v156 offset:32768
	ds_read_b128 v[182:185], v156 offset:33792
	ds_read_b128 v[186:189], v156 offset:34816
	ds_read_b128 v[190:193], v156 offset:35840
	ds_read_b128 v[194:197], v156 offset:36864
	ds_read_b128 v[198:201], v156 offset:37888
	ds_read_b128 v[202:205], v156 offset:38912
	ds_read_b128 v[206:209], v156 offset:39936
	global_load_lds_dwordx4 v[228:229], off
	v_lshl_add_u64 v[228:229], s[6:7], 0, v[138:139]
	s_mov_b32 m0, s93
	s_nop 0
	global_load_lds_dwordx4 v[228:229], off
	s_waitcnt vmcnt(8)
	s_waitcnt lgkmcnt(0)
	s_barrier
	s_waitcnt lgkmcnt(0)
	v_mfma_f32_16x16x32_bf16 v[126:129], v[130:133], v[178:181], v[126:129]
	v_mfma_f32_16x16x32_bf16 v[122:125], v[150:153], v[178:181], v[122:125]
	v_mfma_f32_16x16x32_bf16 v[110:113], v[130:133], v[186:189], v[110:113]
	v_mfma_f32_16x16x32_bf16 v[106:109], v[150:153], v[186:189], v[106:109]
	v_mfma_f32_16x16x32_bf16 v[92:95], v[130:133], v[194:197], v[92:95]
	v_mfma_f32_16x16x32_bf16 v[88:91], v[150:153], v[194:197], v[88:91]
	v_mfma_f32_16x16x32_bf16 v[76:79], v[130:133], v[202:205], v[76:79]
	v_mfma_f32_16x16x32_bf16 v[72:75], v[150:153], v[202:205], v[72:75]
	v_mfma_f32_16x16x32_bf16 v[126:129], v[146:149], v[182:185], v[126:129]
	v_mfma_f32_16x16x32_bf16 v[122:125], v[158:161], v[182:185], v[122:125]
	v_mfma_f32_16x16x32_bf16 v[110:113], v[146:149], v[190:193], v[110:113]
	v_mfma_f32_16x16x32_bf16 v[106:109], v[158:161], v[190:193], v[106:109]
	v_mfma_f32_16x16x32_bf16 v[92:95], v[146:149], v[198:201], v[92:95]
	v_mfma_f32_16x16x32_bf16 v[88:91], v[158:161], v[198:201], v[88:91]
	v_mfma_f32_16x16x32_bf16 v[76:79], v[146:149], v[206:209], v[76:79]
	v_mfma_f32_16x16x32_bf16 v[72:75], v[158:161], v[206:209], v[72:75]
	v_mfma_f32_16x16x32_bf16 v[118:121], v[162:165], v[178:181], v[118:121]
	v_mfma_f32_16x16x32_bf16 v[114:117], v[170:173], v[178:181], v[114:117]
	v_mfma_f32_16x16x32_bf16 v[102:105], v[162:165], v[186:189], v[102:105]
	v_mfma_f32_16x16x32_bf16 v[98:101], v[170:173], v[186:189], v[98:101]
	v_mfma_f32_16x16x32_bf16 v[84:87], v[162:165], v[194:197], v[84:87]
	v_mfma_f32_16x16x32_bf16 v[80:83], v[170:173], v[194:197], v[80:83]
	v_mfma_f32_16x16x32_bf16 v[68:71], v[162:165], v[202:205], v[68:71]
	v_mfma_f32_16x16x32_bf16 v[64:67], v[170:173], v[202:205], v[64:67]
	v_mfma_f32_16x16x32_bf16 v[118:121], v[166:169], v[182:185], v[118:121]
	v_mfma_f32_16x16x32_bf16 v[114:117], v[174:177], v[182:185], v[114:117]
	v_mfma_f32_16x16x32_bf16 v[102:105], v[166:169], v[190:193], v[102:105]
	v_mfma_f32_16x16x32_bf16 v[98:101], v[174:177], v[190:193], v[98:101]
	v_mfma_f32_16x16x32_bf16 v[84:87], v[166:169], v[198:201], v[84:87]
	v_mfma_f32_16x16x32_bf16 v[80:83], v[174:177], v[198:201], v[80:83]
	v_mfma_f32_16x16x32_bf16 v[68:71], v[166:169], v[206:209], v[68:71]
	v_mfma_f32_16x16x32_bf16 v[64:67], v[174:177], v[206:209], v[64:67]
	s_barrier
; #define PG8_STAGE(bufoff, gbase, voff) do { _Pragma("unroll") for (int _i = 0; _i < 2; ++_i) \
;         __builtin_amdgcn_global_load_lds((const unsigned*)((const char*)(gbase) + (voff)[_i]), (PG8_LAS unsigned*)(lds + (bufoff) + ldsw + _i * 8192), 16, 0, 0); } while (0)
; #define PG8_LDA(dst, b, h) do { _Pragma("unroll") for (int m = 0; m < 4; ++m) _Pragma("unroll") for (int k = 0; k < 2; ++k) dst[m][k] = *(const PG8_LAS bf16x8*)(lds + PG8_SA(b, h) + aoff + m * 2048 + k * 1024); } while (0)
; #define PG8_MMA(ai, bj, At, Bt) do { __builtin_amdgcn_s_setprio(1); _Pragma("unroll") for (int m = 0; m < 4; ++m) _Pragma("unroll") for (int n = 0; n < 2; ++n) _Pragma("unroll") for (int k = 0; k < 2; ++k) \
;         acc[ai][bj][m][n] = __builtin_amdgcn_mfma_f32_16x16x32_bf16(Bt[n][k], At[m][k], acc[ai][bj][m][n], 0, 0, 0); __builtin_amdgcn_s_setprio(0); } while (0)
; #define PG8_WAIT_V(n) asm volatile("s_waitcnt vmcnt(" #n ")" ::: "memory")
; #define PG8_WAIT_L(n) asm volatile("s_waitcnt lgkmcnt(" #n ")" ::: "memory")
; #define PG8_BAR __builtin_amdgcn_s_barrier()
; #define PG8_SCHED __builtin_amdgcn_sched_barrier(0)
; template <class Epi>
; __device__ __forceinline__ void gemm_phase(PG8_LAS unsigned char* lds, const Gemm g, const StaticOrder& S, const Epi& E, const int wave_s) {
;     ...
;             PG8_LDA(At, 1, 1); PG8_STAGE(PG8_SB(1, 0), b3, voffB); PG8_STAGE(PG8_SB(1, 1), b3 + hstepB, voffB); PG8_STAGE(PG8_SA(1, 0), a3, voffA);
;             PG8_WAIT_V(8); PG8_WAIT_L(0); PG8_BAR; PG8_MMA(1, 0, At, B0); PG8_MMA(1, 1, At, B1); PG8_BAR; PG8_SCHED;
;         }
	s_add_i32 s6, s13, s37
	v_lshl_add_u64 v[154:155], v[154:155], 0, s[52:53]
	s_mov_b32 m0, s6
	ds_read_b128 v[178:181], v156 offset:49152
	ds_read_b128 v[182:185], v156 offset:50176
	ds_read_b128 v[186:189], v156 offset:51200
	ds_read_b128 v[190:193], v156 offset:52224
	ds_read_b128 v[194:197], v156 offset:53248
	ds_read_b128 v[198:201], v156 offset:54272
	ds_read_b128 v[202:205], v156 offset:55296
	ds_read_b128 v[206:209], v156 offset:56320
	global_load_lds_dwordx4 v[154:155], off
	v_lshl_add_u64 v[154:155], v[218:219], 0, s[52:53]
	s_add_i32 m0, s6, 0x2000
	s_add_i32 s6, s16, s37
	global_load_lds_dwordx4 v[154:155], off
	v_lshl_add_u64 v[154:155], v[220:221], 0, s[52:53]
	s_mov_b32 m0, s6
	s_nop 0
	global_load_lds_dwordx4 v[154:155], off
	v_lshl_add_u64 v[154:155], v[222:223], 0, s[52:53]
	s_add_i32 m0, s6, 0x2000
	s_nop 0
	global_load_lds_dwordx4 v[154:155], off
	v_lshl_add_u64 v[154:155], v[224:225], 0, s[52:53]
	s_mov_b32 m0, s64
	s_nop 0
	global_load_lds_dwordx4 v[154:155], off
	v_lshl_add_u64 v[154:155], v[226:227], 0, s[52:53]
	s_mov_b32 m0, s65
	s_nop 0
	global_load_lds_dwordx4 v[154:155], off
	s_waitcnt vmcnt(8)
	s_waitcnt lgkmcnt(0)
	s_barrier
	s_waitcnt lgkmcnt(0)
	v_mfma_f32_16x16x32_bf16 v[60:63], v[130:133], v[178:181], v[60:63]
	v_mfma_f32_16x16x32_bf16 v[56:59], v[150:153], v[178:181], v[56:59]
	v_mfma_f32_16x16x32_bf16 v[44:47], v[130:133], v[186:189], v[44:47]
	v_mfma_f32_16x16x32_bf16 v[40:43], v[150:153], v[186:189], v[40:43]
	v_mfma_f32_16x16x32_bf16 v[28:31], v[130:133], v[194:197], v[28:31]
	v_mfma_f32_16x16x32_bf16 v[24:27], v[150:153], v[194:197], v[24:27]
	v_mfma_f32_16x16x32_bf16 v[12:15], v[130:133], v[202:205], v[12:15]
	v_mfma_f32_16x16x32_bf16 v[8:11], v[150:153], v[202:205], v[8:11]
	v_mfma_f32_16x16x32_bf16 v[60:63], v[146:149], v[182:185], v[60:63]
	v_mfma_f32_16x16x32_bf16 v[56:59], v[158:161], v[182:185], v[56:59]
	v_mfma_f32_16x16x32_bf16 v[44:47], v[146:149], v[190:193], v[44:47]
	v_mfma_f32_16x16x32_bf16 v[40:43], v[158:161], v[190:193], v[40:43]
	v_mfma_f32_16x16x32_bf16 v[28:31], v[146:149], v[198:201], v[28:31]
	v_mfma_f32_16x16x32_bf16 v[24:27], v[158:161], v[198:201], v[24:27]
	v_mfma_f32_16x16x32_bf16 v[12:15], v[146:149], v[206:209], v[12:15]
	v_mfma_f32_16x16x32_bf16 v[8:11], v[158:161], v[206:209], v[8:11]
	v_mfma_f32_16x16x32_bf16 v[52:55], v[162:165], v[178:181], v[52:55]
	v_mfma_f32_16x16x32_bf16 v[48:51], v[170:173], v[178:181], v[48:51]
	v_mfma_f32_16x16x32_bf16 v[36:39], v[162:165], v[186:189], v[36:39]
	v_mfma_f32_16x16x32_bf16 v[32:35], v[170:173], v[186:189], v[32:35]
	v_mfma_f32_16x16x32_bf16 v[20:23], v[162:165], v[194:197], v[20:23]
	v_mfma_f32_16x16x32_bf16 v[16:19], v[170:173], v[194:197], v[16:19]
	v_mfma_f32_16x16x32_bf16 v[4:7], v[162:165], v[202:205], v[4:7]
	v_mfma_f32_16x16x32_bf16 v[0:3], v[170:173], v[202:205], v[0:3]
	v_mfma_f32_16x16x32_bf16 v[52:55], v[166:169], v[182:185], v[52:55]
	v_mfma_f32_16x16x32_bf16 v[48:51], v[174:177], v[182:185], v[48:51]
	v_mfma_f32_16x16x32_bf16 v[36:39], v[166:169], v[190:193], v[36:39]
	v_mfma_f32_16x16x32_bf16 v[32:35], v[174:177], v[190:193], v[32:35]
	v_mfma_f32_16x16x32_bf16 v[20:23], v[166:169], v[198:201], v[20:23]
	v_mfma_f32_16x16x32_bf16 v[16:19], v[174:177], v[198:201], v[16:19]
	v_mfma_f32_16x16x32_bf16 v[4:7], v[166:169], v[206:209], v[4:7]
	v_mfma_f32_16x16x32_bf16 v[0:3], v[174:177], v[206:209], v[0:3]
	s_barrier
	s_add_u32 s44, s44, 0x100
	s_addc_u32 s45, s45, 0
	s_add_u32 s8, s8, 0x100
	s_addc_u32 s9, s9, 0
	s_cmp_ge_i32 s12, s4
	s_mov_b32 s6, s12
	s_cbranch_scc0 .LBB0_459
	s_setprio 0
	v_readlane_b32 s38, v255, 5
	v_readlane_b32 s39, v255, 6

; template <class Epi>
; __device__ __forceinline__ void gemm_phase(PG8_LAS unsigned char* lds, const Gemm g, const StaticOrder& S, const Epi& E, const int wave_s) {
;     ...
;         for (int t = 0; t < nt; t += 2) {
;             const bool last = (t == nt - 2);
;             const char* a1 = cA + (size_t)(t + 1) * kstep;
;             const char* a2 = last ? nA : cA + (size_t)(t + 2) * kstep; const char* b2 = last ? nB : cB + (size_t)(t + 2) * kstep;
;     ...
;         for (int a = 0; a < 2; ++a)
; #pragma unroll
;             for (int b = 0; b < 2; ++b)
; #pragma unroll
;                 for (int m = 0; m < 4; ++m)
; #pragma unroll
;                     for (int n = 0; n < 2; ++n) acc[a][b][m][n] = (f32x4){0.f, 0.f, 0.f, 0.f};
.LBB0_649:
	v_mov_b32_e32 v133, 0
	s_andn2_b64 vcc, exec, s[68:69]
	v_mov_b32_e32 v132, v133
	v_mov_b32_e32 v131, v133
	v_mov_b32_e32 v130, v133
	v_mov_b32_e32 v129, v133
	v_mov_b32_e32 v128, v133
	v_mov_b32_e32 v127, v133
	v_mov_b32_e32 v126, v133
	v_mov_b32_e32 v117, v133
	v_mov_b32_e32 v116, v133
	v_mov_b32_e32 v115, v133
	v_mov_b32_e32 v114, v133
	v_mov_b32_e32 v113, v133
	v_mov_b32_e32 v112, v133
	v_mov_b32_e32 v111, v133
	v_mov_b32_e32 v110, v133
	v_mov_b32_e32 v101, v133
	v_mov_b32_e32 v100, v133
	v_mov_b32_e32 v99, v133
	v_mov_b32_e32 v98, v133
	v_mov_b32_e32 v95, v133
	v_mov_b32_e32 v94, v133
	v_mov_b32_e32 v93, v133
	v_mov_b32_e32 v92, v133
	v_mov_b32_e32 v83, v133
	v_mov_b32_e32 v82, v133
	v_mov_b32_e32 v81, v133
	v_mov_b32_e32 v80, v133
	v_mov_b32_e32 v79, v133
	v_mov_b32_e32 v78, v133
	v_mov_b32_e32 v77, v133
	v_mov_b32_e32 v76, v133
	v_mov_b32_e32 v125, v133
	v_mov_b32_e32 v124, v133
	v_mov_b32_e32 v123, v133
	v_mov_b32_e32 v122, v133
	v_mov_b32_e32 v121, v133
	v_mov_b32_e32 v120, v133
	v_mov_b32_e32 v119, v133
	v_mov_b32_e32 v118, v133
	v_mov_b32_e32 v109, v133
	v_mov_b32_e32 v108, v133
	v_mov_b32_e32 v107, v133
	v_mov_b32_e32 v106, v133
	v_mov_b32_e32 v105, v133
	v_mov_b32_e32 v104, v133
	v_mov_b32_e32 v103, v133
	v_mov_b32_e32 v102, v133
	v_mov_b32_e32 v91, v133
	v_mov_b32_e32 v90, v133
	v_mov_b32_e32 v89, v133
	v_mov_b32_e32 v88, v133
	v_mov_b32_e32 v87, v133
	v_mov_b32_e32 v86, v133
	v_mov_b32_e32 v85, v133
	v_mov_b32_e32 v84, v133
	v_mov_b32_e32 v75, v133
	v_mov_b32_e32 v74, v133
	v_mov_b32_e32 v73, v133
	v_mov_b32_e32 v72, v133
	v_mov_b32_e32 v71, v133
	v_mov_b32_e32 v70, v133
	v_mov_b32_e32 v69, v133
	v_mov_b32_e32 v68, v133
	v_mov_b32_e32 v67, v133
	v_mov_b32_e32 v66, v133
	v_mov_b32_e32 v65, v133
	v_mov_b32_e32 v64, v133
	v_mov_b32_e32 v63, v133
	v_mov_b32_e32 v62, v133
	v_mov_b32_e32 v61, v133
	v_mov_b32_e32 v60, v133
	v_mov_b32_e32 v51, v133
	v_mov_b32_e32 v50, v133
	v_mov_b32_e32 v49, v133
	v_mov_b32_e32 v48, v133
	v_mov_b32_e32 v47, v133
	v_mov_b32_e32 v46, v133
	v_mov_b32_e32 v45, v133
	v_mov_b32_e32 v44, v133
	v_mov_b32_e32 v35, v133
	v_mov_b32_e32 v34, v133
	v_mov_b32_e32 v33, v133
	v_mov_b32_e32 v32, v133
	v_mov_b32_e32 v31, v133
	v_mov_b32_e32 v30, v133
	v_mov_b32_e32 v29, v133
	v_mov_b32_e32 v28, v133
	v_mov_b32_e32 v19, v133
	v_mov_b32_e32 v18, v133
	v_mov_b32_e32 v17, v133
	v_mov_b32_e32 v16, v133
	v_mov_b32_e32 v15, v133
	v_mov_b32_e32 v14, v133
	v_mov_b32_e32 v13, v133
	v_mov_b32_e32 v12, v133
	v_mov_b32_e32 v59, v133
	v_mov_b32_e32 v58, v133
	v_mov_b32_e32 v57, v133
	v_mov_b32_e32 v56, v133
	v_mov_b32_e32 v55, v133
	v_mov_b32_e32 v54, v133
	v_mov_b32_e32 v53, v133
	v_mov_b32_e32 v52, v133
	v_mov_b32_e32 v43, v133
	v_mov_b32_e32 v42, v133
	v_mov_b32_e32 v41, v133
	v_mov_b32_e32 v40, v133
	v_mov_b32_e32 v39, v133
	v_mov_b32_e32 v38, v133
	v_mov_b32_e32 v37, v133
	v_mov_b32_e32 v36, v133
	v_mov_b32_e32 v27, v133
	v_mov_b32_e32 v26, v133
	v_mov_b32_e32 v25, v133
	v_mov_b32_e32 v24, v133
	v_mov_b32_e32 v23, v133
	v_mov_b32_e32 v22, v133
	v_mov_b32_e32 v21, v133
	v_mov_b32_e32 v20, v133
	v_mov_b32_e32 v11, v133
	v_mov_b32_e32 v10, v133
	v_mov_b32_e32 v9, v133
	v_mov_b32_e32 v8, v133
	v_mov_b32_e32 v7, v133
	v_mov_b32_e32 v6, v133
	v_mov_b32_e32 v5, v133
	v_mov_b32_e32 v4, v133
	s_cbranch_vccnz .LBB0_652
	s_add_u32 s44, s48, 0x80
	s_addc_u32 s45, s49, 0
	s_add_u32 s46, s46, 0x100
	v_mov_b32_e32 v4, 0
	s_addc_u32 s47, s47, 0
	s_mov_b32 s6, 0
	v_mov_b32_e32 v5, v4
	v_mov_b32_e32 v6, v4
	v_mov_b32_e32 v7, v4
	v_mov_b32_e32 v8, v4
	v_mov_b32_e32 v9, v4
	v_mov_b32_e32 v10, v4
	v_mov_b32_e32 v11, v4
	v_mov_b32_e32 v20, v4
	v_mov_b32_e32 v21, v4
	v_mov_b32_e32 v22, v4
	v_mov_b32_e32 v23, v4
	v_mov_b32_e32 v24, v4
	v_mov_b32_e32 v25, v4
	v_mov_b32_e32 v26, v4
	v_mov_b32_e32 v27, v4
	v_mov_b32_e32 v36, v4
	v_mov_b32_e32 v37, v4
	v_mov_b32_e32 v38, v4
	v_mov_b32_e32 v39, v4
	v_mov_b32_e32 v40, v4
	v_mov_b32_e32 v41, v4
	v_mov_b32_e32 v42, v4
	v_mov_b32_e32 v43, v4
	v_mov_b32_e32 v52, v4
	v_mov_b32_e32 v53, v4
	v_mov_b32_e32 v54, v4
	v_mov_b32_e32 v55, v4
	v_mov_b32_e32 v56, v4
	v_mov_b32_e32 v57, v4
	v_mov_b32_e32 v58, v4
	v_mov_b32_e32 v59, v4
	v_mov_b32_e32 v12, v4
	v_mov_b32_e32 v13, v4
	v_mov_b32_e32 v14, v4
	v_mov_b32_e32 v15, v4
	v_mov_b32_e32 v16, v4
	v_mov_b32_e32 v17, v4
	v_mov_b32_e32 v18, v4
	v_mov_b32_e32 v19, v4
	v_mov_b32_e32 v28, v4
	v_mov_b32_e32 v29, v4
	v_mov_b32_e32 v30, v4
	v_mov_b32_e32 v31, v4
	v_mov_b32_e32 v32, v4
	v_mov_b32_e32 v33, v4
	v_mov_b32_e32 v34, v4
	v_mov_b32_e32 v35, v4
	v_mov_b32_e32 v44, v4
	v_mov_b32_e32 v45, v4
	v_mov_b32_e32 v46, v4
	v_mov_b32_e32 v47, v4
	v_mov_b32_e32 v48, v4
	v_mov_b32_e32 v49, v4
	v_mov_b32_e32 v50, v4
	v_mov_b32_e32 v51, v4
	v_mov_b32_e32 v60, v4
	v_mov_b32_e32 v61, v4
	v_mov_b32_e32 v62, v4
	v_mov_b32_e32 v63, v4
	v_mov_b32_e32 v64, v4
	v_mov_b32_e32 v65, v4
	v_mov_b32_e32 v66, v4
	v_mov_b32_e32 v67, v4
	v_mov_b32_e32 v68, v4
	v_mov_b32_e32 v69, v4
	v_mov_b32_e32 v70, v4
	v_mov_b32_e32 v71, v4
	v_mov_b32_e32 v72, v4
	v_mov_b32_e32 v73, v4
	v_mov_b32_e32 v74, v4
	v_mov_b32_e32 v75, v4
	v_mov_b32_e32 v84, v4
	v_mov_b32_e32 v85, v4
	v_mov_b32_e32 v86, v4
	v_mov_b32_e32 v87, v4
	v_mov_b32_e32 v88, v4
	v_mov_b32_e32 v89, v4
	v_mov_b32_e32 v90, v4
	v_mov_b32_e32 v91, v4
	v_mov_b32_e32 v102, v4
	v_mov_b32_e32 v103, v4
	v_mov_b32_e32 v104, v4
	v_mov_b32_e32 v105, v4
	v_mov_b32_e32 v106, v4
	v_mov_b32_e32 v107, v4
	v_mov_b32_e32 v108, v4
	v_mov_b32_e32 v109, v4
	v_mov_b32_e32 v118, v4
	v_mov_b32_e32 v119, v4
	v_mov_b32_e32 v120, v4
	v_mov_b32_e32 v121, v4
	v_mov_b32_e32 v122, v4
	v_mov_b32_e32 v123, v4
	v_mov_b32_e32 v124, v4
	v_mov_b32_e32 v125, v4
	v_mov_b32_e32 v76, v4
	v_mov_b32_e32 v77, v4
	v_mov_b32_e32 v78, v4
	v_mov_b32_e32 v79, v4
	v_mov_b32_e32 v80, v4
	v_mov_b32_e32 v81, v4
	v_mov_b32_e32 v82, v4
	v_mov_b32_e32 v83, v4
	v_mov_b32_e32 v92, v4
	v_mov_b32_e32 v93, v4
	v_mov_b32_e32 v94, v4
	v_mov_b32_e32 v95, v4
	v_mov_b32_e32 v98, v4
	v_mov_b32_e32 v99, v4
	v_mov_b32_e32 v100, v4
	v_mov_b32_e32 v101, v4
	v_mov_b32_e32 v110, v4
	v_mov_b32_e32 v111, v4
	v_mov_b32_e32 v112, v4
	v_mov_b32_e32 v113, v4
	v_mov_b32_e32 v114, v4
	v_mov_b32_e32 v115, v4
	v_mov_b32_e32 v116, v4
	v_mov_b32_e32 v117, v4
	v_mov_b32_e32 v126, v4
	v_mov_b32_e32 v127, v4
	v_mov_b32_e32 v128, v4
	v_mov_b32_e32 v129, v4
	v_mov_b32_e32 v130, v4
	v_mov_b32_e32 v131, v4
	v_mov_b32_e32 v132, v4
	v_mov_b32_e32 v133, v4
	v_readlane_b32 s7, v254, 61
	s_nop 3
	s_cmp_lt_u32 s7, 0x100
	s_cbranch_scc1 .Lg3_prio_done
	s_setprio 1
; #define PG8_STAGE(bufoff, gbase, voff) do { _Pragma("unroll") for (int _i = 0; _i < 2; ++_i) \
;         __builtin_amdgcn_global_load_lds((const unsigned*)((const char*)(gbase) + (voff)[_i]), (PG8_LAS unsigned*)(lds + (bufoff) + ldsw + _i * 8192), 16, 0, 0); } while (0)
; #define PG8_LDA(dst, b, h) do { _Pragma("unroll") for (int m = 0; m < 4; ++m) _Pragma("unroll") for (int k = 0; k < 2; ++k) dst[m][k] = *(const PG8_LAS bf16x8*)(lds + PG8_SA(b, h) + aoff + m * 2048 + k * 1024); } while (0)
; #define PG8_LDB(dst, b, h) do { _Pragma("unroll") for (int n = 0; n < 2; ++n) _Pragma("unroll") for (int k = 0; k < 2; ++k) dst[n][k] = *(const PG8_LAS bf16x8*)(lds + PG8_SB(b, h) + boff + n * 2048 + k * 1024); } while (0)
; #define PG8_MMA(ai, bj, At, Bt) do { __builtin_amdgcn_s_setprio(1); _Pragma("unroll") for (int m = 0; m < 4; ++m) _Pragma("unroll") for (int n = 0; n < 2; ++n) _Pragma("unroll") for (int k = 0; k < 2; ++k) \
;         acc[ai][bj][m][n] = __builtin_amdgcn_mfma_f32_16x16x32_bf16(Bt[n][k], At[m][k], acc[ai][bj][m][n], 0, 0, 0); __builtin_amdgcn_s_setprio(0); } while (0)
; #define PG8_WAIT_V(n) asm volatile("s_waitcnt vmcnt(" #n ")" ::: "memory")
; #define PG8_WAIT_L(n) asm volatile("s_waitcnt lgkmcnt(" #n ")" ::: "memory")
; #define PG8_BAR __builtin_amdgcn_s_barrier()
; #define PG8_SCHED __builtin_amdgcn_sched_barrier(0)
; template <class Epi>
; __device__ __forceinline__ void gemm_phase(PG8_LAS unsigned char* lds, const Gemm g, const StaticOrder& S, const Epi& E, const int wave_s) {
;     ...
;         for (int t = 0; t < nt; t += 2) {
;             const bool last = (t == nt - 2);
;             const char* a1 = cA + (size_t)(t + 1) * kstep;
;             const char* a2 = last ? nA : cA + (size_t)(t + 2) * kstep; const char* b2 = last ? nB : cB + (size_t)(t + 2) * kstep;
;             const char* a3 = a2 + kstep; const char* b3 = b2 + kstep;
;             PG8_LDB(B0, 0, 0); PG8_LDB(B1, 0, 1); PG8_SCHED; PG8_LDA(At, 0, 0); PG8_STAGE(PG8_SA(1, 1), a1 + hstepA, voffA);
;             PG8_WAIT_V(8); PG8_WAIT_L(0); PG8_BAR; PG8_MMA(0, 0, At, B0); PG8_MMA(0, 1, At, B1); PG8_BAR; PG8_SCHED;
;             PG8_LDA(At, 0, 1); PG8_STAGE(PG8_SB(0, 0), b2, voffB); PG8_STAGE(PG8_SB(0, 1), b2 + hstepB, voffB); PG8_STAGE(PG8_SA(0, 0), a2, voffA);
;             PG8_WAIT_V(8); PG8_WAIT_L(0); PG8_BAR; PG8_MMA(1, 0, At, B0); PG8_MMA(1, 1, At, B1); PG8_BAR; PG8_SCHED;
.Lg3_prio_done:
.LBB0_651:
	s_add_i32 s48, s6, 2
	s_add_u32 s49, s44, 0x80
	s_addc_u32 s7, s45, 0
	s_add_i32 s72, 0, 0x10000
	s_cmp_eq_u32 s37, s6
	s_cselect_b32 s7, s87, s7
	s_cselect_b32 s6, s86, s49
	v_add_u32_e32 v97, s72, v159
	s_cselect_b32 s51, s89, s47
	s_cselect_b32 s50, s88, s46
	s_add_i32 s49, 0, 0x14000
	ds_read_b128 v[150:153], v97
	ds_read_b128 v[154:157], v97 offset:1024
	ds_read_b128 v[162:165], v97 offset:2048
	ds_read_b128 v[166:169], v97 offset:3072
	v_add_u32_e32 v97, s49, v159
	ds_read_b128 v[170:173], v97
	ds_read_b128 v[174:177], v97 offset:1024
	ds_read_b128 v[178:181], v97 offset:2048
	ds_read_b128 v[182:185], v97 offset:3072
	v_lshl_add_u64 v[226:227], s[44:45], 0, v[140:141]
	s_add_i32 m0, s8, 0xc000
	ds_read_b128 v[186:189], v160
	ds_read_b128 v[190:193], v160 offset:1024
	ds_read_b128 v[194:197], v160 offset:2048
	ds_read_b128 v[198:201], v160 offset:3072
	ds_read_b128 v[202:205], v160 offset:4096
	ds_read_b128 v[206:209], v160 offset:5120
	ds_read_b128 v[218:221], v160 offset:6144
	ds_read_b128 v[222:225], v160 offset:7168
	global_load_lds_dwordx4 v[226:227], off
	v_lshl_add_u64 v[226:227], s[44:45], 0, v[142:143]
	s_add_i32 m0, s8, 0xe000
	s_nop 0
	global_load_lds_dwordx4 v[226:227], off
	s_waitcnt vmcnt(8)
	s_waitcnt lgkmcnt(0)
	s_barrier
	s_waitcnt lgkmcnt(0)
	v_mfma_f32_16x16x32_bf16 v[130:133], v[150:153], v[186:189], v[130:133]
	v_mfma_f32_16x16x32_bf16 v[126:129], v[162:165], v[186:189], v[126:129]
	v_mfma_f32_16x16x32_bf16 v[114:117], v[150:153], v[194:197], v[114:117]
	v_mfma_f32_16x16x32_bf16 v[110:113], v[162:165], v[194:197], v[110:113]
	v_mfma_f32_16x16x32_bf16 v[98:101], v[150:153], v[202:205], v[98:101]
	v_mfma_f32_16x16x32_bf16 v[92:95], v[162:165], v[202:205], v[92:95]
	v_mfma_f32_16x16x32_bf16 v[80:83], v[150:153], v[218:221], v[80:83]
	v_mfma_f32_16x16x32_bf16 v[76:79], v[162:165], v[218:221], v[76:79]
	v_mfma_f32_16x16x32_bf16 v[130:133], v[154:157], v[190:193], v[130:133]
	v_mfma_f32_16x16x32_bf16 v[126:129], v[166:169], v[190:193], v[126:129]
	v_mfma_f32_16x16x32_bf16 v[114:117], v[154:157], v[198:201], v[114:117]
	v_mfma_f32_16x16x32_bf16 v[110:113], v[166:169], v[198:201], v[110:113]
	v_mfma_f32_16x16x32_bf16 v[98:101], v[154:157], v[206:209], v[98:101]
	v_mfma_f32_16x16x32_bf16 v[92:95], v[166:169], v[206:209], v[92:95]
	v_mfma_f32_16x16x32_bf16 v[80:83], v[154:157], v[222:225], v[80:83]
	v_mfma_f32_16x16x32_bf16 v[76:79], v[166:169], v[222:225], v[76:79]
	v_mfma_f32_16x16x32_bf16 v[122:125], v[170:173], v[186:189], v[122:125]
	v_mfma_f32_16x16x32_bf16 v[118:121], v[178:181], v[186:189], v[118:121]
	v_mfma_f32_16x16x32_bf16 v[106:109], v[170:173], v[194:197], v[106:109]
	v_mfma_f32_16x16x32_bf16 v[102:105], v[178:181], v[194:197], v[102:105]
	v_mfma_f32_16x16x32_bf16 v[88:91], v[170:173], v[202:205], v[88:91]
	v_mfma_f32_16x16x32_bf16 v[84:87], v[178:181], v[202:205], v[84:87]
	v_mfma_f32_16x16x32_bf16 v[72:75], v[170:173], v[218:221], v[72:75]
	v_mfma_f32_16x16x32_bf16 v[68:71], v[178:181], v[218:221], v[68:71]
	v_mfma_f32_16x16x32_bf16 v[122:125], v[174:177], v[190:193], v[122:125]
	v_mfma_f32_16x16x32_bf16 v[118:121], v[182:185], v[190:193], v[118:121]
	v_mfma_f32_16x16x32_bf16 v[106:109], v[174:177], v[198:201], v[106:109]
	v_mfma_f32_16x16x32_bf16 v[102:105], v[182:185], v[198:201], v[102:105]
	v_mfma_f32_16x16x32_bf16 v[88:91], v[174:177], v[206:209], v[88:91]
	v_mfma_f32_16x16x32_bf16 v[84:87], v[182:185], v[206:209], v[84:87]
	v_mfma_f32_16x16x32_bf16 v[72:75], v[174:177], v[222:225], v[72:75]
	v_mfma_f32_16x16x32_bf16 v[68:71], v[182:185], v[222:225], v[68:71]
	s_barrier
	s_add_i32 s72, s72, s5
	v_lshl_add_u64 v[226:227], s[50:51], 0, v[210:211]
	s_mov_b32 m0, s72
	ds_read_b128 v[186:189], v160 offset:16384
	ds_read_b128 v[190:193], v160 offset:17408
	ds_read_b128 v[194:197], v160 offset:18432
	ds_read_b128 v[198:201], v160 offset:19456
	ds_read_b128 v[202:205], v160 offset:20480
	ds_read_b128 v[206:209], v160 offset:21504
	ds_read_b128 v[218:221], v160 offset:22528
	ds_read_b128 v[222:225], v160 offset:23552
	global_load_lds_dwordx4 v[226:227], off
	s_add_i32 m0, s72, 0x2000
	v_lshl_add_u64 v[228:229], s[50:51], 0, v[138:139]
	s_add_u32 s50, s50, s60
	s_addc_u32 s51, s51, s61
	s_add_i32 s49, s49, s5
	global_load_lds_dwordx4 v[228:229], off
	v_lshl_add_u64 v[230:231], s[50:51], 0, v[210:211]
	s_mov_b32 m0, s49
	v_lshl_add_u64 v[232:233], s[50:51], 0, v[138:139]
	global_load_lds_dwordx4 v[230:231], off
	s_add_i32 m0, s49, 0x2000
	v_lshl_add_u64 v[242:243], s[6:7], 0, v[134:135]
	global_load_lds_dwordx4 v[232:233], off
	s_mov_b32 m0, s8
	v_lshl_add_u64 v[244:245], s[6:7], 0, v[136:137]
	global_load_lds_dwordx4 v[242:243], off
	s_mov_b32 m0, s9
	s_nop 0
	global_load_lds_dwordx4 v[244:245], off
	s_waitcnt vmcnt(8)
	s_waitcnt lgkmcnt(0)
	s_barrier
; #define PG8_STAGE(bufoff, gbase, voff) do { _Pragma("unroll") for (int _i = 0; _i < 2; ++_i) \
;         __builtin_amdgcn_global_load_lds((const unsigned*)((const char*)(gbase) + (voff)[_i]), (PG8_LAS unsigned*)(lds + (bufoff) + ldsw + _i * 8192), 16, 0, 0); } while (0)
; #define PG8_LDA(dst, b, h) do { _Pragma("unroll") for (int m = 0; m < 4; ++m) _Pragma("unroll") for (int k = 0; k < 2; ++k) dst[m][k] = *(const PG8_LAS bf16x8*)(lds + PG8_SA(b, h) + aoff + m * 2048 + k * 1024); } while (0)
; #define PG8_LDB(dst, b, h) do { _Pragma("unroll") for (int n = 0; n < 2; ++n) _Pragma("unroll") for (int k = 0; k < 2; ++k) dst[n][k] = *(const PG8_LAS bf16x8*)(lds + PG8_SB(b, h) + boff + n * 2048 + k * 1024); } while (0)
; #define PG8_MMA(ai, bj, At, Bt) do { __builtin_amdgcn_s_setprio(1); _Pragma("unroll") for (int m = 0; m < 4; ++m) _Pragma("unroll") for (int n = 0; n < 2; ++n) _Pragma("unroll") for (int k = 0; k < 2; ++k) \
;         acc[ai][bj][m][n] = __builtin_amdgcn_mfma_f32_16x16x32_bf16(Bt[n][k], At[m][k], acc[ai][bj][m][n], 0, 0, 0); __builtin_amdgcn_s_setprio(0); } while (0)
; #define PG8_WAIT_V(n) asm volatile("s_waitcnt vmcnt(" #n ")" ::: "memory")
; #define PG8_WAIT_L(n) asm volatile("s_waitcnt lgkmcnt(" #n ")" ::: "memory")
; #define PG8_BAR __builtin_amdgcn_s_barrier()
; #define PG8_SCHED __builtin_amdgcn_sched_barrier(0)
; template <class Epi>
; __device__ __forceinline__ void gemm_phase(PG8_LAS unsigned char* lds, const Gemm g, const StaticOrder& S, const Epi& E, const int wave_s) {
;     ...
;             PG8_WAIT_V(8); PG8_WAIT_L(0); PG8_BAR; PG8_MMA(1, 0, At, B0); PG8_MMA(1, 1, At, B1); PG8_BAR; PG8_SCHED;
;             PG8_LDB(B0, 1, 0); PG8_LDB(B1, 1, 1); PG8_SCHED; PG8_LDA(At, 1, 0); PG8_STAGE(PG8_SA(0, 1), a2 + hstepA, voffA);
;             PG8_WAIT_V(8); PG8_WAIT_L(0); PG8_BAR; PG8_MMA(0, 0, At, B0); PG8_MMA(0, 1, At, B1); PG8_BAR; PG8_SCHED;
;             PG8_LDA(At, 1, 1); PG8_STAGE(PG8_SB(1, 0), b3, voffB); PG8_STAGE(PG8_SB(1, 1), b3 + hstepB, voffB); PG8_STAGE(PG8_SA(1, 0), a3, voffA);
;             PG8_WAIT_V(8); PG8_WAIT_L(0); PG8_BAR; PG8_MMA(1, 0, At, B0); PG8_MMA(1, 1, At, B1); PG8_BAR; PG8_SCHED;
	s_waitcnt lgkmcnt(0)
	v_mfma_f32_16x16x32_bf16 v[64:67], v[150:153], v[186:189], v[64:67]
	v_mfma_f32_16x16x32_bf16 v[60:63], v[162:165], v[186:189], v[60:63]
	v_mfma_f32_16x16x32_bf16 v[48:51], v[150:153], v[194:197], v[48:51]
	v_mfma_f32_16x16x32_bf16 v[44:47], v[162:165], v[194:197], v[44:47]
	v_mfma_f32_16x16x32_bf16 v[32:35], v[150:153], v[202:205], v[32:35]
	v_mfma_f32_16x16x32_bf16 v[28:31], v[162:165], v[202:205], v[28:31]
	v_mfma_f32_16x16x32_bf16 v[16:19], v[150:153], v[218:221], v[16:19]
	v_mfma_f32_16x16x32_bf16 v[12:15], v[162:165], v[218:221], v[12:15]
	v_mfma_f32_16x16x32_bf16 v[64:67], v[154:157], v[190:193], v[64:67]
	v_mfma_f32_16x16x32_bf16 v[60:63], v[166:169], v[190:193], v[60:63]
	v_mfma_f32_16x16x32_bf16 v[48:51], v[154:157], v[198:201], v[48:51]
	v_mfma_f32_16x16x32_bf16 v[44:47], v[166:169], v[198:201], v[44:47]
	v_mfma_f32_16x16x32_bf16 v[32:35], v[154:157], v[206:209], v[32:35]
	v_mfma_f32_16x16x32_bf16 v[28:31], v[166:169], v[206:209], v[28:31]
	v_mfma_f32_16x16x32_bf16 v[16:19], v[154:157], v[222:225], v[16:19]
	v_mfma_f32_16x16x32_bf16 v[12:15], v[166:169], v[222:225], v[12:15]
	v_mfma_f32_16x16x32_bf16 v[56:59], v[170:173], v[186:189], v[56:59]
	v_mfma_f32_16x16x32_bf16 v[52:55], v[178:181], v[186:189], v[52:55]
	v_mfma_f32_16x16x32_bf16 v[40:43], v[170:173], v[194:197], v[40:43]
	v_mfma_f32_16x16x32_bf16 v[36:39], v[178:181], v[194:197], v[36:39]
	v_mfma_f32_16x16x32_bf16 v[24:27], v[170:173], v[202:205], v[24:27]
	v_mfma_f32_16x16x32_bf16 v[20:23], v[178:181], v[202:205], v[20:23]
	v_mfma_f32_16x16x32_bf16 v[8:11], v[170:173], v[218:221], v[8:11]
	v_mfma_f32_16x16x32_bf16 v[4:7], v[178:181], v[218:221], v[4:7]
	v_mfma_f32_16x16x32_bf16 v[56:59], v[174:177], v[190:193], v[56:59]
	v_mfma_f32_16x16x32_bf16 v[52:55], v[182:185], v[190:193], v[52:55]
	v_mfma_f32_16x16x32_bf16 v[40:43], v[174:177], v[198:201], v[40:43]
	v_mfma_f32_16x16x32_bf16 v[36:39], v[182:185], v[198:201], v[36:39]
	v_mfma_f32_16x16x32_bf16 v[24:27], v[174:177], v[206:209], v[24:27]
	v_mfma_f32_16x16x32_bf16 v[20:23], v[182:185], v[206:209], v[20:23]
	v_mfma_f32_16x16x32_bf16 v[8:11], v[174:177], v[222:225], v[8:11]
	v_mfma_f32_16x16x32_bf16 v[4:7], v[182:185], v[222:225], v[4:7]
	s_barrier
	s_add_i32 s49, 0, 0x18000
	v_add_u32_e32 v97, s49, v159
	s_add_i32 s50, 0, 0x1c000
	ds_read_b128 v[150:153], v97
	ds_read_b128 v[154:157], v97 offset:1024
	ds_read_b128 v[162:165], v97 offset:2048
	ds_read_b128 v[166:169], v97 offset:3072
	v_add_u32_e32 v97, s50, v159
	ds_read_b128 v[170:173], v97
	ds_read_b128 v[174:177], v97 offset:1024
	ds_read_b128 v[178:181], v97 offset:2048
	ds_read_b128 v[182:185], v97 offset:3072
	s_add_u32 s6, s6, s20
	s_addc_u32 s7, s7, s21
	s_mov_b32 m0, s10
	v_lshl_add_u64 v[246:247], s[6:7], 0, v[134:135]
	ds_read_b128 v[186:189], v160 offset:32768
	ds_read_b128 v[190:193], v160 offset:33792
	ds_read_b128 v[194:197], v160 offset:34816
	ds_read_b128 v[198:201], v160 offset:35840
	ds_read_b128 v[202:205], v160 offset:36864
	ds_read_b128 v[206:209], v160 offset:37888
	ds_read_b128 v[218:221], v160 offset:38912
	ds_read_b128 v[222:225], v160 offset:39936
	global_load_lds_dwordx4 v[246:247], off
	v_lshl_add_u64 v[246:247], s[6:7], 0, v[136:137]
	s_mov_b32 m0, s11
	s_nop 0
	global_load_lds_dwordx4 v[246:247], off
	s_waitcnt vmcnt(8)
	s_waitcnt lgkmcnt(0)
	s_barrier
	s_waitcnt lgkmcnt(0)
	v_mfma_f32_16x16x32_bf16 v[130:133], v[150:153], v[186:189], v[130:133]
	v_mfma_f32_16x16x32_bf16 v[126:129], v[162:165], v[186:189], v[126:129]
	v_mfma_f32_16x16x32_bf16 v[114:117], v[150:153], v[194:197], v[114:117]
	v_mfma_f32_16x16x32_bf16 v[110:113], v[162:165], v[194:197], v[110:113]
	v_mfma_f32_16x16x32_bf16 v[98:101], v[150:153], v[202:205], v[98:101]
	v_mfma_f32_16x16x32_bf16 v[92:95], v[162:165], v[202:205], v[92:95]
	v_mfma_f32_16x16x32_bf16 v[80:83], v[150:153], v[218:221], v[80:83]
	v_mfma_f32_16x16x32_bf16 v[76:79], v[162:165], v[218:221], v[76:79]
	v_mfma_f32_16x16x32_bf16 v[130:133], v[154:157], v[190:193], v[130:133]
	v_mfma_f32_16x16x32_bf16 v[126:129], v[166:169], v[190:193], v[126:129]
	v_mfma_f32_16x16x32_bf16 v[114:117], v[154:157], v[198:201], v[114:117]
	v_mfma_f32_16x16x32_bf16 v[110:113], v[166:169], v[198:201], v[110:113]
	v_mfma_f32_16x16x32_bf16 v[98:101], v[154:157], v[206:209], v[98:101]
	v_mfma_f32_16x16x32_bf16 v[92:95], v[166:169], v[206:209], v[92:95]
	v_mfma_f32_16x16x32_bf16 v[80:83], v[154:157], v[222:225], v[80:83]
	v_mfma_f32_16x16x32_bf16 v[76:79], v[166:169], v[222:225], v[76:79]
	v_mfma_f32_16x16x32_bf16 v[122:125], v[170:173], v[186:189], v[122:125]
	v_mfma_f32_16x16x32_bf16 v[118:121], v[178:181], v[186:189], v[118:121]
	v_mfma_f32_16x16x32_bf16 v[106:109], v[170:173], v[194:197], v[106:109]
	v_mfma_f32_16x16x32_bf16 v[102:105], v[178:181], v[194:197], v[102:105]
	v_mfma_f32_16x16x32_bf16 v[88:91], v[170:173], v[202:205], v[88:91]
	v_mfma_f32_16x16x32_bf16 v[84:87], v[178:181], v[202:205], v[84:87]
	v_mfma_f32_16x16x32_bf16 v[72:75], v[170:173], v[218:221], v[72:75]
	v_mfma_f32_16x16x32_bf16 v[68:71], v[178:181], v[218:221], v[68:71]
	v_mfma_f32_16x16x32_bf16 v[122:125], v[174:177], v[190:193], v[122:125]
	v_mfma_f32_16x16x32_bf16 v[118:121], v[182:185], v[190:193], v[118:121]
	v_mfma_f32_16x16x32_bf16 v[106:109], v[174:177], v[198:201], v[106:109]
	v_mfma_f32_16x16x32_bf16 v[102:105], v[182:185], v[198:201], v[102:105]
	v_mfma_f32_16x16x32_bf16 v[88:91], v[174:177], v[206:209], v[88:91]
	v_mfma_f32_16x16x32_bf16 v[84:87], v[182:185], v[206:209], v[84:87]
	v_mfma_f32_16x16x32_bf16 v[72:75], v[174:177], v[222:225], v[72:75]
	v_mfma_f32_16x16x32_bf16 v[68:71], v[182:185], v[222:225], v[68:71]
	s_barrier
; #define PG8_STAGE(bufoff, gbase, voff) do { _Pragma("unroll") for (int _i = 0; _i < 2; ++_i) \
;         __builtin_amdgcn_global_load_lds((const unsigned*)((const char*)(gbase) + (voff)[_i]), (PG8_LAS unsigned*)(lds + (bufoff) + ldsw + _i * 8192), 16, 0, 0); } while (0)
; #define PG8_LDA(dst, b, h) do { _Pragma("unroll") for (int m = 0; m < 4; ++m) _Pragma("unroll") for (int k = 0; k < 2; ++k) dst[m][k] = *(const PG8_LAS bf16x8*)(lds + PG8_SA(b, h) + aoff + m * 2048 + k * 1024); } while (0)
; #define PG8_MMA(ai, bj, At, Bt) do { __builtin_amdgcn_s_setprio(1); _Pragma("unroll") for (int m = 0; m < 4; ++m) _Pragma("unroll") for (int n = 0; n < 2; ++n) _Pragma("unroll") for (int k = 0; k < 2; ++k) \
;         acc[ai][bj][m][n] = __builtin_amdgcn_mfma_f32_16x16x32_bf16(Bt[n][k], At[m][k], acc[ai][bj][m][n], 0, 0, 0); __builtin_amdgcn_s_setprio(0); } while (0)
; #define PG8_WAIT_V(n) asm volatile("s_waitcnt vmcnt(" #n ")" ::: "memory")
; #define PG8_WAIT_L(n) asm volatile("s_waitcnt lgkmcnt(" #n ")" ::: "memory")
; #define PG8_BAR __builtin_amdgcn_s_barrier()
; #define PG8_SCHED __builtin_amdgcn_sched_barrier(0)
; template <class Epi>
; __device__ __forceinline__ void gemm_phase(PG8_LAS unsigned char* lds, const Gemm g, const StaticOrder& S, const Epi& E, const int wave_s) {
;     ...
;             PG8_LDA(At, 1, 1); PG8_STAGE(PG8_SB(1, 0), b3, voffB); PG8_STAGE(PG8_SB(1, 1), b3 + hstepB, voffB); PG8_STAGE(PG8_SA(1, 0), a3, voffA);
;             PG8_WAIT_V(8); PG8_WAIT_L(0); PG8_BAR; PG8_MMA(1, 0, At, B0); PG8_MMA(1, 1, At, B1); PG8_BAR; PG8_SCHED;
;         }
	s_add_i32 s6, s49, s5
	v_lshl_add_u64 v[226:227], v[226:227], 0, s[52:53]
	s_mov_b32 m0, s6
	ds_read_b128 v[186:189], v160 offset:49152
	ds_read_b128 v[190:193], v160 offset:50176
	ds_read_b128 v[194:197], v160 offset:51200
	ds_read_b128 v[198:201], v160 offset:52224
	ds_read_b128 v[202:205], v160 offset:53248
	ds_read_b128 v[206:209], v160 offset:54272
	ds_read_b128 v[218:221], v160 offset:55296
	ds_read_b128 v[222:225], v160 offset:56320
	global_load_lds_dwordx4 v[226:227], off
	v_lshl_add_u64 v[226:227], v[228:229], 0, s[52:53]
	s_add_i32 m0, s6, 0x2000
	s_add_i32 s6, s50, s5
	global_load_lds_dwordx4 v[226:227], off
	v_lshl_add_u64 v[226:227], v[230:231], 0, s[52:53]
	s_mov_b32 m0, s6
	s_nop 0
	global_load_lds_dwordx4 v[226:227], off
	v_lshl_add_u64 v[226:227], v[232:233], 0, s[52:53]
	s_add_i32 m0, s6, 0x2000
	s_nop 0
	global_load_lds_dwordx4 v[226:227], off
	v_lshl_add_u64 v[226:227], v[242:243], 0, s[52:53]
	s_mov_b32 m0, s27
	s_nop 0
	global_load_lds_dwordx4 v[226:227], off
	v_lshl_add_u64 v[226:227], v[244:245], 0, s[52:53]
	s_mov_b32 m0, s36
	s_nop 0
	global_load_lds_dwordx4 v[226:227], off
	s_waitcnt vmcnt(8)
	s_waitcnt lgkmcnt(0)
	s_barrier
	s_waitcnt lgkmcnt(0)
	v_mfma_f32_16x16x32_bf16 v[64:67], v[150:153], v[186:189], v[64:67]
	v_mfma_f32_16x16x32_bf16 v[60:63], v[162:165], v[186:189], v[60:63]
	v_mfma_f32_16x16x32_bf16 v[48:51], v[150:153], v[194:197], v[48:51]
	v_mfma_f32_16x16x32_bf16 v[44:47], v[162:165], v[194:197], v[44:47]
	v_mfma_f32_16x16x32_bf16 v[32:35], v[150:153], v[202:205], v[32:35]
	v_mfma_f32_16x16x32_bf16 v[28:31], v[162:165], v[202:205], v[28:31]
	v_mfma_f32_16x16x32_bf16 v[16:19], v[150:153], v[218:221], v[16:19]
	v_mfma_f32_16x16x32_bf16 v[12:15], v[162:165], v[218:221], v[12:15]
	v_mfma_f32_16x16x32_bf16 v[64:67], v[154:157], v[190:193], v[64:67]
	v_mfma_f32_16x16x32_bf16 v[60:63], v[166:169], v[190:193], v[60:63]
	v_mfma_f32_16x16x32_bf16 v[48:51], v[154:157], v[198:201], v[48:51]
	v_mfma_f32_16x16x32_bf16 v[44:47], v[166:169], v[198:201], v[44:47]
	v_mfma_f32_16x16x32_bf16 v[32:35], v[154:157], v[206:209], v[32:35]
	v_mfma_f32_16x16x32_bf16 v[28:31], v[166:169], v[206:209], v[28:31]
	v_mfma_f32_16x16x32_bf16 v[16:19], v[154:157], v[222:225], v[16:19]
	v_mfma_f32_16x16x32_bf16 v[12:15], v[166:169], v[222:225], v[12:15]
	v_mfma_f32_16x16x32_bf16 v[56:59], v[170:173], v[186:189], v[56:59]
	v_mfma_f32_16x16x32_bf16 v[52:55], v[178:181], v[186:189], v[52:55]
	v_mfma_f32_16x16x32_bf16 v[40:43], v[170:173], v[194:197], v[40:43]
	v_mfma_f32_16x16x32_bf16 v[36:39], v[178:181], v[194:197], v[36:39]
	v_mfma_f32_16x16x32_bf16 v[24:27], v[170:173], v[202:205], v[24:27]
	v_mfma_f32_16x16x32_bf16 v[20:23], v[178:181], v[202:205], v[20:23]
	v_mfma_f32_16x16x32_bf16 v[8:11], v[170:173], v[218:221], v[8:11]
	v_mfma_f32_16x16x32_bf16 v[4:7], v[178:181], v[218:221], v[4:7]
	v_mfma_f32_16x16x32_bf16 v[56:59], v[174:177], v[190:193], v[56:59]
	v_mfma_f32_16x16x32_bf16 v[52:55], v[182:185], v[190:193], v[52:55]
	v_mfma_f32_16x16x32_bf16 v[40:43], v[174:177], v[198:201], v[40:43]
	v_mfma_f32_16x16x32_bf16 v[36:39], v[182:185], v[198:201], v[36:39]
	v_mfma_f32_16x16x32_bf16 v[24:27], v[174:177], v[206:209], v[24:27]
	v_mfma_f32_16x16x32_bf16 v[20:23], v[182:185], v[206:209], v[20:23]
	v_mfma_f32_16x16x32_bf16 v[8:11], v[174:177], v[222:225], v[8:11]
	v_mfma_f32_16x16x32_bf16 v[4:7], v[182:185], v[222:225], v[4:7]
	s_barrier
	s_add_u32 s44, s44, 0x100
	s_addc_u32 s45, s45, 0
	s_add_u32 s46, s46, 0x100
	s_addc_u32 s47, s47, 0
	s_cmp_ge_i32 s48, s25
	s_mov_b32 s6, s48
	s_cbranch_scc0 .LBB0_651
	s_setprio 0

; template <class Epi>
; __device__ __forceinline__ void gemm_phase(PG8_LAS unsigned char* lds, const Gemm g, const StaticOrder& S, const Epi& E, const int wave_s) {
;     ...
;         for (int t = 0; t < nt; t += 2) {
;             const bool last = (t == nt - 2);
;             const char* a1 = cA + (size_t)(t + 1) * kstep;
;             const char* a2 = last ? nA : cA + (size_t)(t + 2) * kstep; const char* b2 = last ? nB : cB + (size_t)(t + 2) * kstep;
;     ...
;         for (int a = 0; a < 2; ++a)
; #pragma unroll
;             for (int b = 0; b < 2; ++b)
; #pragma unroll
;                 for (int m = 0; m < 4; ++m)
; #pragma unroll
;                     for (int n = 0; n < 2; ++n) acc[a][b][m][n] = (f32x4){0.f, 0.f, 0.f, 0.f};
.LBB0_763:
	v_mov_b32_e32 v161, 0
	s_andn2_b64 vcc, exec, s[64:65]
	v_mov_b32_e32 v160, v161
	v_mov_b32_e32 v159, v161
	v_mov_b32_e32 v158, v161
	v_mov_b32_e32 v157, v161
	v_mov_b32_e32 v156, v161
	v_mov_b32_e32 v155, v161
	v_mov_b32_e32 v154, v161
	s_waitcnt vmcnt(0)
	v_mov_b32_e32 v137, v161
	v_mov_b32_e32 v136, v161
	v_mov_b32_e32 v135, v161
	v_mov_b32_e32 v134, v161
	v_mov_b32_e32 v133, v161
	v_mov_b32_e32 v132, v161
	v_mov_b32_e32 v131, v161
	v_mov_b32_e32 v130, v161
	v_mov_b32_e32 v95, v161
	v_mov_b32_e32 v94, v161
	v_mov_b32_e32 v93, v161
	v_mov_b32_e32 v92, v161
	v_mov_b32_e32 v91, v161
	v_mov_b32_e32 v90, v161
	v_mov_b32_e32 v89, v161
	v_mov_b32_e32 v88, v161
	v_mov_b32_e32 v79, v161
	v_mov_b32_e32 v78, v161
	v_mov_b32_e32 v77, v161
	v_mov_b32_e32 v76, v161
	v_mov_b32_e32 v75, v161
	v_mov_b32_e32 v74, v161
	v_mov_b32_e32 v73, v161
	v_mov_b32_e32 v72, v161
	v_mov_b32_e32 v153, v161
	v_mov_b32_e32 v152, v161
	v_mov_b32_e32 v151, v161
	v_mov_b32_e32 v150, v161
	v_mov_b32_e32 v149, v161
	v_mov_b32_e32 v148, v161
	v_mov_b32_e32 v147, v161
	v_mov_b32_e32 v146, v161
	v_mov_b32_e32 v129, v161
	v_mov_b32_e32 v128, v161
	v_mov_b32_e32 v127, v161
	v_mov_b32_e32 v126, v161
	v_mov_b32_e32 v117, v161
	v_mov_b32_e32 v116, v161
	v_mov_b32_e32 v115, v161
	v_mov_b32_e32 v114, v161
	v_mov_b32_e32 v87, v161
	v_mov_b32_e32 v86, v161
	v_mov_b32_e32 v85, v161
	v_mov_b32_e32 v84, v161
	v_mov_b32_e32 v83, v161
	v_mov_b32_e32 v82, v161
	v_mov_b32_e32 v81, v161
	v_mov_b32_e32 v80, v161
	v_mov_b32_e32 v71, v161
	v_mov_b32_e32 v70, v161
	v_mov_b32_e32 v69, v161
	v_mov_b32_e32 v68, v161
	v_mov_b32_e32 v67, v161
	v_mov_b32_e32 v66, v161
	v_mov_b32_e32 v65, v161
	v_mov_b32_e32 v64, v161
	v_mov_b32_e32 v63, v161
	v_mov_b32_e32 v62, v161
	v_mov_b32_e32 v61, v161
	v_mov_b32_e32 v60, v161
	v_mov_b32_e32 v59, v161
	v_mov_b32_e32 v58, v161
	v_mov_b32_e32 v57, v161
	v_mov_b32_e32 v56, v161
	v_mov_b32_e32 v47, v161
	v_mov_b32_e32 v46, v161
	v_mov_b32_e32 v45, v161
	v_mov_b32_e32 v44, v161
	v_mov_b32_e32 v43, v161
	v_mov_b32_e32 v42, v161
	v_mov_b32_e32 v41, v161
	v_mov_b32_e32 v40, v161
	v_mov_b32_e32 v31, v161
	v_mov_b32_e32 v30, v161
	v_mov_b32_e32 v29, v161
	v_mov_b32_e32 v28, v161
	v_mov_b32_e32 v27, v161
	v_mov_b32_e32 v26, v161
	v_mov_b32_e32 v25, v161
	v_mov_b32_e32 v24, v161
	v_mov_b32_e32 v15, v161
	v_mov_b32_e32 v14, v161
	v_mov_b32_e32 v13, v161
	v_mov_b32_e32 v12, v161
	v_mov_b32_e32 v11, v161
	v_mov_b32_e32 v10, v161
	v_mov_b32_e32 v9, v161
	v_mov_b32_e32 v8, v161
	v_mov_b32_e32 v55, v161
	v_mov_b32_e32 v54, v161
	v_mov_b32_e32 v53, v161
	v_mov_b32_e32 v52, v161
	v_mov_b32_e32 v51, v161
	v_mov_b32_e32 v50, v161
	v_mov_b32_e32 v49, v161
	v_mov_b32_e32 v48, v161
	v_mov_b32_e32 v39, v161
	v_mov_b32_e32 v38, v161
	v_mov_b32_e32 v37, v161
	v_mov_b32_e32 v36, v161
	v_mov_b32_e32 v35, v161
	v_mov_b32_e32 v34, v161
	v_mov_b32_e32 v33, v161
	v_mov_b32_e32 v32, v161
	v_mov_b32_e32 v23, v161
	v_mov_b32_e32 v22, v161
	v_mov_b32_e32 v21, v161
	v_mov_b32_e32 v20, v161
	v_mov_b32_e32 v19, v161
	v_mov_b32_e32 v18, v161
	v_mov_b32_e32 v17, v161
	v_mov_b32_e32 v16, v161
	v_mov_b32_e32 v7, v161
	v_mov_b32_e32 v6, v161
	v_mov_b32_e32 v5, v161
	v_mov_b32_e32 v4, v161
	v_mov_b32_e32 v3, v161
	v_mov_b32_e32 v2, v161
	v_mov_b32_e32 v1, v161
	v_mov_b32_e32 v0, v161
	s_cbranch_vccnz .LBB0_766
	s_add_u32 s44, s48, 0x80
	s_addc_u32 s45, s49, 0
	s_add_u32 s12, s46, 0x100
	v_mov_b32_e32 v0, 0
	s_addc_u32 s13, s47, 0
	s_mov_b32 s6, 0
	v_mov_b32_e32 v1, v0
	v_mov_b32_e32 v2, v0
	v_mov_b32_e32 v3, v0
	v_mov_b32_e32 v4, v0
	v_mov_b32_e32 v5, v0
	v_mov_b32_e32 v6, v0
	v_mov_b32_e32 v7, v0
	v_mov_b32_e32 v16, v0
	v_mov_b32_e32 v17, v0
	v_mov_b32_e32 v18, v0
	v_mov_b32_e32 v19, v0
	v_mov_b32_e32 v20, v0
	v_mov_b32_e32 v21, v0
	v_mov_b32_e32 v22, v0
	v_mov_b32_e32 v23, v0
	v_mov_b32_e32 v32, v0
	v_mov_b32_e32 v33, v0
	v_mov_b32_e32 v34, v0
	v_mov_b32_e32 v35, v0
	v_mov_b32_e32 v36, v0
	v_mov_b32_e32 v37, v0
	v_mov_b32_e32 v38, v0
	v_mov_b32_e32 v39, v0
	v_mov_b32_e32 v48, v0
	v_mov_b32_e32 v49, v0
	v_mov_b32_e32 v50, v0
	v_mov_b32_e32 v51, v0
	v_mov_b32_e32 v52, v0
	v_mov_b32_e32 v53, v0
	v_mov_b32_e32 v54, v0
	v_mov_b32_e32 v55, v0
	v_mov_b32_e32 v8, v0
	v_mov_b32_e32 v9, v0
	v_mov_b32_e32 v10, v0
	v_mov_b32_e32 v11, v0
	v_mov_b32_e32 v12, v0
	v_mov_b32_e32 v13, v0
	v_mov_b32_e32 v14, v0
	v_mov_b32_e32 v15, v0
	v_mov_b32_e32 v24, v0
	v_mov_b32_e32 v25, v0
	v_mov_b32_e32 v26, v0
	v_mov_b32_e32 v27, v0
	v_mov_b32_e32 v28, v0
	v_mov_b32_e32 v29, v0
	v_mov_b32_e32 v30, v0
	v_mov_b32_e32 v31, v0
	v_mov_b32_e32 v40, v0
	v_mov_b32_e32 v41, v0
	v_mov_b32_e32 v42, v0
	v_mov_b32_e32 v43, v0
	v_mov_b32_e32 v44, v0
	v_mov_b32_e32 v45, v0
	v_mov_b32_e32 v46, v0
	v_mov_b32_e32 v47, v0
	v_mov_b32_e32 v56, v0
	v_mov_b32_e32 v57, v0
	v_mov_b32_e32 v58, v0
	v_mov_b32_e32 v59, v0
	v_mov_b32_e32 v60, v0
	v_mov_b32_e32 v61, v0
	v_mov_b32_e32 v62, v0
	v_mov_b32_e32 v63, v0
	v_mov_b32_e32 v64, v0
	v_mov_b32_e32 v65, v0
	v_mov_b32_e32 v66, v0
	v_mov_b32_e32 v67, v0
	v_mov_b32_e32 v68, v0
	v_mov_b32_e32 v69, v0
	v_mov_b32_e32 v70, v0
	v_mov_b32_e32 v71, v0
	v_mov_b32_e32 v80, v0
	v_mov_b32_e32 v81, v0
	v_mov_b32_e32 v82, v0
	v_mov_b32_e32 v83, v0
	v_mov_b32_e32 v84, v0
	v_mov_b32_e32 v85, v0
	v_mov_b32_e32 v86, v0
	v_mov_b32_e32 v87, v0
	v_mov_b32_e32 v114, v0
	v_mov_b32_e32 v115, v0
	v_mov_b32_e32 v116, v0
	v_mov_b32_e32 v117, v0
	v_mov_b32_e32 v126, v0
	v_mov_b32_e32 v127, v0
	v_mov_b32_e32 v128, v0
	v_mov_b32_e32 v129, v0
	v_mov_b32_e32 v146, v0
	v_mov_b32_e32 v147, v0
	v_mov_b32_e32 v148, v0
	v_mov_b32_e32 v149, v0
	v_mov_b32_e32 v150, v0
	v_mov_b32_e32 v151, v0
	v_mov_b32_e32 v152, v0
	v_mov_b32_e32 v153, v0
	v_mov_b32_e32 v72, v0
	v_mov_b32_e32 v73, v0
	v_mov_b32_e32 v74, v0
	v_mov_b32_e32 v75, v0
	v_mov_b32_e32 v76, v0
	v_mov_b32_e32 v77, v0
	v_mov_b32_e32 v78, v0
	v_mov_b32_e32 v79, v0
	v_mov_b32_e32 v88, v0
	v_mov_b32_e32 v89, v0
	v_mov_b32_e32 v90, v0
	v_mov_b32_e32 v91, v0
	v_mov_b32_e32 v92, v0
	v_mov_b32_e32 v93, v0
	v_mov_b32_e32 v94, v0
	v_mov_b32_e32 v95, v0
	v_mov_b32_e32 v130, v0
	v_mov_b32_e32 v131, v0
	v_mov_b32_e32 v132, v0
	v_mov_b32_e32 v133, v0
	v_mov_b32_e32 v134, v0
	v_mov_b32_e32 v135, v0
	v_mov_b32_e32 v136, v0
	v_mov_b32_e32 v137, v0
	v_mov_b32_e32 v154, v0
	v_mov_b32_e32 v155, v0
	v_mov_b32_e32 v156, v0
	v_mov_b32_e32 v157, v0
	v_mov_b32_e32 v158, v0
	v_mov_b32_e32 v159, v0
	v_mov_b32_e32 v160, v0
	v_mov_b32_e32 v161, v0
	v_readlane_b32 s7, v254, 61
	s_nop 3
	s_cmp_lt_u32 s7, 0x100
	s_cbranch_scc1 .Lg4_prio_done
	s_setprio 1
; #define PG8_STAGE(bufoff, gbase, voff) do { _Pragma("unroll") for (int _i = 0; _i < 2; ++_i) \
;         __builtin_amdgcn_global_load_lds((const unsigned*)((const char*)(gbase) + (voff)[_i]), (PG8_LAS unsigned*)(lds + (bufoff) + ldsw + _i * 8192), 16, 0, 0); } while (0)
; #define PG8_LDA(dst, b, h) do { _Pragma("unroll") for (int m = 0; m < 4; ++m) _Pragma("unroll") for (int k = 0; k < 2; ++k) dst[m][k] = *(const PG8_LAS bf16x8*)(lds + PG8_SA(b, h) + aoff + m * 2048 + k * 1024); } while (0)
; #define PG8_LDB(dst, b, h) do { _Pragma("unroll") for (int n = 0; n < 2; ++n) _Pragma("unroll") for (int k = 0; k < 2; ++k) dst[n][k] = *(const PG8_LAS bf16x8*)(lds + PG8_SB(b, h) + boff + n * 2048 + k * 1024); } while (0)
; #define PG8_MMA(ai, bj, At, Bt) do { __builtin_amdgcn_s_setprio(1); _Pragma("unroll") for (int m = 0; m < 4; ++m) _Pragma("unroll") for (int n = 0; n < 2; ++n) _Pragma("unroll") for (int k = 0; k < 2; ++k) \
;         acc[ai][bj][m][n] = __builtin_amdgcn_mfma_f32_16x16x32_bf16(Bt[n][k], At[m][k], acc[ai][bj][m][n], 0, 0, 0); __builtin_amdgcn_s_setprio(0); } while (0)
; #define PG8_WAIT_V(n) asm volatile("s_waitcnt vmcnt(" #n ")" ::: "memory")
; #define PG8_WAIT_L(n) asm volatile("s_waitcnt lgkmcnt(" #n ")" ::: "memory")
; #define PG8_BAR __builtin_amdgcn_s_barrier()
; #define PG8_SCHED __builtin_amdgcn_sched_barrier(0)
; template <class Epi>
; __device__ __forceinline__ void gemm_phase(PG8_LAS unsigned char* lds, const Gemm g, const StaticOrder& S, const Epi& E, const int wave_s) {
;     ...
;         for (int t = 0; t < nt; t += 2) {
;             const bool last = (t == nt - 2);
;             const char* a1 = cA + (size_t)(t + 1) * kstep;
;             const char* a2 = last ? nA : cA + (size_t)(t + 2) * kstep; const char* b2 = last ? nB : cB + (size_t)(t + 2) * kstep;
;             const char* a3 = a2 + kstep; const char* b3 = b2 + kstep;
;             PG8_LDB(B0, 0, 0); PG8_LDB(B1, 0, 1); PG8_SCHED; PG8_LDA(At, 0, 0); PG8_STAGE(PG8_SA(1, 1), a1 + hstepA, voffA);
;             PG8_WAIT_V(8); PG8_WAIT_L(0); PG8_BAR; PG8_MMA(0, 0, At, B0); PG8_MMA(0, 1, At, B1); PG8_BAR; PG8_SCHED;
;             PG8_LDA(At, 0, 1); PG8_STAGE(PG8_SB(0, 0), b2, voffB); PG8_STAGE(PG8_SB(0, 1), b2 + hstepB, voffB); PG8_STAGE(PG8_SA(0, 0), a2, voffA);
;             PG8_WAIT_V(8); PG8_WAIT_L(0); PG8_BAR; PG8_MMA(1, 0, At, B0); PG8_MMA(1, 1, At, B1); PG8_BAR; PG8_SCHED;
.Lg4_prio_done:
.LBB0_765:
	s_add_i32 s46, s6, 2
	s_add_u32 s47, s44, 0x80
	s_addc_u32 s7, s45, 0
	s_add_i32 s57, 0, 0x10000
	s_cmp_eq_u32 s92, s6
	s_cselect_b32 s7, s85, s7
	s_cselect_b32 s6, s84, s47
	s_cselect_b32 s49, s87, s13
	s_cselect_b32 s48, s86, s12
	s_add_i32 s47, 0, 0x14000
	v_add_u32_e32 v110, s57, v97
	v_add_u32_e32 v142, s47, v97
	ds_read_b128 v[98:101], v110
	ds_read_b128 v[102:105], v110 offset:1024
	ds_read_b128 v[106:109], v110 offset:2048
	ds_read_b128 v[110:113], v110 offset:3072
	ds_read_b128 v[118:121], v142
	ds_read_b128 v[122:125], v142 offset:1024
	ds_read_b128 v[138:141], v142 offset:2048
	ds_read_b128 v[142:145], v142 offset:3072
	v_lshl_add_u64 v[194:195], s[44:45], 0, v[224:225]
	s_add_i32 m0, s27, 0xc000
	ds_read_b128 v[162:165], v242
	ds_read_b128 v[166:169], v242 offset:1024
	ds_read_b128 v[170:173], v242 offset:2048
	ds_read_b128 v[174:177], v242 offset:3072
	ds_read_b128 v[178:181], v242 offset:4096
	ds_read_b128 v[182:185], v242 offset:5120
	ds_read_b128 v[186:189], v242 offset:6144
	ds_read_b128 v[190:193], v242 offset:7168
	global_load_lds_dwordx4 v[194:195], off
	v_lshl_add_u64 v[194:195], s[44:45], 0, v[226:227]
	s_add_i32 m0, s27, 0xe000
	s_nop 0
	global_load_lds_dwordx4 v[194:195], off
	s_waitcnt vmcnt(8)
	s_waitcnt lgkmcnt(0)
	s_barrier
	s_waitcnt lgkmcnt(0)
	v_mfma_f32_16x16x32_bf16 v[158:161], v[98:101], v[162:165], v[158:161]
	v_mfma_f32_16x16x32_bf16 v[154:157], v[106:109], v[162:165], v[154:157]
	v_mfma_f32_16x16x32_bf16 v[134:137], v[98:101], v[170:173], v[134:137]
	v_mfma_f32_16x16x32_bf16 v[130:133], v[106:109], v[170:173], v[130:133]
	v_mfma_f32_16x16x32_bf16 v[92:95], v[98:101], v[178:181], v[92:95]
	v_mfma_f32_16x16x32_bf16 v[88:91], v[106:109], v[178:181], v[88:91]
	v_mfma_f32_16x16x32_bf16 v[76:79], v[98:101], v[186:189], v[76:79]
	v_mfma_f32_16x16x32_bf16 v[72:75], v[106:109], v[186:189], v[72:75]
	v_mfma_f32_16x16x32_bf16 v[158:161], v[102:105], v[166:169], v[158:161]
	v_mfma_f32_16x16x32_bf16 v[154:157], v[110:113], v[166:169], v[154:157]
	v_mfma_f32_16x16x32_bf16 v[134:137], v[102:105], v[174:177], v[134:137]
	v_mfma_f32_16x16x32_bf16 v[130:133], v[110:113], v[174:177], v[130:133]
	v_mfma_f32_16x16x32_bf16 v[92:95], v[102:105], v[182:185], v[92:95]
	v_mfma_f32_16x16x32_bf16 v[88:91], v[110:113], v[182:185], v[88:91]
	v_mfma_f32_16x16x32_bf16 v[76:79], v[102:105], v[190:193], v[76:79]
	v_mfma_f32_16x16x32_bf16 v[72:75], v[110:113], v[190:193], v[72:75]
	v_mfma_f32_16x16x32_bf16 v[150:153], v[118:121], v[162:165], v[150:153]
	v_mfma_f32_16x16x32_bf16 v[146:149], v[138:141], v[162:165], v[146:149]
	v_mfma_f32_16x16x32_bf16 v[126:129], v[118:121], v[170:173], v[126:129]
	v_mfma_f32_16x16x32_bf16 v[114:117], v[138:141], v[170:173], v[114:117]
	v_mfma_f32_16x16x32_bf16 v[84:87], v[118:121], v[178:181], v[84:87]
	v_mfma_f32_16x16x32_bf16 v[80:83], v[138:141], v[178:181], v[80:83]
	v_mfma_f32_16x16x32_bf16 v[68:71], v[118:121], v[186:189], v[68:71]
	v_mfma_f32_16x16x32_bf16 v[64:67], v[138:141], v[186:189], v[64:67]
	v_mfma_f32_16x16x32_bf16 v[150:153], v[122:125], v[166:169], v[150:153]
	v_mfma_f32_16x16x32_bf16 v[146:149], v[142:145], v[166:169], v[146:149]
	v_mfma_f32_16x16x32_bf16 v[126:129], v[122:125], v[174:177], v[126:129]
	v_mfma_f32_16x16x32_bf16 v[114:117], v[142:145], v[174:177], v[114:117]
	v_mfma_f32_16x16x32_bf16 v[84:87], v[122:125], v[182:185], v[84:87]
	v_mfma_f32_16x16x32_bf16 v[80:83], v[142:145], v[182:185], v[80:83]
	v_mfma_f32_16x16x32_bf16 v[68:71], v[122:125], v[190:193], v[68:71]
	v_mfma_f32_16x16x32_bf16 v[64:67], v[142:145], v[190:193], v[64:67]
	s_barrier
	s_add_i32 s57, s57, s16
	v_lshl_add_u64 v[194:195], s[48:49], 0, v[210:211]
	s_mov_b32 m0, s57
	ds_read_b128 v[162:165], v242 offset:16384
	ds_read_b128 v[166:169], v242 offset:17408
	ds_read_b128 v[170:173], v242 offset:18432
	ds_read_b128 v[174:177], v242 offset:19456
	ds_read_b128 v[178:181], v242 offset:20480
	ds_read_b128 v[182:185], v242 offset:21504
	ds_read_b128 v[186:189], v242 offset:22528
	ds_read_b128 v[190:193], v242 offset:23552
	global_load_lds_dwordx4 v[194:195], off
	s_add_i32 m0, s57, 0x2000
	v_lshl_add_u64 v[196:197], s[48:49], 0, v[222:223]
	s_add_u32 s48, s48, s20
	s_addc_u32 s49, s49, s21
	s_add_i32 s47, s47, s16
	global_load_lds_dwordx4 v[196:197], off
	v_lshl_add_u64 v[198:199], s[48:49], 0, v[210:211]
	s_mov_b32 m0, s47
	v_lshl_add_u64 v[200:201], s[48:49], 0, v[222:223]
	global_load_lds_dwordx4 v[198:199], off
	s_add_i32 m0, s47, 0x2000
	v_lshl_add_u64 v[202:203], s[6:7], 0, v[218:219]
	global_load_lds_dwordx4 v[200:201], off
	s_mov_b32 m0, s27
	v_lshl_add_u64 v[204:205], s[6:7], 0, v[220:221]
	global_load_lds_dwordx4 v[202:203], off
	s_mov_b32 m0, s36
	s_nop 0
	global_load_lds_dwordx4 v[204:205], off
	s_waitcnt vmcnt(8)
	s_waitcnt lgkmcnt(0)
	s_barrier
; #define PG8_STAGE(bufoff, gbase, voff) do { _Pragma("unroll") for (int _i = 0; _i < 2; ++_i) \
;         __builtin_amdgcn_global_load_lds((const unsigned*)((const char*)(gbase) + (voff)[_i]), (PG8_LAS unsigned*)(lds + (bufoff) + ldsw + _i * 8192), 16, 0, 0); } while (0)
; #define PG8_LDA(dst, b, h) do { _Pragma("unroll") for (int m = 0; m < 4; ++m) _Pragma("unroll") for (int k = 0; k < 2; ++k) dst[m][k] = *(const PG8_LAS bf16x8*)(lds + PG8_SA(b, h) + aoff + m * 2048 + k * 1024); } while (0)
; #define PG8_LDB(dst, b, h) do { _Pragma("unroll") for (int n = 0; n < 2; ++n) _Pragma("unroll") for (int k = 0; k < 2; ++k) dst[n][k] = *(const PG8_LAS bf16x8*)(lds + PG8_SB(b, h) + boff + n * 2048 + k * 1024); } while (0)
; #define PG8_MMA(ai, bj, At, Bt) do { __builtin_amdgcn_s_setprio(1); _Pragma("unroll") for (int m = 0; m < 4; ++m) _Pragma("unroll") for (int n = 0; n < 2; ++n) _Pragma("unroll") for (int k = 0; k < 2; ++k) \
;         acc[ai][bj][m][n] = __builtin_amdgcn_mfma_f32_16x16x32_bf16(Bt[n][k], At[m][k], acc[ai][bj][m][n], 0, 0, 0); __builtin_amdgcn_s_setprio(0); } while (0)
; #define PG8_WAIT_V(n) asm volatile("s_waitcnt vmcnt(" #n ")" ::: "memory")
; #define PG8_WAIT_L(n) asm volatile("s_waitcnt lgkmcnt(" #n ")" ::: "memory")
; #define PG8_BAR __builtin_amdgcn_s_barrier()
; #define PG8_SCHED __builtin_amdgcn_sched_barrier(0)
; template <class Epi>
; __device__ __forceinline__ void gemm_phase(PG8_LAS unsigned char* lds, const Gemm g, const StaticOrder& S, const Epi& E, const int wave_s) {
;     ...
;             PG8_WAIT_V(8); PG8_WAIT_L(0); PG8_BAR; PG8_MMA(1, 0, At, B0); PG8_MMA(1, 1, At, B1); PG8_BAR; PG8_SCHED;
;             PG8_LDB(B0, 1, 0); PG8_LDB(B1, 1, 1); PG8_SCHED; PG8_LDA(At, 1, 0); PG8_STAGE(PG8_SA(0, 1), a2 + hstepA, voffA);
;             PG8_WAIT_V(8); PG8_WAIT_L(0); PG8_BAR; PG8_MMA(0, 0, At, B0); PG8_MMA(0, 1, At, B1); PG8_BAR; PG8_SCHED;
;             PG8_LDA(At, 1, 1); PG8_STAGE(PG8_SB(1, 0), b3, voffB); PG8_STAGE(PG8_SB(1, 1), b3 + hstepB, voffB); PG8_STAGE(PG8_SA(1, 0), a3, voffA);
;             PG8_WAIT_V(8); PG8_WAIT_L(0); PG8_BAR; PG8_MMA(1, 0, At, B0); PG8_MMA(1, 1, At, B1); PG8_BAR; PG8_SCHED;
	s_waitcnt lgkmcnt(0)
	v_mfma_f32_16x16x32_bf16 v[60:63], v[98:101], v[162:165], v[60:63]
	v_mfma_f32_16x16x32_bf16 v[56:59], v[106:109], v[162:165], v[56:59]
	v_mfma_f32_16x16x32_bf16 v[44:47], v[98:101], v[170:173], v[44:47]
	v_mfma_f32_16x16x32_bf16 v[40:43], v[106:109], v[170:173], v[40:43]
	v_mfma_f32_16x16x32_bf16 v[28:31], v[98:101], v[178:181], v[28:31]
	v_mfma_f32_16x16x32_bf16 v[24:27], v[106:109], v[178:181], v[24:27]
	v_mfma_f32_16x16x32_bf16 v[12:15], v[98:101], v[186:189], v[12:15]
	v_mfma_f32_16x16x32_bf16 v[8:11], v[106:109], v[186:189], v[8:11]
	v_mfma_f32_16x16x32_bf16 v[60:63], v[102:105], v[166:169], v[60:63]
	v_mfma_f32_16x16x32_bf16 v[56:59], v[110:113], v[166:169], v[56:59]
	v_mfma_f32_16x16x32_bf16 v[44:47], v[102:105], v[174:177], v[44:47]
	v_mfma_f32_16x16x32_bf16 v[40:43], v[110:113], v[174:177], v[40:43]
	v_mfma_f32_16x16x32_bf16 v[28:31], v[102:105], v[182:185], v[28:31]
	v_mfma_f32_16x16x32_bf16 v[24:27], v[110:113], v[182:185], v[24:27]
	v_mfma_f32_16x16x32_bf16 v[12:15], v[102:105], v[190:193], v[12:15]
	v_mfma_f32_16x16x32_bf16 v[8:11], v[110:113], v[190:193], v[8:11]
	v_mfma_f32_16x16x32_bf16 v[52:55], v[118:121], v[162:165], v[52:55]
	v_mfma_f32_16x16x32_bf16 v[48:51], v[138:141], v[162:165], v[48:51]
	v_mfma_f32_16x16x32_bf16 v[36:39], v[118:121], v[170:173], v[36:39]
	v_mfma_f32_16x16x32_bf16 v[32:35], v[138:141], v[170:173], v[32:35]
	v_mfma_f32_16x16x32_bf16 v[20:23], v[118:121], v[178:181], v[20:23]
	v_mfma_f32_16x16x32_bf16 v[16:19], v[138:141], v[178:181], v[16:19]
	v_mfma_f32_16x16x32_bf16 v[4:7], v[118:121], v[186:189], v[4:7]
	v_mfma_f32_16x16x32_bf16 v[0:3], v[138:141], v[186:189], v[0:3]
	v_mfma_f32_16x16x32_bf16 v[52:55], v[122:125], v[166:169], v[52:55]
	v_mfma_f32_16x16x32_bf16 v[48:51], v[142:145], v[166:169], v[48:51]
	v_mfma_f32_16x16x32_bf16 v[36:39], v[122:125], v[174:177], v[36:39]
	v_mfma_f32_16x16x32_bf16 v[32:35], v[142:145], v[174:177], v[32:35]
	v_mfma_f32_16x16x32_bf16 v[20:23], v[122:125], v[182:185], v[20:23]
	v_mfma_f32_16x16x32_bf16 v[16:19], v[142:145], v[182:185], v[16:19]
	v_mfma_f32_16x16x32_bf16 v[4:7], v[122:125], v[190:193], v[4:7]
	v_mfma_f32_16x16x32_bf16 v[0:3], v[142:145], v[190:193], v[0:3]
	s_barrier
	s_add_i32 s47, 0, 0x18000
	s_add_i32 s48, 0, 0x1c000
	v_add_u32_e32 v110, s47, v97
	v_add_u32_e32 v142, s48, v97
	ds_read_b128 v[98:101], v110
	ds_read_b128 v[102:105], v110 offset:1024
	ds_read_b128 v[106:109], v110 offset:2048
	ds_read_b128 v[110:113], v110 offset:3072
	ds_read_b128 v[118:121], v142
	ds_read_b128 v[122:125], v142 offset:1024
	ds_read_b128 v[138:141], v142 offset:2048
	ds_read_b128 v[142:145], v142 offset:3072
	s_add_u32 s6, s6, s10
	s_addc_u32 s7, s7, s11
	s_mov_b32 m0, s37
	v_lshl_add_u64 v[206:207], s[6:7], 0, v[218:219]
	ds_read_b128 v[162:165], v242 offset:32768
	ds_read_b128 v[166:169], v242 offset:33792
	ds_read_b128 v[170:173], v242 offset:34816
	ds_read_b128 v[174:177], v242 offset:35840
	ds_read_b128 v[178:181], v242 offset:36864
	ds_read_b128 v[182:185], v242 offset:37888
	ds_read_b128 v[186:189], v242 offset:38912
	ds_read_b128 v[190:193], v242 offset:39936
	global_load_lds_dwordx4 v[206:207], off
	v_lshl_add_u64 v[206:207], s[6:7], 0, v[220:221]
	s_mov_b32 m0, s88
	s_nop 0
	global_load_lds_dwordx4 v[206:207], off
	s_waitcnt vmcnt(8)
	s_waitcnt lgkmcnt(0)
	s_barrier
	s_waitcnt lgkmcnt(0)
	v_mfma_f32_16x16x32_bf16 v[158:161], v[98:101], v[162:165], v[158:161]
	v_mfma_f32_16x16x32_bf16 v[154:157], v[106:109], v[162:165], v[154:157]
	v_mfma_f32_16x16x32_bf16 v[134:137], v[98:101], v[170:173], v[134:137]
	v_mfma_f32_16x16x32_bf16 v[130:133], v[106:109], v[170:173], v[130:133]
	v_mfma_f32_16x16x32_bf16 v[92:95], v[98:101], v[178:181], v[92:95]
	v_mfma_f32_16x16x32_bf16 v[88:91], v[106:109], v[178:181], v[88:91]
	v_mfma_f32_16x16x32_bf16 v[76:79], v[98:101], v[186:189], v[76:79]
	v_mfma_f32_16x16x32_bf16 v[72:75], v[106:109], v[186:189], v[72:75]
	v_mfma_f32_16x16x32_bf16 v[158:161], v[102:105], v[166:169], v[158:161]
	v_mfma_f32_16x16x32_bf16 v[154:157], v[110:113], v[166:169], v[154:157]
	v_mfma_f32_16x16x32_bf16 v[134:137], v[102:105], v[174:177], v[134:137]
	v_mfma_f32_16x16x32_bf16 v[130:133], v[110:113], v[174:177], v[130:133]
	v_mfma_f32_16x16x32_bf16 v[92:95], v[102:105], v[182:185], v[92:95]
	v_mfma_f32_16x16x32_bf16 v[88:91], v[110:113], v[182:185], v[88:91]
	v_mfma_f32_16x16x32_bf16 v[76:79], v[102:105], v[190:193], v[76:79]
	v_mfma_f32_16x16x32_bf16 v[72:75], v[110:113], v[190:193], v[72:75]
	v_mfma_f32_16x16x32_bf16 v[150:153], v[118:121], v[162:165], v[150:153]
	v_mfma_f32_16x16x32_bf16 v[146:149], v[138:141], v[162:165], v[146:149]
	v_mfma_f32_16x16x32_bf16 v[126:129], v[118:121], v[170:173], v[126:129]
	v_mfma_f32_16x16x32_bf16 v[114:117], v[138:141], v[170:173], v[114:117]
	v_mfma_f32_16x16x32_bf16 v[84:87], v[118:121], v[178:181], v[84:87]
	v_mfma_f32_16x16x32_bf16 v[80:83], v[138:141], v[178:181], v[80:83]
	v_mfma_f32_16x16x32_bf16 v[68:71], v[118:121], v[186:189], v[68:71]
	v_mfma_f32_16x16x32_bf16 v[64:67], v[138:141], v[186:189], v[64:67]
	v_mfma_f32_16x16x32_bf16 v[150:153], v[122:125], v[166:169], v[150:153]
	v_mfma_f32_16x16x32_bf16 v[146:149], v[142:145], v[166:169], v[146:149]
	v_mfma_f32_16x16x32_bf16 v[126:129], v[122:125], v[174:177], v[126:129]
	v_mfma_f32_16x16x32_bf16 v[114:117], v[142:145], v[174:177], v[114:117]
	v_mfma_f32_16x16x32_bf16 v[84:87], v[122:125], v[182:185], v[84:87]
	v_mfma_f32_16x16x32_bf16 v[80:83], v[142:145], v[182:185], v[80:83]
	v_mfma_f32_16x16x32_bf16 v[68:71], v[122:125], v[190:193], v[68:71]
	v_mfma_f32_16x16x32_bf16 v[64:67], v[142:145], v[190:193], v[64:67]
	s_barrier
; #define PG8_STAGE(bufoff, gbase, voff) do { _Pragma("unroll") for (int _i = 0; _i < 2; ++_i) \
;         __builtin_amdgcn_global_load_lds((const unsigned*)((const char*)(gbase) + (voff)[_i]), (PG8_LAS unsigned*)(lds + (bufoff) + ldsw + _i * 8192), 16, 0, 0); } while (0)
; #define PG8_LDA(dst, b, h) do { _Pragma("unroll") for (int m = 0; m < 4; ++m) _Pragma("unroll") for (int k = 0; k < 2; ++k) dst[m][k] = *(const PG8_LAS bf16x8*)(lds + PG8_SA(b, h) + aoff + m * 2048 + k * 1024); } while (0)
; #define PG8_MMA(ai, bj, At, Bt) do { __builtin_amdgcn_s_setprio(1); _Pragma("unroll") for (int m = 0; m < 4; ++m) _Pragma("unroll") for (int n = 0; n < 2; ++n) _Pragma("unroll") for (int k = 0; k < 2; ++k) \
;         acc[ai][bj][m][n] = __builtin_amdgcn_mfma_f32_16x16x32_bf16(Bt[n][k], At[m][k], acc[ai][bj][m][n], 0, 0, 0); __builtin_amdgcn_s_setprio(0); } while (0)
; #define PG8_WAIT_V(n) asm volatile("s_waitcnt vmcnt(" #n ")" ::: "memory")
; #define PG8_WAIT_L(n) asm volatile("s_waitcnt lgkmcnt(" #n ")" ::: "memory")
; #define PG8_BAR __builtin_amdgcn_s_barrier()
; #define PG8_SCHED __builtin_amdgcn_sched_barrier(0)
; template <class Epi>
; __device__ __forceinline__ void gemm_phase(PG8_LAS unsigned char* lds, const Gemm g, const StaticOrder& S, const Epi& E, const int wave_s) {
;     ...
;             PG8_LDA(At, 1, 1); PG8_STAGE(PG8_SB(1, 0), b3, voffB); PG8_STAGE(PG8_SB(1, 1), b3 + hstepB, voffB); PG8_STAGE(PG8_SA(1, 0), a3, voffA);
;             PG8_WAIT_V(8); PG8_WAIT_L(0); PG8_BAR; PG8_MMA(1, 0, At, B0); PG8_MMA(1, 1, At, B1); PG8_BAR; PG8_SCHED;
;         }
	s_add_i32 s6, s47, s16
	v_lshl_add_u64 v[194:195], v[194:195], 0, s[52:53]
	s_mov_b32 m0, s6
	ds_read_b128 v[162:165], v242 offset:49152
	ds_read_b128 v[166:169], v242 offset:50176
	ds_read_b128 v[170:173], v242 offset:51200
	ds_read_b128 v[174:177], v242 offset:52224
	ds_read_b128 v[178:181], v242 offset:53248
	ds_read_b128 v[182:185], v242 offset:54272
	ds_read_b128 v[186:189], v242 offset:55296
	ds_read_b128 v[190:193], v242 offset:56320
	global_load_lds_dwordx4 v[194:195], off
	v_lshl_add_u64 v[194:195], v[196:197], 0, s[52:53]
	s_add_i32 m0, s6, 0x2000
	s_add_i32 s6, s48, s16
	global_load_lds_dwordx4 v[194:195], off
	v_lshl_add_u64 v[194:195], v[198:199], 0, s[52:53]
	s_mov_b32 m0, s6
	s_nop 0
	global_load_lds_dwordx4 v[194:195], off
	v_lshl_add_u64 v[194:195], v[200:201], 0, s[52:53]
	s_add_i32 m0, s6, 0x2000
	s_nop 0
	global_load_lds_dwordx4 v[194:195], off
	v_lshl_add_u64 v[194:195], v[202:203], 0, s[52:53]
	s_mov_b32 m0, s93
	s_nop 0
	global_load_lds_dwordx4 v[194:195], off
	v_lshl_add_u64 v[194:195], v[204:205], 0, s[52:53]
	s_mov_b32 m0, s97
	s_nop 0
	global_load_lds_dwordx4 v[194:195], off
	s_waitcnt vmcnt(8)
	s_waitcnt lgkmcnt(0)
	s_barrier
	s_waitcnt lgkmcnt(0)
	v_mfma_f32_16x16x32_bf16 v[60:63], v[98:101], v[162:165], v[60:63]
	v_mfma_f32_16x16x32_bf16 v[56:59], v[106:109], v[162:165], v[56:59]
	v_mfma_f32_16x16x32_bf16 v[44:47], v[98:101], v[170:173], v[44:47]
	v_mfma_f32_16x16x32_bf16 v[40:43], v[106:109], v[170:173], v[40:43]
	v_mfma_f32_16x16x32_bf16 v[28:31], v[98:101], v[178:181], v[28:31]
	v_mfma_f32_16x16x32_bf16 v[24:27], v[106:109], v[178:181], v[24:27]
	v_mfma_f32_16x16x32_bf16 v[12:15], v[98:101], v[186:189], v[12:15]
	v_mfma_f32_16x16x32_bf16 v[8:11], v[106:109], v[186:189], v[8:11]
	v_mfma_f32_16x16x32_bf16 v[60:63], v[102:105], v[166:169], v[60:63]
	v_mfma_f32_16x16x32_bf16 v[56:59], v[110:113], v[166:169], v[56:59]
	v_mfma_f32_16x16x32_bf16 v[44:47], v[102:105], v[174:177], v[44:47]
	v_mfma_f32_16x16x32_bf16 v[40:43], v[110:113], v[174:177], v[40:43]
	v_mfma_f32_16x16x32_bf16 v[28:31], v[102:105], v[182:185], v[28:31]
	v_mfma_f32_16x16x32_bf16 v[24:27], v[110:113], v[182:185], v[24:27]
	v_mfma_f32_16x16x32_bf16 v[12:15], v[102:105], v[190:193], v[12:15]
	v_mfma_f32_16x16x32_bf16 v[8:11], v[110:113], v[190:193], v[8:11]
	v_mfma_f32_16x16x32_bf16 v[52:55], v[118:121], v[162:165], v[52:55]
	v_mfma_f32_16x16x32_bf16 v[48:51], v[138:141], v[162:165], v[48:51]
	v_mfma_f32_16x16x32_bf16 v[36:39], v[118:121], v[170:173], v[36:39]
	v_mfma_f32_16x16x32_bf16 v[32:35], v[138:141], v[170:173], v[32:35]
	v_mfma_f32_16x16x32_bf16 v[20:23], v[118:121], v[178:181], v[20:23]
	v_mfma_f32_16x16x32_bf16 v[16:19], v[138:141], v[178:181], v[16:19]
	v_mfma_f32_16x16x32_bf16 v[4:7], v[118:121], v[186:189], v[4:7]
	v_mfma_f32_16x16x32_bf16 v[0:3], v[138:141], v[186:189], v[0:3]
	v_mfma_f32_16x16x32_bf16 v[52:55], v[122:125], v[166:169], v[52:55]
	v_mfma_f32_16x16x32_bf16 v[48:51], v[142:145], v[166:169], v[48:51]
	v_mfma_f32_16x16x32_bf16 v[36:39], v[122:125], v[174:177], v[36:39]
	v_mfma_f32_16x16x32_bf16 v[32:35], v[142:145], v[174:177], v[32:35]
	v_mfma_f32_16x16x32_bf16 v[20:23], v[122:125], v[182:185], v[20:23]
	v_mfma_f32_16x16x32_bf16 v[16:19], v[142:145], v[182:185], v[16:19]
	v_mfma_f32_16x16x32_bf16 v[4:7], v[122:125], v[190:193], v[4:7]
	v_mfma_f32_16x16x32_bf16 v[0:3], v[142:145], v[190:193], v[0:3]
	s_barrier
	s_add_u32 s44, s44, 0x100
	s_addc_u32 s45, s45, 0
	s_add_u32 s12, s12, 0x100
	s_addc_u32 s13, s13, 0
	s_cmp_ge_i32 s46, s94
	s_mov_b32 s6, s46
	s_cbranch_scc0 .LBB0_765
	s_setprio 0
